# baseline (speedup 1.0000x reference)
; #define G_STA(bufoff, gbase, ld) G_STAGE(bufoff, gbase, RA0, RA1, ld)
; #define G_STB(bufoff, gbase, ld) G_STAGE(bufoff, gbase, RB0, RB1, ld)
; #define G_LDA(dst, b, h) do { _Pragma("unroll") for (int m = 0; m < 4; ++m) _Pragma("unroll") for (int k = 0; k < 2; ++k) dst[m][k] = *(const LAS bf16x8*)(lds + G_SA(b, h) + aoff + m * 2048 + k * 1024); } while (0)
; #define G_LDB(dst, b, h) do { _Pragma("unroll") for (int n = 0; n < 2; ++n) _Pragma("unroll") for (int k = 0; k < 2; ++k) dst[n][k] = *(const LAS bf16x8*)(lds + G_SB(b, h) + boff + n * 2048 + k * 1024); } while (0)
; #define G_MMA(ai, bj, At, Bt) do { __builtin_amdgcn_s_setprio(1); _Pragma("unroll") for (int m = 0; m < 4; ++m) _Pragma("unroll") for (int n = 0; n < 2; ++n) _Pragma("unroll") for (int k = 0; k < 2; ++k) \
;         acc[ai][bj][m][n] = __builtin_amdgcn_mfma_f32_16x16x32_bf16(Bt[n][k], At[m][k], acc[ai][bj][m][n], 0, 0, 0); __builtin_amdgcn_s_setprio(0); } while (0)
; #define G_WAIT_L(n) asm volatile("s_waitcnt lgkmcnt(" #n ")" ::: "memory")
; #define G_BAR __builtin_amdgcn_s_barrier()
; #define G_SCHED __builtin_amdgcn_sched_barrier(0)
; template <bool PERM, class SchedT, class Epi>
; __device__ __forceinline__ void gemm_phase(LAS unsigned char* lds, const SchedT& S, const Epi& E) {
;     ...
;         for (int t = 0; t < nt; t += 2) {
;             const bool last = (t == nt - 2);
;             const char* a1 = cA + (size_t)(t + 1) * kstep;
;             const char* a2 = last ? nA : cA + (size_t)(t + 2) * kstep; const char* b2 = last ? nB : cB + (size_t)(t + 2) * kstep;
;             const char* a3 = a2 + kstep; const char* b3 = b2 + kstep;
;             const int wlda = last ? nlda : lda, wK = last ? nK : K;
;             G_LDB(B0, 0, 0); G_SCHED; G_LDA(At, 0, 0); G_STA(G_SA(1, 1), a1 + HSTEP(lda), lda);
;             G_WAIT_L(8); G_BAR; G_WAIT_L(0); G_MMA(0, 0, At, B0); G_BAR; G_SCHED;
;             G_LDB(B1, 0, 1); G_STB(G_SB(0, 0), b2, wK);
;             G_BAR; G_WAIT_L(0); G_MMA(0, 1, At, B1); G_BAR;
;             G_LDA(At, 0, 1); G_STA(G_SA(0, 0), a2, wlda);
;             G_BAR; G_WAIT_L(0); G_MMA(1, 0, At, B0); G_BAR; G_SCHED;
.LBB0_44:
	s_cmp_eq_u32 s45, s47
	s_cselect_b64 s[28:29], -1, 0
	s_add_i32 s47, s47, 2
	s_add_u32 s26, s22, 0x80
	s_addc_u32 s27, s23, 0
	s_and_b64 s[24:25], s[28:29], exec
	s_cselect_b32 s25, s13, s27
	s_cselect_b32 s24, s12, s26
	s_cselect_b32 s26, s40, s20
	s_add_i32 s27, 0, 0x10000
	v_add_u32_e32 v152, s27, v194
	ds_read_b128 v[134:137], v152
	ds_read_b128 v[144:147], v152 offset:1024
	ds_read_b128 v[148:151], v152 offset:2048
	ds_read_b128 v[152:155], v152 offset:3072
	s_and_b64 s[28:29], s[28:29], exec
	s_cselect_b32 s29, s19, s46
	s_cselect_b32 s28, s18, s21
	s_cselect_b32 s72, s11, s44
	v_lshl_add_u64 v[156:157], s[22:23], 0, v[130:131]
	s_add_i32 m0, s30, 0xc000
	ds_read_b128 v[160:163], v196
	ds_read_b128 v[164:167], v196 offset:1024
	ds_read_b128 v[168:171], v196 offset:2048
	ds_read_b128 v[172:175], v196 offset:3072
	ds_read_b128 v[176:179], v196 offset:4096
	ds_read_b128 v[198:201], v196 offset:5120
	ds_read_b128 v[202:205], v196 offset:6144
	ds_read_b128 v[206:209], v196 offset:7168
	global_load_lds_dwordx4 v[156:157], off
	v_lshl_add_u64 v[156:157], s[22:23], 0, v[132:133]
	s_add_i32 m0, s30, 0xe000
	s_nop 0
	global_load_lds_dwordx4 v[156:157], off
	s_waitcnt lgkmcnt(8)
	s_barrier
	s_waitcnt lgkmcnt(0)
	s_setprio 1
	s_waitcnt lgkmcnt(0)
	v_mfma_f32_16x16x32_bf16 v[126:129], v[134:137], v[160:163], v[126:129]
	v_mfma_f32_16x16x32_bf16 v[122:125], v[148:151], v[160:163], v[122:125]
	v_mfma_f32_16x16x32_bf16 v[118:121], v[134:137], v[168:171], v[118:121]
	v_mfma_f32_16x16x32_bf16 v[114:117], v[148:151], v[168:171], v[114:117]
	v_mfma_f32_16x16x32_bf16 v[102:105], v[134:137], v[176:179], v[102:105]
	v_mfma_f32_16x16x32_bf16 v[98:101], v[148:151], v[176:179], v[98:101]
	v_mfma_f32_16x16x32_bf16 v[86:89], v[134:137], v[202:205], v[86:89]
	v_mfma_f32_16x16x32_bf16 v[82:85], v[148:151], v[202:205], v[82:85]
	v_mfma_f32_16x16x32_bf16 v[126:129], v[144:147], v[164:167], v[126:129]
	v_mfma_f32_16x16x32_bf16 v[122:125], v[152:155], v[164:167], v[122:125]
	v_mfma_f32_16x16x32_bf16 v[118:121], v[144:147], v[172:175], v[118:121]
	v_mfma_f32_16x16x32_bf16 v[114:117], v[152:155], v[172:175], v[114:117]
	v_mfma_f32_16x16x32_bf16 v[102:105], v[144:147], v[198:201], v[102:105]
	v_mfma_f32_16x16x32_bf16 v[98:101], v[152:155], v[198:201], v[98:101]
	v_mfma_f32_16x16x32_bf16 v[86:89], v[144:147], v[206:209], v[86:89]
	v_mfma_f32_16x16x32_bf16 v[82:85], v[152:155], v[206:209], v[82:85]
	s_setprio 0
	s_barrier
	s_add_i32 s50, 0, 0x14000
	v_add_u32_e32 v156, s50, v194
	s_add_i32 s27, s27, s5
	ds_read_b128 v[210:213], v156
	ds_read_b128 v[214:217], v156 offset:1024
	ds_read_b128 v[218:221], v156 offset:2048
	ds_read_b128 v[222:225], v156 offset:3072
	v_mad_u64_u32 v[156:157], s[48:49], v143, s72, v[138:139]
	s_mov_b32 m0, s27
	v_mad_u64_u32 v[230:231], s[48:49], v192, s72, v[140:141]
	global_load_lds_dwordx4 v156, s[28:29]
	s_add_i32 m0, s27, 0x2000
	v_mov_b32_e32 v157, v1
	global_load_lds_dwordx4 v230, s[28:29]
	s_barrier
	s_waitcnt lgkmcnt(0)
	v_mov_b32_e32 v231, v1
	v_lshl_add_u64 v[232:233], s[28:29], 0, v[156:157]
	v_lshl_add_u64 v[234:235], s[28:29], 0, v[230:231]
	s_setprio 1
	s_waitcnt lgkmcnt(0)
	v_mfma_f32_16x16x32_bf16 v[110:113], v[210:213], v[160:163], v[110:113]
	v_mfma_f32_16x16x32_bf16 v[106:109], v[218:221], v[160:163], v[106:109]
	v_mfma_f32_16x16x32_bf16 v[94:97], v[210:213], v[168:171], v[94:97]
	v_mfma_f32_16x16x32_bf16 v[90:93], v[218:221], v[168:171], v[90:93]
	v_mfma_f32_16x16x32_bf16 v[78:81], v[210:213], v[176:179], v[78:81]
	v_mfma_f32_16x16x32_bf16 v[74:77], v[218:221], v[176:179], v[74:77]
	v_mfma_f32_16x16x32_bf16 v[70:73], v[210:213], v[202:205], v[70:73]
	v_mfma_f32_16x16x32_bf16 v[66:69], v[218:221], v[202:205], v[66:69]
	v_mfma_f32_16x16x32_bf16 v[110:113], v[214:217], v[164:167], v[110:113]
	v_mfma_f32_16x16x32_bf16 v[106:109], v[222:225], v[164:167], v[106:109]
	v_mfma_f32_16x16x32_bf16 v[94:97], v[214:217], v[172:175], v[94:97]
	v_mfma_f32_16x16x32_bf16 v[90:93], v[222:225], v[172:175], v[90:93]
	v_mfma_f32_16x16x32_bf16 v[78:81], v[214:217], v[198:201], v[78:81]
	v_mfma_f32_16x16x32_bf16 v[74:77], v[222:225], v[198:201], v[74:77]
	v_mfma_f32_16x16x32_bf16 v[70:73], v[214:217], v[206:209], v[70:73]
	v_mfma_f32_16x16x32_bf16 v[66:69], v[222:225], v[206:209], v[66:69]
	s_setprio 0
	s_mov_b32 m0, s30
	v_mad_u64_u32 v[236:237], s[48:49], s26, v139, v[138:139]
	s_barrier
	ds_read_b128 v[160:163], v196 offset:16384
	ds_read_b128 v[164:167], v196 offset:17408
	ds_read_b128 v[168:171], v196 offset:18432
	ds_read_b128 v[172:175], v196 offset:19456
	ds_read_b128 v[176:179], v196 offset:20480
	ds_read_b128 v[198:201], v196 offset:21504
	ds_read_b128 v[202:205], v196 offset:22528
	ds_read_b128 v[206:209], v196 offset:23552
	global_load_lds_dwordx4 v236, s[24:25]
	v_mad_u64_u32 v[238:239], s[48:49], s26, v141, v[140:141]
	s_mov_b32 m0, s31
	v_mov_b32_e32 v237, v1
	global_load_lds_dwordx4 v238, s[24:25]
	s_barrier
	s_waitcnt lgkmcnt(0)
	v_mov_b32_e32 v239, v1
	v_lshl_add_u64 v[240:241], s[24:25], 0, v[236:237]
	v_lshl_add_u64 v[242:243], s[24:25], 0, v[238:239]
	s_setprio 1
	s_waitcnt lgkmcnt(0)
	v_mfma_f32_16x16x32_bf16 v[62:65], v[134:137], v[160:163], v[62:65]
	v_mfma_f32_16x16x32_bf16 v[58:61], v[148:151], v[160:163], v[58:61]
	v_mfma_f32_16x16x32_bf16 v[54:57], v[134:137], v[168:171], v[54:57]
	v_mfma_f32_16x16x32_bf16 v[50:53], v[148:151], v[168:171], v[50:53]
	v_mfma_f32_16x16x32_bf16 v[38:41], v[134:137], v[176:179], v[38:41]
	v_mfma_f32_16x16x32_bf16 v[34:37], v[148:151], v[176:179], v[34:37]
	v_mfma_f32_16x16x32_bf16 v[22:25], v[134:137], v[202:205], v[22:25]
	v_mfma_f32_16x16x32_bf16 v[18:21], v[148:151], v[202:205], v[18:21]
	v_mfma_f32_16x16x32_bf16 v[62:65], v[144:147], v[164:167], v[62:65]
	v_mfma_f32_16x16x32_bf16 v[58:61], v[152:155], v[164:167], v[58:61]
	v_mfma_f32_16x16x32_bf16 v[54:57], v[144:147], v[172:175], v[54:57]
	v_mfma_f32_16x16x32_bf16 v[50:53], v[152:155], v[172:175], v[50:53]
	v_mfma_f32_16x16x32_bf16 v[38:41], v[144:147], v[198:201], v[38:41]
	v_mfma_f32_16x16x32_bf16 v[34:37], v[152:155], v[198:201], v[34:37]
	v_mfma_f32_16x16x32_bf16 v[22:25], v[144:147], v[206:209], v[22:25]
	v_mfma_f32_16x16x32_bf16 v[18:21], v[152:155], v[206:209], v[18:21]
	s_setprio 0
	s_barrier
; #define G_STA(bufoff, gbase, ld) G_STAGE(bufoff, gbase, RA0, RA1, ld)
; #define G_STB(bufoff, gbase, ld) G_STAGE(bufoff, gbase, RB0, RB1, ld)
; #define G_LDA(dst, b, h) do { _Pragma("unroll") for (int m = 0; m < 4; ++m) _Pragma("unroll") for (int k = 0; k < 2; ++k) dst[m][k] = *(const LAS bf16x8*)(lds + G_SA(b, h) + aoff + m * 2048 + k * 1024); } while (0)
; #define G_LDB(dst, b, h) do { _Pragma("unroll") for (int n = 0; n < 2; ++n) _Pragma("unroll") for (int k = 0; k < 2; ++k) dst[n][k] = *(const LAS bf16x8*)(lds + G_SB(b, h) + boff + n * 2048 + k * 1024); } while (0)
; #define G_MMA(ai, bj, At, Bt) do { __builtin_amdgcn_s_setprio(1); _Pragma("unroll") for (int m = 0; m < 4; ++m) _Pragma("unroll") for (int n = 0; n < 2; ++n) _Pragma("unroll") for (int k = 0; k < 2; ++k) \
;         acc[ai][bj][m][n] = __builtin_amdgcn_mfma_f32_16x16x32_bf16(Bt[n][k], At[m][k], acc[ai][bj][m][n], 0, 0, 0); __builtin_amdgcn_s_setprio(0); } while (0)
; #define G_WAIT_V(n) asm volatile("s_waitcnt vmcnt(" #n ")" ::: "memory")
; #define G_WAIT_L(n) asm volatile("s_waitcnt lgkmcnt(" #n ")" ::: "memory")
; #define G_BAR __builtin_amdgcn_s_barrier()
; #define G_SCHED __builtin_amdgcn_sched_barrier(0)
; template <bool PERM, class SchedT, class Epi>
; __device__ __forceinline__ void gemm_phase(LAS unsigned char* lds, const SchedT& S, const Epi& E) {
;     ...
;             G_BAR; G_WAIT_L(0); G_MMA(1, 0, At, B0); G_BAR; G_SCHED;
;             G_STB(G_SB(0, 1), b2 + HSTEP(wK), wK);
;             G_WAIT_V(6); G_BAR; G_MMA(1, 1, At, B1); G_BAR;
;             G_LDB(B0, 1, 0); G_SCHED; G_LDA(At, 1, 0); G_STA(G_SA(0, 1), a2 + HSTEP(wlda), wlda);
;             G_WAIT_L(8); G_BAR; G_WAIT_L(0); G_MMA(0, 0, At, B0); G_BAR; G_SCHED;
;             G_LDB(B1, 1, 1); G_STB(G_SB(1, 0), b3, wK);
;             G_BAR; G_WAIT_L(0); G_MMA(0, 1, At, B1); G_BAR;
;             G_LDA(At, 1, 1); G_STA(G_SA(1, 0), a3, wlda);
	s_lshl_b64 s[48:49], s[72:73], 8
	s_add_u32 s28, s28, s48
	s_addc_u32 s29, s29, s49
	s_add_i32 s27, s50, s5
	s_mov_b32 m0, s27
	s_nop 0
	global_load_lds_dwordx4 v156, s[28:29]
	s_add_i32 m0, s27, 0x2000
	v_lshl_add_u64 v[156:157], s[28:29], 0, v[156:157]
	global_load_lds_dwordx4 v230, s[28:29]
	s_waitcnt vmcnt(6)
	v_lshl_add_u64 v[230:231], s[28:29], 0, v[230:231]
	s_barrier
	s_setprio 1
	v_mfma_f32_16x16x32_bf16 v[46:49], v[210:213], v[160:163], v[46:49]
	v_mfma_f32_16x16x32_bf16 v[42:45], v[218:221], v[160:163], v[42:45]
	v_mfma_f32_16x16x32_bf16 v[30:33], v[210:213], v[168:171], v[30:33]
	v_mfma_f32_16x16x32_bf16 v[26:29], v[218:221], v[168:171], v[26:29]
	v_mfma_f32_16x16x32_bf16 v[14:17], v[210:213], v[176:179], v[14:17]
	v_mfma_f32_16x16x32_bf16 v[10:13], v[218:221], v[176:179], v[10:13]
	v_mfma_f32_16x16x32_bf16 v[6:9], v[210:213], v[202:205], v[6:9]
	v_mfma_f32_16x16x32_bf16 v[2:5], v[218:221], v[202:205], v[2:5]
	v_mfma_f32_16x16x32_bf16 v[46:49], v[214:217], v[164:167], v[46:49]
	v_mfma_f32_16x16x32_bf16 v[42:45], v[222:225], v[164:167], v[42:45]
	v_mfma_f32_16x16x32_bf16 v[30:33], v[214:217], v[172:175], v[30:33]
	v_mfma_f32_16x16x32_bf16 v[26:29], v[222:225], v[172:175], v[26:29]
	v_mfma_f32_16x16x32_bf16 v[14:17], v[214:217], v[198:201], v[14:17]
	v_mfma_f32_16x16x32_bf16 v[10:13], v[222:225], v[198:201], v[10:13]
	v_mfma_f32_16x16x32_bf16 v[6:9], v[214:217], v[206:209], v[6:9]
	v_mfma_f32_16x16x32_bf16 v[2:5], v[222:225], v[206:209], v[2:5]
	s_setprio 0
	s_add_i32 s28, 0, 0x18000
	v_add_u32_e32 v152, s28, v194
	s_barrier
	ds_read_b128 v[134:137], v152
	ds_read_b128 v[144:147], v152 offset:1024
	ds_read_b128 v[148:151], v152 offset:2048
	ds_read_b128 v[152:155], v152 offset:3072
	s_mov_b32 s27, s73
	s_lshl_b64 s[26:27], s[26:27], 8
	s_add_u32 s24, s24, s26
	s_addc_u32 s25, s25, s27
	s_mov_b32 m0, s34
	ds_read_b128 v[160:163], v196 offset:32768
	ds_read_b128 v[164:167], v196 offset:33792
	ds_read_b128 v[168:171], v196 offset:34816
	ds_read_b128 v[172:175], v196 offset:35840
	ds_read_b128 v[176:179], v196 offset:36864
	ds_read_b128 v[198:201], v196 offset:37888
	ds_read_b128 v[202:205], v196 offset:38912
	ds_read_b128 v[206:209], v196 offset:39936
	global_load_lds_dwordx4 v236, s[24:25]
	s_mov_b32 m0, s35
	s_nop 0
	global_load_lds_dwordx4 v238, s[24:25]
	s_waitcnt lgkmcnt(8)
	s_barrier
	s_waitcnt lgkmcnt(0)
	s_setprio 1
	s_waitcnt lgkmcnt(0)
	v_mfma_f32_16x16x32_bf16 v[126:129], v[134:137], v[160:163], v[126:129]
	v_mfma_f32_16x16x32_bf16 v[122:125], v[148:151], v[160:163], v[122:125]
	v_mfma_f32_16x16x32_bf16 v[118:121], v[134:137], v[168:171], v[118:121]
	v_mfma_f32_16x16x32_bf16 v[114:117], v[148:151], v[168:171], v[114:117]
	v_mfma_f32_16x16x32_bf16 v[102:105], v[134:137], v[176:179], v[102:105]
	v_mfma_f32_16x16x32_bf16 v[98:101], v[148:151], v[176:179], v[98:101]
	v_mfma_f32_16x16x32_bf16 v[86:89], v[134:137], v[202:205], v[86:89]
	v_mfma_f32_16x16x32_bf16 v[82:85], v[148:151], v[202:205], v[82:85]
	v_mfma_f32_16x16x32_bf16 v[126:129], v[144:147], v[164:167], v[126:129]
	v_mfma_f32_16x16x32_bf16 v[122:125], v[152:155], v[164:167], v[122:125]
	v_mfma_f32_16x16x32_bf16 v[118:121], v[144:147], v[172:175], v[118:121]
	v_mfma_f32_16x16x32_bf16 v[114:117], v[152:155], v[172:175], v[114:117]
	v_mfma_f32_16x16x32_bf16 v[102:105], v[144:147], v[198:201], v[102:105]
	v_mfma_f32_16x16x32_bf16 v[98:101], v[152:155], v[198:201], v[98:101]
	v_mfma_f32_16x16x32_bf16 v[86:89], v[144:147], v[206:209], v[86:89]
	v_mfma_f32_16x16x32_bf16 v[82:85], v[152:155], v[206:209], v[82:85]
	s_setprio 0
	s_barrier
	s_add_i32 s24, 0, 0x1c000
	s_add_i32 s25, s28, s5
	v_add_u32_e32 v197, s24, v194
	v_lshl_add_u64 v[232:233], v[232:233], 0, s[78:79]
	s_mov_b32 m0, s25
	ds_read_b128 v[210:213], v197
	ds_read_b128 v[214:217], v197 offset:1024
	ds_read_b128 v[218:221], v197 offset:2048
	ds_read_b128 v[222:225], v197 offset:3072
	global_load_lds_dwordx4 v[232:233], off
	v_lshl_add_u64 v[232:233], v[234:235], 0, s[78:79]
	s_add_i32 m0, s25, 0x2000
	s_nop 0
	global_load_lds_dwordx4 v[232:233], off
	s_barrier
	s_waitcnt lgkmcnt(0)
	s_setprio 1
	s_waitcnt lgkmcnt(0)
	v_mfma_f32_16x16x32_bf16 v[110:113], v[210:213], v[160:163], v[110:113]
	v_mfma_f32_16x16x32_bf16 v[106:109], v[218:221], v[160:163], v[106:109]
	v_mfma_f32_16x16x32_bf16 v[94:97], v[210:213], v[168:171], v[94:97]
	v_mfma_f32_16x16x32_bf16 v[90:93], v[218:221], v[168:171], v[90:93]
	v_mfma_f32_16x16x32_bf16 v[78:81], v[210:213], v[176:179], v[78:81]
	v_mfma_f32_16x16x32_bf16 v[74:77], v[218:221], v[176:179], v[74:77]
	v_mfma_f32_16x16x32_bf16 v[70:73], v[210:213], v[202:205], v[70:73]
	v_mfma_f32_16x16x32_bf16 v[66:69], v[218:221], v[202:205], v[66:69]
	v_mfma_f32_16x16x32_bf16 v[110:113], v[214:217], v[164:167], v[110:113]
	v_mfma_f32_16x16x32_bf16 v[106:109], v[222:225], v[164:167], v[106:109]
	v_mfma_f32_16x16x32_bf16 v[94:97], v[214:217], v[172:175], v[94:97]
	v_mfma_f32_16x16x32_bf16 v[90:93], v[222:225], v[172:175], v[90:93]
	v_mfma_f32_16x16x32_bf16 v[78:81], v[214:217], v[198:201], v[78:81]
	v_mfma_f32_16x16x32_bf16 v[74:77], v[222:225], v[198:201], v[74:77]
	v_mfma_f32_16x16x32_bf16 v[70:73], v[214:217], v[206:209], v[70:73]
	v_mfma_f32_16x16x32_bf16 v[66:69], v[222:225], v[206:209], v[66:69]
	s_setprio 0
	s_mov_b32 m0, s36
	v_lshl_add_u64 v[232:233], v[240:241], 0, s[78:79]
	s_barrier
	ds_read_b128 v[160:163], v196 offset:49152
	ds_read_b128 v[164:167], v196 offset:50176
	ds_read_b128 v[168:171], v196 offset:51200
	ds_read_b128 v[172:175], v196 offset:52224
	ds_read_b128 v[176:179], v196 offset:53248
	ds_read_b128 v[198:201], v196 offset:54272
	ds_read_b128 v[202:205], v196 offset:55296
	ds_read_b128 v[206:209], v196 offset:56320
	global_load_lds_dwordx4 v[232:233], off
	v_lshl_add_u64 v[232:233], v[242:243], 0, s[78:79]
	s_mov_b32 m0, s37
	s_nop 0
	global_load_lds_dwordx4 v[232:233], off
	s_barrier
; #define G_STA(bufoff, gbase, ld) G_STAGE(bufoff, gbase, RA0, RA1, ld)
; #define G_STB(bufoff, gbase, ld) G_STAGE(bufoff, gbase, RB0, RB1, ld)
; #define G_LDA(dst, b, h) do { _Pragma("unroll") for (int m = 0; m < 4; ++m) _Pragma("unroll") for (int k = 0; k < 2; ++k) dst[m][k] = *(const LAS bf16x8*)(lds + G_SA(b, h) + aoff + m * 2048 + k * 1024); } while (0)
; #define G_MMA(ai, bj, At, Bt) do { __builtin_amdgcn_s_setprio(1); _Pragma("unroll") for (int m = 0; m < 4; ++m) _Pragma("unroll") for (int n = 0; n < 2; ++n) _Pragma("unroll") for (int k = 0; k < 2; ++k) \
;         acc[ai][bj][m][n] = __builtin_amdgcn_mfma_f32_16x16x32_bf16(Bt[n][k], At[m][k], acc[ai][bj][m][n], 0, 0, 0); __builtin_amdgcn_s_setprio(0); } while (0)
; #define G_WAIT_V(n) asm volatile("s_waitcnt vmcnt(" #n ")" ::: "memory")
; #define G_WAIT_L(n) asm volatile("s_waitcnt lgkmcnt(" #n ")" ::: "memory")
; #define G_BAR __builtin_amdgcn_s_barrier()
; #define G_SCHED __builtin_amdgcn_sched_barrier(0)
; template <bool PERM, class SchedT, class Epi>
; __device__ __forceinline__ void gemm_phase(LAS unsigned char* lds, const SchedT& S, const Epi& E) {
;     ...
;             G_BAR; G_WAIT_L(0); G_MMA(0, 1, At, B1); G_BAR;
;             G_LDA(At, 1, 1); G_STA(G_SA(1, 0), a3, wlda);
;             G_BAR; G_WAIT_L(0); G_MMA(1, 0, At, B0); G_BAR; G_SCHED;
;             G_STB(G_SB(1, 1), b3 + HSTEP(wK), wK);
;             G_WAIT_V(6); G_BAR; G_MMA(1, 1, At, B1); G_BAR;
;     __device__ __forceinline__ void operator()(const f32x4 (&acc)[2][2][4][2], const UnitD& u, int wr, int wc, int fr, int fq) const {
;     ...
;             for (int ai = 0; ai < 2; ++ai)
; #pragma unroll
;                 for (int m = 0; m < 4; ++m) { const int row = row0 + ai * HALF + m * 16;
;                     const unsigned char* gp = (const unsigned char*)(proj + (size_t)row * NP + C_G) + col0; const size_t po = (size_t)row * 2048 + col0;
;                     u32x2 g0[2], g1[2], g2[2]; u32x4 a[2], b[2];
; #pragma unroll
;                     for (int bj = 0; bj < 2; ++bj) { g0[bj] = *(const u32x2*)(gp + bj * HALF); g1[bj] = *(const u32x2*)(gp + 2048 + bj * HALF); g2[bj] = *(const u32x2*)(gp + 4096 + bj * HALF);
;                         a[bj] = *(const u32x4*)(PA + po + bj * HALF); b[bj] = *(const u32x4*)(PB + po + bj * HALF); }
	s_waitcnt lgkmcnt(0)
	s_setprio 1
	s_waitcnt lgkmcnt(0)
	v_mfma_f32_16x16x32_bf16 v[62:65], v[134:137], v[160:163], v[62:65]
	v_mfma_f32_16x16x32_bf16 v[58:61], v[148:151], v[160:163], v[58:61]
	v_mfma_f32_16x16x32_bf16 v[54:57], v[134:137], v[168:171], v[54:57]
	v_mfma_f32_16x16x32_bf16 v[50:53], v[148:151], v[168:171], v[50:53]
	v_mfma_f32_16x16x32_bf16 v[38:41], v[134:137], v[176:179], v[38:41]
	v_mfma_f32_16x16x32_bf16 v[34:37], v[148:151], v[176:179], v[34:37]
	v_mfma_f32_16x16x32_bf16 v[22:25], v[134:137], v[202:205], v[22:25]
	v_mfma_f32_16x16x32_bf16 v[18:21], v[148:151], v[202:205], v[18:21]
	v_mfma_f32_16x16x32_bf16 v[62:65], v[144:147], v[164:167], v[62:65]
	v_mfma_f32_16x16x32_bf16 v[58:61], v[152:155], v[164:167], v[58:61]
	v_mfma_f32_16x16x32_bf16 v[54:57], v[144:147], v[172:175], v[54:57]
	v_mfma_f32_16x16x32_bf16 v[50:53], v[152:155], v[172:175], v[50:53]
	v_mfma_f32_16x16x32_bf16 v[38:41], v[144:147], v[198:201], v[38:41]
	v_mfma_f32_16x16x32_bf16 v[34:37], v[152:155], v[198:201], v[34:37]
	v_mfma_f32_16x16x32_bf16 v[22:25], v[144:147], v[206:209], v[22:25]
	v_mfma_f32_16x16x32_bf16 v[18:21], v[152:155], v[206:209], v[18:21]
	s_setprio 0
	s_barrier
	s_add_i32 s24, s24, s5
	v_lshl_add_u64 v[134:135], v[156:157], 0, s[78:79]
	s_mov_b32 m0, s24
	s_nop 0
	global_load_lds_dwordx4 v[134:135], off
	v_lshl_add_u64 v[134:135], v[230:231], 0, s[78:79]
	s_add_i32 m0, s24, 0x2000
	s_nop 0
	global_load_lds_dwordx4 v[134:135], off
	s_waitcnt vmcnt(6)
	s_barrier
	s_setprio 1
	v_mfma_f32_16x16x32_bf16 v[46:49], v[210:213], v[160:163], v[46:49]
	v_mfma_f32_16x16x32_bf16 v[42:45], v[218:221], v[160:163], v[42:45]
	v_mfma_f32_16x16x32_bf16 v[30:33], v[210:213], v[168:171], v[30:33]
	v_mfma_f32_16x16x32_bf16 v[26:29], v[218:221], v[168:171], v[26:29]
	v_mfma_f32_16x16x32_bf16 v[14:17], v[210:213], v[176:179], v[14:17]
	v_mfma_f32_16x16x32_bf16 v[10:13], v[218:221], v[176:179], v[10:13]
	v_mfma_f32_16x16x32_bf16 v[6:9], v[210:213], v[202:205], v[6:9]
	v_mfma_f32_16x16x32_bf16 v[2:5], v[218:221], v[202:205], v[2:5]
	v_mfma_f32_16x16x32_bf16 v[46:49], v[214:217], v[164:167], v[46:49]
	v_mfma_f32_16x16x32_bf16 v[42:45], v[222:225], v[164:167], v[42:45]
	v_mfma_f32_16x16x32_bf16 v[30:33], v[214:217], v[172:175], v[30:33]
	v_mfma_f32_16x16x32_bf16 v[26:29], v[222:225], v[172:175], v[26:29]
	v_mfma_f32_16x16x32_bf16 v[14:17], v[214:217], v[198:201], v[14:17]
	v_mfma_f32_16x16x32_bf16 v[10:13], v[222:225], v[198:201], v[10:13]
	v_mfma_f32_16x16x32_bf16 v[6:9], v[214:217], v[206:209], v[6:9]
	v_mfma_f32_16x16x32_bf16 v[2:5], v[222:225], v[206:209], v[2:5]
	s_setprio 0
	s_add_u32 s22, s22, 0x100
	s_addc_u32 s23, s23, 0
	s_add_u32 s21, s21, 0x100
	s_addc_u32 s46, s46, 0
	s_cmp_ge_u32 s47, s9
	s_barrier
	s_cbranch_scc0 .LBB0_44
	v_lshl_add_u32 v144, s43, 8, v193
	v_lshl_or_b32 v150, s42, 8, v195
	s_lshl_b32 vcc_lo, s43, 3
	s_add_u32 vcc_lo, vcc_lo, s42
	s_lshl_b32 vcc_lo, vcc_lo, 17
	v_lshl_add_u32 v145, v193, 8, v195
	v_lshlrev_b32_e32 v145, 1, v145
	v_add_u32_e32 v145, vcc_lo, v145
	s_cmp_lt_i32 s41, 2
	s_cbranch_scc1 .Lg3_k01
	v_readlane_b32 s20, v249, 2
	v_readlane_b32 s21, v249, 3
	v_lshl_add_u32 v151, v144, 11, v150
	v_lshlrev_b32_e32 v151, 1, v151
	v_mul_lo_u32 v146, v144, s3
	v_add_u32_e32 v146, v146, v150
	v_add_u32_e32 v146, 0x5880, v146
	v_mov_b32_e32 v147, v145
	v_mov_b32_e32 v148, v146
	global_load_dwordx2 v[130:131], v148, s[20:21] offset:-2048
	global_load_dwordx2 v[132:133], v148, s[20:21]
	global_load_dwordx2 v[134:135], v148, s[20:21] offset:2048
	global_load_dwordx2 v[136:137], v148, s[20:21] offset:-1920
	global_load_dwordx2 v[160:161], v148, s[20:21] offset:128
	global_load_dwordx2 v[162:163], v148, s[20:21] offset:2176
	global_load_dwordx4 v[164:167], v147, s[58:59]
	global_load_dwordx4 v[168:171], v147, s[60:61]
	global_load_dwordx4 v[172:175], v147, s[58:59] offset:256
	global_load_dwordx4 v[176:179], v147, s[60:61] offset:256
	v_add_u32_e32 v147, 0x2000, v145
	v_add_u32_e32 v148, 0x82000, v146
	global_load_dwordx2 v[198:199], v148, s[20:21] offset:-2048
	global_load_dwordx2 v[200:201], v148, s[20:21]
	global_load_dwordx2 v[202:203], v148, s[20:21] offset:2048
	global_load_dwordx2 v[204:205], v148, s[20:21] offset:-1920
	global_load_dwordx2 v[206:207], v148, s[20:21] offset:128
	global_load_dwordx2 v[208:209], v148, s[20:21] offset:2176
	global_load_dwordx4 v[210:213], v147, s[58:59]
	global_load_dwordx4 v[214:217], v147, s[60:61]
	global_load_dwordx4 v[218:221], v147, s[58:59] offset:256
	global_load_dwordx4 v[222:225], v147, s[60:61] offset:256
	ds_write_b128 v251, v[126:129]
	ds_read_b128 v[126:129], v252
	ds_write_b128 v251, v[122:125]
	ds_read_b128 v[122:125], v252
	ds_write_b128 v251, v[110:113]
	ds_read_b128 v[110:113], v252
	ds_write_b128 v251, v[106:109]
	ds_read_b128 v[106:109], v252
	v_mov_b32_e32 v149, v151
	s_waitcnt vmcnt(10)
	s_waitcnt lgkmcnt(4)
; __device__ __forceinline__ void unpack8(const u32x4 w, float* f) { f[0] = bflo(w.x); f[1] = bfhi(w.x); f[2] = bflo(w.y); f[3] = bfhi(w.y); f[4] = bflo(w.z); f[5] = bfhi(w.z); f[6] = bflo(w.w); f[7] = bfhi(w.w); }
; __device__ __forceinline__ u32x4 pack8(const float* f) { u32x4 w; w.x = cvt_pk(f[0], f[1]); w.y = cvt_pk(f[2], f[3]); w.z = cvt_pk(f[4], f[5]); w.w = cvt_pk(f[6], f[7]); return w; }
;     __device__ __forceinline__ void operator()(const f32x4 (&acc)[2][2][4][2], const UnitD& u, int wr, int wc, int fr, int fq) const {
;     ...
;                     for (int bj = 0; bj < 2; ++bj) { float f0[8], f1[8], f2[8], fa[8], fb[8], o[8];
;                         unpack_u8(g0[bj], f0); unpack_u8(g1[bj], f1); unpack_u8(g2[bj], f2); unpack8(a[bj], fa); unpack8(b[bj], fb);
;                         const f32x4 v0 = acc[ai][bj][m][0], v1 = acc[ai][bj][m][1];
; #pragma unroll
;                         for (int j = 0; j < 4; ++j) { o[j] = f0[j] * fa[j] + f1[j] * fb[j] + f2[j] * v0[j]; o[4 + j] = f0[4 + j] * fa[4 + j] + f1[4 + j] * fb[4 + j] + f2[4 + j] * v1[j]; }
;                         *(u32x4*)(H + po + bj * HALF) = pack8(o); } }
	v_cvt_f32_ubyte0_e32 v152, v130
	v_cvt_f32_ubyte0_e32 v153, v132
	v_cvt_f32_ubyte0_e32 v154, v134
	v_lshlrev_b32_e32 v155, 16, v164
	v_lshlrev_b32_e32 v156, 16, v168
	v_mul_f32_e32 v152, 0x3b808081, v152
	v_mul_f32_e32 v153, 0x3b808081, v153
	v_mul_f32_e32 v154, 0x3b808081, v154
	v_mul_f32_e32 v157, v152, v155
	v_fmac_f32_e32 v157, v153, v156
	v_fma_f32 v126, v154, v126, v157
	v_cvt_f32_ubyte1_e32 v152, v130
	v_cvt_f32_ubyte1_e32 v153, v132
	v_cvt_f32_ubyte1_e32 v154, v134
	v_and_b32_e32 v155, 0xffff0000, v164
	v_and_b32_e32 v156, 0xffff0000, v168
	v_mul_f32_e32 v152, 0x3b808081, v152
	v_mul_f32_e32 v153, 0x3b808081, v153
	v_mul_f32_e32 v154, 0x3b808081, v154
	v_mul_f32_e32 v157, v152, v155
	v_fmac_f32_e32 v157, v153, v156
	v_fma_f32 v127, v154, v127, v157
	v_cvt_f32_ubyte2_e32 v152, v130
	v_cvt_f32_ubyte2_e32 v153, v132
	v_cvt_f32_ubyte2_e32 v154, v134
	v_lshlrev_b32_e32 v155, 16, v165
	v_lshlrev_b32_e32 v156, 16, v169
	v_mul_f32_e32 v152, 0x3b808081, v152
	v_mul_f32_e32 v153, 0x3b808081, v153
	v_mul_f32_e32 v154, 0x3b808081, v154
	v_mul_f32_e32 v157, v152, v155
	v_fmac_f32_e32 v157, v153, v156
	v_fma_f32 v128, v154, v128, v157
	v_cvt_f32_ubyte3_e32 v152, v130
	v_cvt_f32_ubyte3_e32 v153, v132
	v_cvt_f32_ubyte3_e32 v154, v134
	v_and_b32_e32 v155, 0xffff0000, v165
	v_and_b32_e32 v156, 0xffff0000, v169
	v_mul_f32_e32 v152, 0x3b808081, v152
	v_mul_f32_e32 v153, 0x3b808081, v153
	v_mul_f32_e32 v154, 0x3b808081, v154
	v_mul_f32_e32 v157, v152, v155
	v_fmac_f32_e32 v157, v153, v156
	v_fma_f32 v129, v154, v129, v157
	v_cvt_f32_ubyte0_e32 v152, v131
	v_cvt_f32_ubyte0_e32 v153, v133
	v_cvt_f32_ubyte0_e32 v154, v135
	v_lshlrev_b32_e32 v155, 16, v166
	v_lshlrev_b32_e32 v156, 16, v170
	v_mul_f32_e32 v152, 0x3b808081, v152
	v_mul_f32_e32 v153, 0x3b808081, v153
	v_mul_f32_e32 v154, 0x3b808081, v154
	v_mul_f32_e32 v157, v152, v155
	v_fmac_f32_e32 v157, v153, v156
	v_fma_f32 v122, v154, v122, v157
	v_cvt_f32_ubyte1_e32 v152, v131
	v_cvt_f32_ubyte1_e32 v153, v133
	v_cvt_f32_ubyte1_e32 v154, v135
	v_and_b32_e32 v155, 0xffff0000, v166
	v_and_b32_e32 v156, 0xffff0000, v170
	v_mul_f32_e32 v152, 0x3b808081, v152
	v_mul_f32_e32 v153, 0x3b808081, v153
	v_mul_f32_e32 v154, 0x3b808081, v154
	v_mul_f32_e32 v157, v152, v155
	v_fmac_f32_e32 v157, v153, v156
	v_fma_f32 v123, v154, v123, v157
	v_cvt_f32_ubyte2_e32 v152, v131
	v_cvt_f32_ubyte2_e32 v153, v133
	v_cvt_f32_ubyte2_e32 v154, v135
	v_lshlrev_b32_e32 v155, 16, v167
	v_lshlrev_b32_e32 v156, 16, v171
	v_mul_f32_e32 v152, 0x3b808081, v152
	v_mul_f32_e32 v153, 0x3b808081, v153
	v_mul_f32_e32 v154, 0x3b808081, v154
	v_mul_f32_e32 v157, v152, v155
	v_fmac_f32_e32 v157, v153, v156
	v_fma_f32 v124, v154, v124, v157
	v_cvt_f32_ubyte3_e32 v152, v131
	v_cvt_f32_ubyte3_e32 v153, v133
	v_cvt_f32_ubyte3_e32 v154, v135
	v_and_b32_e32 v155, 0xffff0000, v167
	v_and_b32_e32 v156, 0xffff0000, v171
	v_mul_f32_e32 v152, 0x3b808081, v152
	v_mul_f32_e32 v153, 0x3b808081, v153
	v_mul_f32_e32 v154, 0x3b808081, v154
	v_mul_f32_e32 v157, v152, v155
	v_fmac_f32_e32 v157, v153, v156
	v_fma_f32 v125, v154, v125, v157
	v_cvt_pk_bf16_f32 v126, v126, v127
	v_cvt_pk_bf16_f32 v127, v128, v129
	v_cvt_pk_bf16_f32 v128, v122, v123
	v_cvt_pk_bf16_f32 v129, v124, v125
	s_waitcnt lgkmcnt(0)
	v_cvt_f32_ubyte0_e32 v152, v136
	v_cvt_f32_ubyte0_e32 v153, v160
	v_cvt_f32_ubyte0_e32 v154, v162
	v_lshlrev_b32_e32 v155, 16, v172
	v_lshlrev_b32_e32 v156, 16, v176
	v_mul_f32_e32 v152, 0x3b808081, v152
	v_mul_f32_e32 v153, 0x3b808081, v153
	v_mul_f32_e32 v154, 0x3b808081, v154
	v_mul_f32_e32 v157, v152, v155
	v_fmac_f32_e32 v157, v153, v156
	v_fma_f32 v110, v154, v110, v157
	v_cvt_f32_ubyte1_e32 v152, v136
	v_cvt_f32_ubyte1_e32 v153, v160
	v_cvt_f32_ubyte1_e32 v154, v162
	v_and_b32_e32 v155, 0xffff0000, v172
	v_and_b32_e32 v156, 0xffff0000, v176
	v_mul_f32_e32 v152, 0x3b808081, v152
	v_mul_f32_e32 v153, 0x3b808081, v153
	v_mul_f32_e32 v154, 0x3b808081, v154
	v_mul_f32_e32 v157, v152, v155
	v_fmac_f32_e32 v157, v153, v156
	v_fma_f32 v111, v154, v111, v157
	v_cvt_f32_ubyte2_e32 v152, v136
	v_cvt_f32_ubyte2_e32 v153, v160
	v_cvt_f32_ubyte2_e32 v154, v162
	v_lshlrev_b32_e32 v155, 16, v173
	v_lshlrev_b32_e32 v156, 16, v177
	v_mul_f32_e32 v152, 0x3b808081, v152
	v_mul_f32_e32 v153, 0x3b808081, v153
	v_mul_f32_e32 v154, 0x3b808081, v154
	v_mul_f32_e32 v157, v152, v155
	v_fmac_f32_e32 v157, v153, v156
	v_fma_f32 v112, v154, v112, v157
	v_cvt_f32_ubyte3_e32 v152, v136
	v_cvt_f32_ubyte3_e32 v153, v160
	v_cvt_f32_ubyte3_e32 v154, v162
	v_and_b32_e32 v155, 0xffff0000, v173
	v_and_b32_e32 v156, 0xffff0000, v177
	v_mul_f32_e32 v152, 0x3b808081, v152
	v_mul_f32_e32 v153, 0x3b808081, v153
	v_mul_f32_e32 v154, 0x3b808081, v154
	v_mul_f32_e32 v157, v152, v155
	v_fmac_f32_e32 v157, v153, v156
	v_fma_f32 v113, v154, v113, v157
	v_cvt_f32_ubyte0_e32 v152, v137
	v_cvt_f32_ubyte0_e32 v153, v161
	v_cvt_f32_ubyte0_e32 v154, v163
	v_lshlrev_b32_e32 v155, 16, v174
	v_lshlrev_b32_e32 v156, 16, v178
	v_mul_f32_e32 v152, 0x3b808081, v152
	v_mul_f32_e32 v153, 0x3b808081, v153
	v_mul_f32_e32 v154, 0x3b808081, v154
	v_mul_f32_e32 v157, v152, v155
	v_fmac_f32_e32 v157, v153, v156
	v_fma_f32 v106, v154, v106, v157
	v_cvt_f32_ubyte1_e32 v152, v137
	v_cvt_f32_ubyte1_e32 v153, v161
	v_cvt_f32_ubyte1_e32 v154, v163
	v_and_b32_e32 v155, 0xffff0000, v174
	v_and_b32_e32 v156, 0xffff0000, v178
	v_mul_f32_e32 v152, 0x3b808081, v152
	v_mul_f32_e32 v153, 0x3b808081, v153
	v_mul_f32_e32 v154, 0x3b808081, v154
	v_mul_f32_e32 v157, v152, v155
	v_fmac_f32_e32 v157, v153, v156
	v_fma_f32 v107, v154, v107, v157
	v_cvt_f32_ubyte2_e32 v152, v137
	v_cvt_f32_ubyte2_e32 v153, v161
	v_cvt_f32_ubyte2_e32 v154, v163
; __device__ __forceinline__ void unpack8(const u32x4 w, float* f) { f[0] = bflo(w.x); f[1] = bfhi(w.x); f[2] = bflo(w.y); f[3] = bfhi(w.y); f[4] = bflo(w.z); f[5] = bfhi(w.z); f[6] = bflo(w.w); f[7] = bfhi(w.w); }
; __device__ __forceinline__ u32x4 pack8(const float* f) { u32x4 w; w.x = cvt_pk(f[0], f[1]); w.y = cvt_pk(f[2], f[3]); w.z = cvt_pk(f[4], f[5]); w.w = cvt_pk(f[6], f[7]); return w; }
;     __device__ __forceinline__ void operator()(const f32x4 (&acc)[2][2][4][2], const UnitD& u, int wr, int wc, int fr, int fq) const {
;     ...
;                     for (int bj = 0; bj < 2; ++bj) { g0[bj] = *(const u32x2*)(gp + bj * HALF); g1[bj] = *(const u32x2*)(gp + 2048 + bj * HALF); g2[bj] = *(const u32x2*)(gp + 4096 + bj * HALF);
;                         a[bj] = *(const u32x4*)(PA + po + bj * HALF); b[bj] = *(const u32x4*)(PB + po + bj * HALF); }
; #pragma unroll
;                     for (int bj = 0; bj < 2; ++bj) { float f0[8], f1[8], f2[8], fa[8], fb[8], o[8];
;                         unpack_u8(g0[bj], f0); unpack_u8(g1[bj], f1); unpack_u8(g2[bj], f2); unpack8(a[bj], fa); unpack8(b[bj], fb);
;                         const f32x4 v0 = acc[ai][bj][m][0], v1 = acc[ai][bj][m][1];
; #pragma unroll
;                         for (int j = 0; j < 4; ++j) { o[j] = f0[j] * fa[j] + f1[j] * fb[j] + f2[j] * v0[j]; o[4 + j] = f0[4 + j] * fa[4 + j] + f1[4 + j] * fb[4 + j] + f2[4 + j] * v1[j]; }
;                         *(u32x4*)(H + po + bj * HALF) = pack8(o); } }
	v_lshlrev_b32_e32 v155, 16, v175
	v_lshlrev_b32_e32 v156, 16, v179
	v_mul_f32_e32 v152, 0x3b808081, v152
	v_mul_f32_e32 v153, 0x3b808081, v153
	v_mul_f32_e32 v154, 0x3b808081, v154
	v_mul_f32_e32 v157, v152, v155
	v_fmac_f32_e32 v157, v153, v156
	v_fma_f32 v108, v154, v108, v157
	v_cvt_f32_ubyte3_e32 v152, v137
	v_cvt_f32_ubyte3_e32 v153, v161
	v_cvt_f32_ubyte3_e32 v154, v163
	v_and_b32_e32 v155, 0xffff0000, v175
	v_and_b32_e32 v156, 0xffff0000, v179
	v_mul_f32_e32 v152, 0x3b808081, v152
	v_mul_f32_e32 v153, 0x3b808081, v153
	v_mul_f32_e32 v154, 0x3b808081, v154
	v_mul_f32_e32 v157, v152, v155
	v_fmac_f32_e32 v157, v153, v156
	v_fma_f32 v109, v154, v109, v157
	v_cvt_pk_bf16_f32 v110, v110, v111
	v_cvt_pk_bf16_f32 v111, v112, v113
	v_cvt_pk_bf16_f32 v112, v106, v107
	v_cvt_pk_bf16_f32 v113, v108, v109
	v_add_u32_e32 v147, 0x4000, v145
	v_add_u32_e32 v148, 0x104000, v146
	global_load_dwordx2 v[130:131], v148, s[20:21] offset:-2048
	global_load_dwordx2 v[132:133], v148, s[20:21]
	global_load_dwordx2 v[134:135], v148, s[20:21] offset:2048
	global_load_dwordx2 v[136:137], v148, s[20:21] offset:-1920
	global_load_dwordx2 v[160:161], v148, s[20:21] offset:128
	global_load_dwordx2 v[162:163], v148, s[20:21] offset:2176
	global_load_dwordx4 v[164:167], v147, s[58:59]
	global_load_dwordx4 v[168:171], v147, s[60:61]
	global_load_dwordx4 v[172:175], v147, s[58:59] offset:256
	global_load_dwordx4 v[176:179], v147, s[60:61] offset:256
	ds_write_b128 v251, v[118:121]
	ds_read_b128 v[118:121], v252
	ds_write_b128 v251, v[114:117]
	ds_read_b128 v[114:117], v252
	ds_write_b128 v251, v[94:97]
	ds_read_b128 v[94:97], v252
	ds_write_b128 v251, v[90:93]
	ds_read_b128 v[90:93], v252
	v_add_u32_e32 v149, 0x10000, v151
	s_waitcnt vmcnt(10)
	s_waitcnt lgkmcnt(4)
	v_cvt_f32_ubyte0_e32 v152, v198
	v_cvt_f32_ubyte0_e32 v153, v200
	v_cvt_f32_ubyte0_e32 v154, v202
	v_lshlrev_b32_e32 v155, 16, v210
	v_lshlrev_b32_e32 v156, 16, v214
	v_mul_f32_e32 v152, 0x3b808081, v152
	v_mul_f32_e32 v153, 0x3b808081, v153
	v_mul_f32_e32 v154, 0x3b808081, v154
	v_mul_f32_e32 v157, v152, v155
	v_fmac_f32_e32 v157, v153, v156
	v_fma_f32 v118, v154, v118, v157
	v_cvt_f32_ubyte1_e32 v152, v198
	v_cvt_f32_ubyte1_e32 v153, v200
	v_cvt_f32_ubyte1_e32 v154, v202
	v_and_b32_e32 v155, 0xffff0000, v210
	v_and_b32_e32 v156, 0xffff0000, v214
	v_mul_f32_e32 v152, 0x3b808081, v152
	v_mul_f32_e32 v153, 0x3b808081, v153
	v_mul_f32_e32 v154, 0x3b808081, v154
	v_mul_f32_e32 v157, v152, v155
	v_fmac_f32_e32 v157, v153, v156
	v_fma_f32 v119, v154, v119, v157
	v_cvt_f32_ubyte2_e32 v152, v198
	v_cvt_f32_ubyte2_e32 v153, v200
	v_cvt_f32_ubyte2_e32 v154, v202
	v_lshlrev_b32_e32 v155, 16, v211
	v_lshlrev_b32_e32 v156, 16, v215
	v_mul_f32_e32 v152, 0x3b808081, v152
	v_mul_f32_e32 v153, 0x3b808081, v153
	v_mul_f32_e32 v154, 0x3b808081, v154
	v_mul_f32_e32 v157, v152, v155
	v_fmac_f32_e32 v157, v153, v156
	v_fma_f32 v120, v154, v120, v157
	v_cvt_f32_ubyte3_e32 v152, v198
	v_cvt_f32_ubyte3_e32 v153, v200
	v_cvt_f32_ubyte3_e32 v154, v202
	v_and_b32_e32 v155, 0xffff0000, v211
	v_and_b32_e32 v156, 0xffff0000, v215
	v_mul_f32_e32 v152, 0x3b808081, v152
	v_mul_f32_e32 v153, 0x3b808081, v153
	v_mul_f32_e32 v154, 0x3b808081, v154
	v_mul_f32_e32 v157, v152, v155
	v_fmac_f32_e32 v157, v153, v156
	v_fma_f32 v121, v154, v121, v157
	v_cvt_f32_ubyte0_e32 v152, v199
	v_cvt_f32_ubyte0_e32 v153, v201
	v_cvt_f32_ubyte0_e32 v154, v203
	v_lshlrev_b32_e32 v155, 16, v212
	v_lshlrev_b32_e32 v156, 16, v216
	v_mul_f32_e32 v152, 0x3b808081, v152
	v_mul_f32_e32 v153, 0x3b808081, v153
	v_mul_f32_e32 v154, 0x3b808081, v154
	v_mul_f32_e32 v157, v152, v155
	v_fmac_f32_e32 v157, v153, v156
	v_fma_f32 v114, v154, v114, v157
	v_cvt_f32_ubyte1_e32 v152, v199
	v_cvt_f32_ubyte1_e32 v153, v201
	v_cvt_f32_ubyte1_e32 v154, v203
	v_and_b32_e32 v155, 0xffff0000, v212
	v_and_b32_e32 v156, 0xffff0000, v216
	v_mul_f32_e32 v152, 0x3b808081, v152
	v_mul_f32_e32 v153, 0x3b808081, v153
	v_mul_f32_e32 v154, 0x3b808081, v154
	v_mul_f32_e32 v157, v152, v155
	v_fmac_f32_e32 v157, v153, v156
	v_fma_f32 v115, v154, v115, v157
	v_cvt_f32_ubyte2_e32 v152, v199
	v_cvt_f32_ubyte2_e32 v153, v201
	v_cvt_f32_ubyte2_e32 v154, v203
	v_lshlrev_b32_e32 v155, 16, v213
	v_lshlrev_b32_e32 v156, 16, v217
	v_mul_f32_e32 v152, 0x3b808081, v152
	v_mul_f32_e32 v153, 0x3b808081, v153
	v_mul_f32_e32 v154, 0x3b808081, v154
	v_mul_f32_e32 v157, v152, v155
	v_fmac_f32_e32 v157, v153, v156
	v_fma_f32 v116, v154, v116, v157
	v_cvt_f32_ubyte3_e32 v152, v199
	v_cvt_f32_ubyte3_e32 v153, v201
	v_cvt_f32_ubyte3_e32 v154, v203
	v_and_b32_e32 v155, 0xffff0000, v213
	v_and_b32_e32 v156, 0xffff0000, v217
	v_mul_f32_e32 v152, 0x3b808081, v152
	v_mul_f32_e32 v153, 0x3b808081, v153
	v_mul_f32_e32 v154, 0x3b808081, v154
	v_mul_f32_e32 v157, v152, v155
	v_fmac_f32_e32 v157, v153, v156
	v_fma_f32 v117, v154, v117, v157
	v_cvt_pk_bf16_f32 v118, v118, v119
	v_cvt_pk_bf16_f32 v119, v120, v121
	v_cvt_pk_bf16_f32 v120, v114, v115
	v_cvt_pk_bf16_f32 v121, v116, v117
	s_waitcnt lgkmcnt(0)
; __device__ __forceinline__ void unpack8(const u32x4 w, float* f) { f[0] = bflo(w.x); f[1] = bfhi(w.x); f[2] = bflo(w.y); f[3] = bfhi(w.y); f[4] = bflo(w.z); f[5] = bfhi(w.z); f[6] = bflo(w.w); f[7] = bfhi(w.w); }
; __device__ __forceinline__ u32x4 pack8(const float* f) { u32x4 w; w.x = cvt_pk(f[0], f[1]); w.y = cvt_pk(f[2], f[3]); w.z = cvt_pk(f[4], f[5]); w.w = cvt_pk(f[6], f[7]); return w; }
;     __device__ __forceinline__ void operator()(const f32x4 (&acc)[2][2][4][2], const UnitD& u, int wr, int wc, int fr, int fq) const {
;     ...
;                     for (int bj = 0; bj < 2; ++bj) { g0[bj] = *(const u32x2*)(gp + bj * HALF); g1[bj] = *(const u32x2*)(gp + 2048 + bj * HALF); g2[bj] = *(const u32x2*)(gp + 4096 + bj * HALF);
;                         a[bj] = *(const u32x4*)(PA + po + bj * HALF); b[bj] = *(const u32x4*)(PB + po + bj * HALF); }
; #pragma unroll
;                     for (int bj = 0; bj < 2; ++bj) { float f0[8], f1[8], f2[8], fa[8], fb[8], o[8];
;                         unpack_u8(g0[bj], f0); unpack_u8(g1[bj], f1); unpack_u8(g2[bj], f2); unpack8(a[bj], fa); unpack8(b[bj], fb);
;                         const f32x4 v0 = acc[ai][bj][m][0], v1 = acc[ai][bj][m][1];
; #pragma unroll
;                         for (int j = 0; j < 4; ++j) { o[j] = f0[j] * fa[j] + f1[j] * fb[j] + f2[j] * v0[j]; o[4 + j] = f0[4 + j] * fa[4 + j] + f1[4 + j] * fb[4 + j] + f2[4 + j] * v1[j]; }
;                         *(u32x4*)(H + po + bj * HALF) = pack8(o); } }
	v_cvt_f32_ubyte0_e32 v152, v204
	v_cvt_f32_ubyte0_e32 v153, v206
	v_cvt_f32_ubyte0_e32 v154, v208
	v_lshlrev_b32_e32 v155, 16, v218
	v_lshlrev_b32_e32 v156, 16, v222
	v_mul_f32_e32 v152, 0x3b808081, v152
	v_mul_f32_e32 v153, 0x3b808081, v153
	v_mul_f32_e32 v154, 0x3b808081, v154
	v_mul_f32_e32 v157, v152, v155
	v_fmac_f32_e32 v157, v153, v156
	v_fma_f32 v94, v154, v94, v157
	v_cvt_f32_ubyte1_e32 v152, v204
	v_cvt_f32_ubyte1_e32 v153, v206
	v_cvt_f32_ubyte1_e32 v154, v208
	v_and_b32_e32 v155, 0xffff0000, v218
	v_and_b32_e32 v156, 0xffff0000, v222
	v_mul_f32_e32 v152, 0x3b808081, v152
	v_mul_f32_e32 v153, 0x3b808081, v153
	v_mul_f32_e32 v154, 0x3b808081, v154
	v_mul_f32_e32 v157, v152, v155
	v_fmac_f32_e32 v157, v153, v156
	v_fma_f32 v95, v154, v95, v157
	v_cvt_f32_ubyte2_e32 v152, v204
	v_cvt_f32_ubyte2_e32 v153, v206
	v_cvt_f32_ubyte2_e32 v154, v208
	v_lshlrev_b32_e32 v155, 16, v219
	v_lshlrev_b32_e32 v156, 16, v223
	v_mul_f32_e32 v152, 0x3b808081, v152
	v_mul_f32_e32 v153, 0x3b808081, v153
	v_mul_f32_e32 v154, 0x3b808081, v154
	v_mul_f32_e32 v157, v152, v155
	v_fmac_f32_e32 v157, v153, v156
	v_fma_f32 v96, v154, v96, v157
	v_cvt_f32_ubyte3_e32 v152, v204
	v_cvt_f32_ubyte3_e32 v153, v206
	v_cvt_f32_ubyte3_e32 v154, v208
	v_and_b32_e32 v155, 0xffff0000, v219
	v_and_b32_e32 v156, 0xffff0000, v223
	v_mul_f32_e32 v152, 0x3b808081, v152
	v_mul_f32_e32 v153, 0x3b808081, v153
	v_mul_f32_e32 v154, 0x3b808081, v154
	v_mul_f32_e32 v157, v152, v155
	v_fmac_f32_e32 v157, v153, v156
	v_fma_f32 v97, v154, v97, v157
	v_cvt_f32_ubyte0_e32 v152, v205
	v_cvt_f32_ubyte0_e32 v153, v207
	v_cvt_f32_ubyte0_e32 v154, v209
	v_lshlrev_b32_e32 v155, 16, v220
	v_lshlrev_b32_e32 v156, 16, v224
	v_mul_f32_e32 v152, 0x3b808081, v152
	v_mul_f32_e32 v153, 0x3b808081, v153
	v_mul_f32_e32 v154, 0x3b808081, v154
	v_mul_f32_e32 v157, v152, v155
	v_fmac_f32_e32 v157, v153, v156
	v_fma_f32 v90, v154, v90, v157
	v_cvt_f32_ubyte1_e32 v152, v205
	v_cvt_f32_ubyte1_e32 v153, v207
	v_cvt_f32_ubyte1_e32 v154, v209
	v_and_b32_e32 v155, 0xffff0000, v220
	v_and_b32_e32 v156, 0xffff0000, v224
	v_mul_f32_e32 v152, 0x3b808081, v152
	v_mul_f32_e32 v153, 0x3b808081, v153
	v_mul_f32_e32 v154, 0x3b808081, v154
	v_mul_f32_e32 v157, v152, v155
	v_fmac_f32_e32 v157, v153, v156
	v_fma_f32 v91, v154, v91, v157
	v_cvt_f32_ubyte2_e32 v152, v205
	v_cvt_f32_ubyte2_e32 v153, v207
	v_cvt_f32_ubyte2_e32 v154, v209
	v_lshlrev_b32_e32 v155, 16, v221
	v_lshlrev_b32_e32 v156, 16, v225
	v_mul_f32_e32 v152, 0x3b808081, v152
	v_mul_f32_e32 v153, 0x3b808081, v153
	v_mul_f32_e32 v154, 0x3b808081, v154
	v_mul_f32_e32 v157, v152, v155
	v_fmac_f32_e32 v157, v153, v156
	v_fma_f32 v92, v154, v92, v157
	v_cvt_f32_ubyte3_e32 v152, v205
	v_cvt_f32_ubyte3_e32 v153, v207
	v_cvt_f32_ubyte3_e32 v154, v209
	v_and_b32_e32 v155, 0xffff0000, v221
	v_and_b32_e32 v156, 0xffff0000, v225
	v_mul_f32_e32 v152, 0x3b808081, v152
	v_mul_f32_e32 v153, 0x3b808081, v153
	v_mul_f32_e32 v154, 0x3b808081, v154
	v_mul_f32_e32 v157, v152, v155
	v_fmac_f32_e32 v157, v153, v156
	v_fma_f32 v93, v154, v93, v157
	v_cvt_pk_bf16_f32 v94, v94, v95
	v_cvt_pk_bf16_f32 v95, v96, v97
	v_cvt_pk_bf16_f32 v96, v90, v91
	v_cvt_pk_bf16_f32 v97, v92, v93
	v_add_u32_e32 v147, 0x6000, v145
	v_add_u32_e32 v148, 0x186000, v146
	global_load_dwordx2 v[198:199], v148, s[20:21] offset:-2048
	global_load_dwordx2 v[200:201], v148, s[20:21]
	global_load_dwordx2 v[202:203], v148, s[20:21] offset:2048
	global_load_dwordx2 v[204:205], v148, s[20:21] offset:-1920
	global_load_dwordx2 v[206:207], v148, s[20:21] offset:128
	global_load_dwordx2 v[208:209], v148, s[20:21] offset:2176
	global_load_dwordx4 v[210:213], v147, s[58:59]
	global_load_dwordx4 v[214:217], v147, s[60:61]
	global_load_dwordx4 v[218:221], v147, s[58:59] offset:256
	global_load_dwordx4 v[222:225], v147, s[60:61] offset:256
	ds_write_b128 v251, v[102:105]
	ds_read_b128 v[102:105], v252
	ds_write_b128 v251, v[98:101]
	ds_read_b128 v[98:101], v252
	ds_write_b128 v251, v[78:81]
	ds_read_b128 v[78:81], v252
	ds_write_b128 v251, v[74:77]
	ds_read_b128 v[74:77], v252
	v_add_u32_e32 v149, 0x20000, v151
	s_waitcnt vmcnt(10)
	s_waitcnt lgkmcnt(4)
	v_cvt_f32_ubyte0_e32 v152, v130
	v_cvt_f32_ubyte0_e32 v153, v132
	v_cvt_f32_ubyte0_e32 v154, v134
	v_lshlrev_b32_e32 v155, 16, v164
	v_lshlrev_b32_e32 v156, 16, v168
	v_mul_f32_e32 v152, 0x3b808081, v152
	v_mul_f32_e32 v153, 0x3b808081, v153
	v_mul_f32_e32 v154, 0x3b808081, v154
	v_mul_f32_e32 v157, v152, v155
	v_fmac_f32_e32 v157, v153, v156
	v_fma_f32 v102, v154, v102, v157
	v_cvt_f32_ubyte1_e32 v152, v130
	v_cvt_f32_ubyte1_e32 v153, v132
	v_cvt_f32_ubyte1_e32 v154, v134
	v_and_b32_e32 v155, 0xffff0000, v164
	v_and_b32_e32 v156, 0xffff0000, v168
	v_mul_f32_e32 v152, 0x3b808081, v152
	v_mul_f32_e32 v153, 0x3b808081, v153
	v_mul_f32_e32 v154, 0x3b808081, v154
	v_mul_f32_e32 v157, v152, v155
	v_fmac_f32_e32 v157, v153, v156
	v_fma_f32 v103, v154, v103, v157
	v_cvt_f32_ubyte2_e32 v152, v130
	v_cvt_f32_ubyte2_e32 v153, v132
	v_cvt_f32_ubyte2_e32 v154, v134
	v_lshlrev_b32_e32 v155, 16, v165
	v_lshlrev_b32_e32 v156, 16, v169
	v_mul_f32_e32 v152, 0x3b808081, v152
	v_mul_f32_e32 v153, 0x3b808081, v153
	v_mul_f32_e32 v154, 0x3b808081, v154
	v_mul_f32_e32 v157, v152, v155
	v_fmac_f32_e32 v157, v153, v156
	v_fma_f32 v104, v154, v104, v157
	v_cvt_f32_ubyte3_e32 v152, v130
	v_cvt_f32_ubyte3_e32 v153, v132
	v_cvt_f32_ubyte3_e32 v154, v134
	v_and_b32_e32 v155, 0xffff0000, v165
	v_and_b32_e32 v156, 0xffff0000, v169
	v_mul_f32_e32 v152, 0x3b808081, v152
	v_mul_f32_e32 v153, 0x3b808081, v153
	v_mul_f32_e32 v154, 0x3b808081, v154
	v_mul_f32_e32 v157, v152, v155
	v_fmac_f32_e32 v157, v153, v156
; __device__ __forceinline__ void unpack8(const u32x4 w, float* f) { f[0] = bflo(w.x); f[1] = bfhi(w.x); f[2] = bflo(w.y); f[3] = bfhi(w.y); f[4] = bflo(w.z); f[5] = bfhi(w.z); f[6] = bflo(w.w); f[7] = bfhi(w.w); }
; __device__ __forceinline__ u32x4 pack8(const float* f) { u32x4 w; w.x = cvt_pk(f[0], f[1]); w.y = cvt_pk(f[2], f[3]); w.z = cvt_pk(f[4], f[5]); w.w = cvt_pk(f[6], f[7]); return w; }
;     __device__ __forceinline__ void operator()(const f32x4 (&acc)[2][2][4][2], const UnitD& u, int wr, int wc, int fr, int fq) const {
;     ...
;                     for (int bj = 0; bj < 2; ++bj) { g0[bj] = *(const u32x2*)(gp + bj * HALF); g1[bj] = *(const u32x2*)(gp + 2048 + bj * HALF); g2[bj] = *(const u32x2*)(gp + 4096 + bj * HALF);
;                         a[bj] = *(const u32x4*)(PA + po + bj * HALF); b[bj] = *(const u32x4*)(PB + po + bj * HALF); }
; #pragma unroll
;                     for (int bj = 0; bj < 2; ++bj) { float f0[8], f1[8], f2[8], fa[8], fb[8], o[8];
;                         unpack_u8(g0[bj], f0); unpack_u8(g1[bj], f1); unpack_u8(g2[bj], f2); unpack8(a[bj], fa); unpack8(b[bj], fb);
;                         const f32x4 v0 = acc[ai][bj][m][0], v1 = acc[ai][bj][m][1];
; #pragma unroll
;                         for (int j = 0; j < 4; ++j) { o[j] = f0[j] * fa[j] + f1[j] * fb[j] + f2[j] * v0[j]; o[4 + j] = f0[4 + j] * fa[4 + j] + f1[4 + j] * fb[4 + j] + f2[4 + j] * v1[j]; }
;                         *(u32x4*)(H + po + bj * HALF) = pack8(o); } }
	v_fma_f32 v105, v154, v105, v157
	v_cvt_f32_ubyte0_e32 v152, v131
	v_cvt_f32_ubyte0_e32 v153, v133
	v_cvt_f32_ubyte0_e32 v154, v135
	v_lshlrev_b32_e32 v155, 16, v166
	v_lshlrev_b32_e32 v156, 16, v170
	v_mul_f32_e32 v152, 0x3b808081, v152
	v_mul_f32_e32 v153, 0x3b808081, v153
	v_mul_f32_e32 v154, 0x3b808081, v154
	v_mul_f32_e32 v157, v152, v155
	v_fmac_f32_e32 v157, v153, v156
	v_fma_f32 v98, v154, v98, v157
	v_cvt_f32_ubyte1_e32 v152, v131
	v_cvt_f32_ubyte1_e32 v153, v133
	v_cvt_f32_ubyte1_e32 v154, v135
	v_and_b32_e32 v155, 0xffff0000, v166
	v_and_b32_e32 v156, 0xffff0000, v170
	v_mul_f32_e32 v152, 0x3b808081, v152
	v_mul_f32_e32 v153, 0x3b808081, v153
	v_mul_f32_e32 v154, 0x3b808081, v154
	v_mul_f32_e32 v157, v152, v155
	v_fmac_f32_e32 v157, v153, v156
	v_fma_f32 v99, v154, v99, v157
	v_cvt_f32_ubyte2_e32 v152, v131
	v_cvt_f32_ubyte2_e32 v153, v133
	v_cvt_f32_ubyte2_e32 v154, v135
	v_lshlrev_b32_e32 v155, 16, v167
	v_lshlrev_b32_e32 v156, 16, v171
	v_mul_f32_e32 v152, 0x3b808081, v152
	v_mul_f32_e32 v153, 0x3b808081, v153
	v_mul_f32_e32 v154, 0x3b808081, v154
	v_mul_f32_e32 v157, v152, v155
	v_fmac_f32_e32 v157, v153, v156
	v_fma_f32 v100, v154, v100, v157
	v_cvt_f32_ubyte3_e32 v152, v131
	v_cvt_f32_ubyte3_e32 v153, v133
	v_cvt_f32_ubyte3_e32 v154, v135
	v_and_b32_e32 v155, 0xffff0000, v167
	v_and_b32_e32 v156, 0xffff0000, v171
	v_mul_f32_e32 v152, 0x3b808081, v152
	v_mul_f32_e32 v153, 0x3b808081, v153
	v_mul_f32_e32 v154, 0x3b808081, v154
	v_mul_f32_e32 v157, v152, v155
	v_fmac_f32_e32 v157, v153, v156
	v_fma_f32 v101, v154, v101, v157
	v_cvt_pk_bf16_f32 v102, v102, v103
	v_cvt_pk_bf16_f32 v103, v104, v105
	v_cvt_pk_bf16_f32 v104, v98, v99
	v_cvt_pk_bf16_f32 v105, v100, v101
	s_waitcnt lgkmcnt(0)
	v_cvt_f32_ubyte0_e32 v152, v136
	v_cvt_f32_ubyte0_e32 v153, v160
	v_cvt_f32_ubyte0_e32 v154, v162
	v_lshlrev_b32_e32 v155, 16, v172
	v_lshlrev_b32_e32 v156, 16, v176
	v_mul_f32_e32 v152, 0x3b808081, v152
	v_mul_f32_e32 v153, 0x3b808081, v153
	v_mul_f32_e32 v154, 0x3b808081, v154
	v_mul_f32_e32 v157, v152, v155
	v_fmac_f32_e32 v157, v153, v156
	v_fma_f32 v78, v154, v78, v157
	v_cvt_f32_ubyte1_e32 v152, v136
	v_cvt_f32_ubyte1_e32 v153, v160
	v_cvt_f32_ubyte1_e32 v154, v162
	v_and_b32_e32 v155, 0xffff0000, v172
	v_and_b32_e32 v156, 0xffff0000, v176
	v_mul_f32_e32 v152, 0x3b808081, v152
	v_mul_f32_e32 v153, 0x3b808081, v153
	v_mul_f32_e32 v154, 0x3b808081, v154
	v_mul_f32_e32 v157, v152, v155
	v_fmac_f32_e32 v157, v153, v156
	v_fma_f32 v79, v154, v79, v157
	v_cvt_f32_ubyte2_e32 v152, v136
	v_cvt_f32_ubyte2_e32 v153, v160
	v_cvt_f32_ubyte2_e32 v154, v162
	v_lshlrev_b32_e32 v155, 16, v173
	v_lshlrev_b32_e32 v156, 16, v177
	v_mul_f32_e32 v152, 0x3b808081, v152
	v_mul_f32_e32 v153, 0x3b808081, v153
	v_mul_f32_e32 v154, 0x3b808081, v154
	v_mul_f32_e32 v157, v152, v155
	v_fmac_f32_e32 v157, v153, v156
	v_fma_f32 v80, v154, v80, v157
	v_cvt_f32_ubyte3_e32 v152, v136
	v_cvt_f32_ubyte3_e32 v153, v160
	v_cvt_f32_ubyte3_e32 v154, v162
	v_and_b32_e32 v155, 0xffff0000, v173
	v_and_b32_e32 v156, 0xffff0000, v177
	v_mul_f32_e32 v152, 0x3b808081, v152
	v_mul_f32_e32 v153, 0x3b808081, v153
	v_mul_f32_e32 v154, 0x3b808081, v154
	v_mul_f32_e32 v157, v152, v155
	v_fmac_f32_e32 v157, v153, v156
	v_fma_f32 v81, v154, v81, v157
	v_cvt_f32_ubyte0_e32 v152, v137
	v_cvt_f32_ubyte0_e32 v153, v161
	v_cvt_f32_ubyte0_e32 v154, v163
	v_lshlrev_b32_e32 v155, 16, v174
	v_lshlrev_b32_e32 v156, 16, v178
	v_mul_f32_e32 v152, 0x3b808081, v152
	v_mul_f32_e32 v153, 0x3b808081, v153
	v_mul_f32_e32 v154, 0x3b808081, v154
	v_mul_f32_e32 v157, v152, v155
	v_fmac_f32_e32 v157, v153, v156
	v_fma_f32 v74, v154, v74, v157
	v_cvt_f32_ubyte1_e32 v152, v137
	v_cvt_f32_ubyte1_e32 v153, v161
	v_cvt_f32_ubyte1_e32 v154, v163
	v_and_b32_e32 v155, 0xffff0000, v174
	v_and_b32_e32 v156, 0xffff0000, v178
	v_mul_f32_e32 v152, 0x3b808081, v152
	v_mul_f32_e32 v153, 0x3b808081, v153
	v_mul_f32_e32 v154, 0x3b808081, v154
	v_mul_f32_e32 v157, v152, v155
	v_fmac_f32_e32 v157, v153, v156
	v_fma_f32 v75, v154, v75, v157
	v_cvt_f32_ubyte2_e32 v152, v137
	v_cvt_f32_ubyte2_e32 v153, v161
	v_cvt_f32_ubyte2_e32 v154, v163
	v_lshlrev_b32_e32 v155, 16, v175
	v_lshlrev_b32_e32 v156, 16, v179
	v_mul_f32_e32 v152, 0x3b808081, v152
	v_mul_f32_e32 v153, 0x3b808081, v153
	v_mul_f32_e32 v154, 0x3b808081, v154
	v_mul_f32_e32 v157, v152, v155
	v_fmac_f32_e32 v157, v153, v156
	v_fma_f32 v76, v154, v76, v157
	v_cvt_f32_ubyte3_e32 v152, v137
	v_cvt_f32_ubyte3_e32 v153, v161
	v_cvt_f32_ubyte3_e32 v154, v163
	v_and_b32_e32 v155, 0xffff0000, v175
	v_and_b32_e32 v156, 0xffff0000, v179
	v_mul_f32_e32 v152, 0x3b808081, v152
	v_mul_f32_e32 v153, 0x3b808081, v153
	v_mul_f32_e32 v154, 0x3b808081, v154
	v_mul_f32_e32 v157, v152, v155
	v_fmac_f32_e32 v157, v153, v156
	v_fma_f32 v77, v154, v77, v157
	v_cvt_pk_bf16_f32 v78, v78, v79
	v_cvt_pk_bf16_f32 v79, v80, v81
	v_cvt_pk_bf16_f32 v80, v74, v75
	v_cvt_pk_bf16_f32 v81, v76, v77
	v_add_u32_e32 v147, 0x10000, v145
	v_add_u32_e32 v148, 0x410000, v146
	global_load_dwordx2 v[130:131], v148, s[20:21] offset:-2048
	global_load_dwordx2 v[132:133], v148, s[20:21]
	global_load_dwordx2 v[134:135], v148, s[20:21] offset:2048
	global_load_dwordx2 v[136:137], v148, s[20:21] offset:-1920
	global_load_dwordx2 v[160:161], v148, s[20:21] offset:128
	global_load_dwordx2 v[162:163], v148, s[20:21] offset:2176
	global_load_dwordx4 v[164:167], v147, s[58:59]
	global_load_dwordx4 v[168:171], v147, s[60:61]
	global_load_dwordx4 v[172:175], v147, s[58:59] offset:256
	global_load_dwordx4 v[176:179], v147, s[60:61] offset:256
	ds_write_b128 v251, v[86:89]
	ds_read_b128 v[86:89], v252
	ds_write_b128 v251, v[82:85]
	ds_read_b128 v[82:85], v252
	ds_write_b128 v251, v[70:73]
	ds_read_b128 v[70:73], v252
	ds_write_b128 v251, v[66:69]
	ds_read_b128 v[66:69], v252
	v_add_u32_e32 v149, 0x30000, v151
	s_waitcnt vmcnt(10)
; __device__ __forceinline__ void unpack8(const u32x4 w, float* f) { f[0] = bflo(w.x); f[1] = bfhi(w.x); f[2] = bflo(w.y); f[3] = bfhi(w.y); f[4] = bflo(w.z); f[5] = bfhi(w.z); f[6] = bflo(w.w); f[7] = bfhi(w.w); }
; __device__ __forceinline__ u32x4 pack8(const float* f) { u32x4 w; w.x = cvt_pk(f[0], f[1]); w.y = cvt_pk(f[2], f[3]); w.z = cvt_pk(f[4], f[5]); w.w = cvt_pk(f[6], f[7]); return w; }
;     __device__ __forceinline__ void operator()(const f32x4 (&acc)[2][2][4][2], const UnitD& u, int wr, int wc, int fr, int fq) const {
;     ...
;                     for (int bj = 0; bj < 2; ++bj) { g0[bj] = *(const u32x2*)(gp + bj * HALF); g1[bj] = *(const u32x2*)(gp + 2048 + bj * HALF); g2[bj] = *(const u32x2*)(gp + 4096 + bj * HALF);
;                         a[bj] = *(const u32x4*)(PA + po + bj * HALF); b[bj] = *(const u32x4*)(PB + po + bj * HALF); }
; #pragma unroll
;                     for (int bj = 0; bj < 2; ++bj) { float f0[8], f1[8], f2[8], fa[8], fb[8], o[8];
;                         unpack_u8(g0[bj], f0); unpack_u8(g1[bj], f1); unpack_u8(g2[bj], f2); unpack8(a[bj], fa); unpack8(b[bj], fb);
;                         const f32x4 v0 = acc[ai][bj][m][0], v1 = acc[ai][bj][m][1];
; #pragma unroll
;                         for (int j = 0; j < 4; ++j) { o[j] = f0[j] * fa[j] + f1[j] * fb[j] + f2[j] * v0[j]; o[4 + j] = f0[4 + j] * fa[4 + j] + f1[4 + j] * fb[4 + j] + f2[4 + j] * v1[j]; }
;                         *(u32x4*)(H + po + bj * HALF) = pack8(o); } }
	s_waitcnt lgkmcnt(4)
	v_cvt_f32_ubyte0_e32 v152, v198
	v_cvt_f32_ubyte0_e32 v153, v200
	v_cvt_f32_ubyte0_e32 v154, v202
	v_lshlrev_b32_e32 v155, 16, v210
	v_lshlrev_b32_e32 v156, 16, v214
	v_mul_f32_e32 v152, 0x3b808081, v152
	v_mul_f32_e32 v153, 0x3b808081, v153
	v_mul_f32_e32 v154, 0x3b808081, v154
	v_mul_f32_e32 v157, v152, v155
	v_fmac_f32_e32 v157, v153, v156
	v_fma_f32 v86, v154, v86, v157
	v_cvt_f32_ubyte1_e32 v152, v198
	v_cvt_f32_ubyte1_e32 v153, v200
	v_cvt_f32_ubyte1_e32 v154, v202
	v_and_b32_e32 v155, 0xffff0000, v210
	v_and_b32_e32 v156, 0xffff0000, v214
	v_mul_f32_e32 v152, 0x3b808081, v152
	v_mul_f32_e32 v153, 0x3b808081, v153
	v_mul_f32_e32 v154, 0x3b808081, v154
	v_mul_f32_e32 v157, v152, v155
	v_fmac_f32_e32 v157, v153, v156
	v_fma_f32 v87, v154, v87, v157
	v_cvt_f32_ubyte2_e32 v152, v198
	v_cvt_f32_ubyte2_e32 v153, v200
	v_cvt_f32_ubyte2_e32 v154, v202
	v_lshlrev_b32_e32 v155, 16, v211
	v_lshlrev_b32_e32 v156, 16, v215
	v_mul_f32_e32 v152, 0x3b808081, v152
	v_mul_f32_e32 v153, 0x3b808081, v153
	v_mul_f32_e32 v154, 0x3b808081, v154
	v_mul_f32_e32 v157, v152, v155
	v_fmac_f32_e32 v157, v153, v156
	v_fma_f32 v88, v154, v88, v157
	v_cvt_f32_ubyte3_e32 v152, v198
	v_cvt_f32_ubyte3_e32 v153, v200
	v_cvt_f32_ubyte3_e32 v154, v202
	v_and_b32_e32 v155, 0xffff0000, v211
	v_and_b32_e32 v156, 0xffff0000, v215
	v_mul_f32_e32 v152, 0x3b808081, v152
	v_mul_f32_e32 v153, 0x3b808081, v153
	v_mul_f32_e32 v154, 0x3b808081, v154
	v_mul_f32_e32 v157, v152, v155
	v_fmac_f32_e32 v157, v153, v156
	v_fma_f32 v89, v154, v89, v157
	v_cvt_f32_ubyte0_e32 v152, v199
	v_cvt_f32_ubyte0_e32 v153, v201
	v_cvt_f32_ubyte0_e32 v154, v203
	v_lshlrev_b32_e32 v155, 16, v212
	v_lshlrev_b32_e32 v156, 16, v216
	v_mul_f32_e32 v152, 0x3b808081, v152
	v_mul_f32_e32 v153, 0x3b808081, v153
	v_mul_f32_e32 v154, 0x3b808081, v154
	v_mul_f32_e32 v157, v152, v155
	v_fmac_f32_e32 v157, v153, v156
	v_fma_f32 v82, v154, v82, v157
	v_cvt_f32_ubyte1_e32 v152, v199
	v_cvt_f32_ubyte1_e32 v153, v201
	v_cvt_f32_ubyte1_e32 v154, v203
	v_and_b32_e32 v155, 0xffff0000, v212
	v_and_b32_e32 v156, 0xffff0000, v216
	v_mul_f32_e32 v152, 0x3b808081, v152
	v_mul_f32_e32 v153, 0x3b808081, v153
	v_mul_f32_e32 v154, 0x3b808081, v154
	v_mul_f32_e32 v157, v152, v155
	v_fmac_f32_e32 v157, v153, v156
	v_fma_f32 v83, v154, v83, v157
	v_cvt_f32_ubyte2_e32 v152, v199
	v_cvt_f32_ubyte2_e32 v153, v201
	v_cvt_f32_ubyte2_e32 v154, v203
	v_lshlrev_b32_e32 v155, 16, v213
	v_lshlrev_b32_e32 v156, 16, v217
	v_mul_f32_e32 v152, 0x3b808081, v152
	v_mul_f32_e32 v153, 0x3b808081, v153
	v_mul_f32_e32 v154, 0x3b808081, v154
	v_mul_f32_e32 v157, v152, v155
	v_fmac_f32_e32 v157, v153, v156
	v_fma_f32 v84, v154, v84, v157
	v_cvt_f32_ubyte3_e32 v152, v199
	v_cvt_f32_ubyte3_e32 v153, v201
	v_cvt_f32_ubyte3_e32 v154, v203
	v_and_b32_e32 v155, 0xffff0000, v213
	v_and_b32_e32 v156, 0xffff0000, v217
	v_mul_f32_e32 v152, 0x3b808081, v152
	v_mul_f32_e32 v153, 0x3b808081, v153
	v_mul_f32_e32 v154, 0x3b808081, v154
	v_mul_f32_e32 v157, v152, v155
	v_fmac_f32_e32 v157, v153, v156
	v_fma_f32 v85, v154, v85, v157
	v_cvt_pk_bf16_f32 v86, v86, v87
	v_cvt_pk_bf16_f32 v87, v88, v89
	v_cvt_pk_bf16_f32 v88, v82, v83
	v_cvt_pk_bf16_f32 v89, v84, v85
	s_waitcnt lgkmcnt(0)
	v_cvt_f32_ubyte0_e32 v152, v204
	v_cvt_f32_ubyte0_e32 v153, v206
	v_cvt_f32_ubyte0_e32 v154, v208
	v_lshlrev_b32_e32 v155, 16, v218
	v_lshlrev_b32_e32 v156, 16, v222
	v_mul_f32_e32 v152, 0x3b808081, v152
	v_mul_f32_e32 v153, 0x3b808081, v153
	v_mul_f32_e32 v154, 0x3b808081, v154
	v_mul_f32_e32 v157, v152, v155
	v_fmac_f32_e32 v157, v153, v156
	v_fma_f32 v70, v154, v70, v157
	v_cvt_f32_ubyte1_e32 v152, v204
	v_cvt_f32_ubyte1_e32 v153, v206
	v_cvt_f32_ubyte1_e32 v154, v208
	v_and_b32_e32 v155, 0xffff0000, v218
	v_and_b32_e32 v156, 0xffff0000, v222
	v_mul_f32_e32 v152, 0x3b808081, v152
	v_mul_f32_e32 v153, 0x3b808081, v153
	v_mul_f32_e32 v154, 0x3b808081, v154
	v_mul_f32_e32 v157, v152, v155
	v_fmac_f32_e32 v157, v153, v156
	v_fma_f32 v71, v154, v71, v157
	v_cvt_f32_ubyte2_e32 v152, v204
	v_cvt_f32_ubyte2_e32 v153, v206
	v_cvt_f32_ubyte2_e32 v154, v208
	v_lshlrev_b32_e32 v155, 16, v219
	v_lshlrev_b32_e32 v156, 16, v223
	v_mul_f32_e32 v152, 0x3b808081, v152
	v_mul_f32_e32 v153, 0x3b808081, v153
	v_mul_f32_e32 v154, 0x3b808081, v154
	v_mul_f32_e32 v157, v152, v155
	v_fmac_f32_e32 v157, v153, v156
	v_fma_f32 v72, v154, v72, v157
	v_cvt_f32_ubyte3_e32 v152, v204
	v_cvt_f32_ubyte3_e32 v153, v206
	v_cvt_f32_ubyte3_e32 v154, v208
	v_and_b32_e32 v155, 0xffff0000, v219
	v_and_b32_e32 v156, 0xffff0000, v223
	v_mul_f32_e32 v152, 0x3b808081, v152
	v_mul_f32_e32 v153, 0x3b808081, v153
	v_mul_f32_e32 v154, 0x3b808081, v154
	v_mul_f32_e32 v157, v152, v155
	v_fmac_f32_e32 v157, v153, v156
	v_fma_f32 v73, v154, v73, v157
	v_cvt_f32_ubyte0_e32 v152, v205
	v_cvt_f32_ubyte0_e32 v153, v207
	v_cvt_f32_ubyte0_e32 v154, v209
	v_lshlrev_b32_e32 v155, 16, v220
	v_lshlrev_b32_e32 v156, 16, v224
	v_mul_f32_e32 v152, 0x3b808081, v152
	v_mul_f32_e32 v153, 0x3b808081, v153
	v_mul_f32_e32 v154, 0x3b808081, v154
	v_mul_f32_e32 v157, v152, v155
	v_fmac_f32_e32 v157, v153, v156
	v_fma_f32 v66, v154, v66, v157
	v_cvt_f32_ubyte1_e32 v152, v205
	v_cvt_f32_ubyte1_e32 v153, v207
	v_cvt_f32_ubyte1_e32 v154, v209
	v_and_b32_e32 v155, 0xffff0000, v220
	v_and_b32_e32 v156, 0xffff0000, v224
	v_mul_f32_e32 v152, 0x3b808081, v152
	v_mul_f32_e32 v153, 0x3b808081, v153
	v_mul_f32_e32 v154, 0x3b808081, v154
	v_mul_f32_e32 v157, v152, v155
	v_fmac_f32_e32 v157, v153, v156
	v_fma_f32 v67, v154, v67, v157
	v_cvt_f32_ubyte2_e32 v152, v205
	v_cvt_f32_ubyte2_e32 v153, v207
	v_cvt_f32_ubyte2_e32 v154, v209
; __device__ __forceinline__ void unpack8(const u32x4 w, float* f) { f[0] = bflo(w.x); f[1] = bfhi(w.x); f[2] = bflo(w.y); f[3] = bfhi(w.y); f[4] = bflo(w.z); f[5] = bfhi(w.z); f[6] = bflo(w.w); f[7] = bfhi(w.w); }
; __device__ __forceinline__ u32x4 pack8(const float* f) { u32x4 w; w.x = cvt_pk(f[0], f[1]); w.y = cvt_pk(f[2], f[3]); w.z = cvt_pk(f[4], f[5]); w.w = cvt_pk(f[6], f[7]); return w; }
;     __device__ __forceinline__ void operator()(const f32x4 (&acc)[2][2][4][2], const UnitD& u, int wr, int wc, int fr, int fq) const {
;     ...
;                     for (int bj = 0; bj < 2; ++bj) { g0[bj] = *(const u32x2*)(gp + bj * HALF); g1[bj] = *(const u32x2*)(gp + 2048 + bj * HALF); g2[bj] = *(const u32x2*)(gp + 4096 + bj * HALF);
;                         a[bj] = *(const u32x4*)(PA + po + bj * HALF); b[bj] = *(const u32x4*)(PB + po + bj * HALF); }
; #pragma unroll
;                     for (int bj = 0; bj < 2; ++bj) { float f0[8], f1[8], f2[8], fa[8], fb[8], o[8];
;                         unpack_u8(g0[bj], f0); unpack_u8(g1[bj], f1); unpack_u8(g2[bj], f2); unpack8(a[bj], fa); unpack8(b[bj], fb);
;                         const f32x4 v0 = acc[ai][bj][m][0], v1 = acc[ai][bj][m][1];
; #pragma unroll
;                         for (int j = 0; j < 4; ++j) { o[j] = f0[j] * fa[j] + f1[j] * fb[j] + f2[j] * v0[j]; o[4 + j] = f0[4 + j] * fa[4 + j] + f1[4 + j] * fb[4 + j] + f2[4 + j] * v1[j]; }
;                         *(u32x4*)(H + po + bj * HALF) = pack8(o); } }
	v_lshlrev_b32_e32 v155, 16, v221
	v_lshlrev_b32_e32 v156, 16, v225
	v_mul_f32_e32 v152, 0x3b808081, v152
	v_mul_f32_e32 v153, 0x3b808081, v153
	v_mul_f32_e32 v154, 0x3b808081, v154
	v_mul_f32_e32 v157, v152, v155
	v_fmac_f32_e32 v157, v153, v156
	v_fma_f32 v68, v154, v68, v157
	v_cvt_f32_ubyte3_e32 v152, v205
	v_cvt_f32_ubyte3_e32 v153, v207
	v_cvt_f32_ubyte3_e32 v154, v209
	v_and_b32_e32 v155, 0xffff0000, v221
	v_and_b32_e32 v156, 0xffff0000, v225
	v_mul_f32_e32 v152, 0x3b808081, v152
	v_mul_f32_e32 v153, 0x3b808081, v153
	v_mul_f32_e32 v154, 0x3b808081, v154
	v_mul_f32_e32 v157, v152, v155
	v_fmac_f32_e32 v157, v153, v156
	v_fma_f32 v69, v154, v69, v157
	v_cvt_pk_bf16_f32 v70, v70, v71
	v_cvt_pk_bf16_f32 v71, v72, v73
	v_cvt_pk_bf16_f32 v72, v66, v67
	v_cvt_pk_bf16_f32 v73, v68, v69
	v_add_u32_e32 v147, 0x12000, v145
	v_add_u32_e32 v148, 0x492000, v146
	global_load_dwordx2 v[198:199], v148, s[20:21] offset:-2048
	global_load_dwordx2 v[200:201], v148, s[20:21]
	global_load_dwordx2 v[202:203], v148, s[20:21] offset:2048
	global_load_dwordx2 v[204:205], v148, s[20:21] offset:-1920
	global_load_dwordx2 v[206:207], v148, s[20:21] offset:128
	global_load_dwordx2 v[208:209], v148, s[20:21] offset:2176
	global_load_dwordx4 v[210:213], v147, s[58:59]
	global_load_dwordx4 v[214:217], v147, s[60:61]
	global_load_dwordx4 v[218:221], v147, s[58:59] offset:256
	global_load_dwordx4 v[222:225], v147, s[60:61] offset:256
	ds_write_b128 v251, v[62:65]
	ds_read_b128 v[62:65], v252
	ds_write_b128 v251, v[58:61]
	ds_read_b128 v[58:61], v252
	ds_write_b128 v251, v[46:49]
	ds_read_b128 v[46:49], v252
	ds_write_b128 v251, v[42:45]
	ds_read_b128 v[42:45], v252
	v_add_u32_e32 v149, 0x80000, v151
	s_waitcnt vmcnt(10)
	s_waitcnt lgkmcnt(4)
	v_cvt_f32_ubyte0_e32 v152, v130
	v_cvt_f32_ubyte0_e32 v153, v132
	v_cvt_f32_ubyte0_e32 v154, v134
	v_lshlrev_b32_e32 v155, 16, v164
	v_lshlrev_b32_e32 v156, 16, v168
	v_mul_f32_e32 v152, 0x3b808081, v152
	v_mul_f32_e32 v153, 0x3b808081, v153
	v_mul_f32_e32 v154, 0x3b808081, v154
	v_mul_f32_e32 v157, v152, v155
	v_fmac_f32_e32 v157, v153, v156
	v_fma_f32 v62, v154, v62, v157
	v_cvt_f32_ubyte1_e32 v152, v130
	v_cvt_f32_ubyte1_e32 v153, v132
	v_cvt_f32_ubyte1_e32 v154, v134
	v_and_b32_e32 v155, 0xffff0000, v164
	v_and_b32_e32 v156, 0xffff0000, v168
	v_mul_f32_e32 v152, 0x3b808081, v152
	v_mul_f32_e32 v153, 0x3b808081, v153
	v_mul_f32_e32 v154, 0x3b808081, v154
	v_mul_f32_e32 v157, v152, v155
	v_fmac_f32_e32 v157, v153, v156
	v_fma_f32 v63, v154, v63, v157
	v_cvt_f32_ubyte2_e32 v152, v130
	v_cvt_f32_ubyte2_e32 v153, v132
	v_cvt_f32_ubyte2_e32 v154, v134
	v_lshlrev_b32_e32 v155, 16, v165
	v_lshlrev_b32_e32 v156, 16, v169
	v_mul_f32_e32 v152, 0x3b808081, v152
	v_mul_f32_e32 v153, 0x3b808081, v153
	v_mul_f32_e32 v154, 0x3b808081, v154
	v_mul_f32_e32 v157, v152, v155
	v_fmac_f32_e32 v157, v153, v156
	v_fma_f32 v64, v154, v64, v157
	v_cvt_f32_ubyte3_e32 v152, v130
	v_cvt_f32_ubyte3_e32 v153, v132
	v_cvt_f32_ubyte3_e32 v154, v134
	v_and_b32_e32 v155, 0xffff0000, v165
	v_and_b32_e32 v156, 0xffff0000, v169
	v_mul_f32_e32 v152, 0x3b808081, v152
	v_mul_f32_e32 v153, 0x3b808081, v153
	v_mul_f32_e32 v154, 0x3b808081, v154
	v_mul_f32_e32 v157, v152, v155
	v_fmac_f32_e32 v157, v153, v156
	v_fma_f32 v65, v154, v65, v157
	v_cvt_f32_ubyte0_e32 v152, v131
	v_cvt_f32_ubyte0_e32 v153, v133
	v_cvt_f32_ubyte0_e32 v154, v135
	v_lshlrev_b32_e32 v155, 16, v166
	v_lshlrev_b32_e32 v156, 16, v170
	v_mul_f32_e32 v152, 0x3b808081, v152
	v_mul_f32_e32 v153, 0x3b808081, v153
	v_mul_f32_e32 v154, 0x3b808081, v154
	v_mul_f32_e32 v157, v152, v155
	v_fmac_f32_e32 v157, v153, v156
	v_fma_f32 v58, v154, v58, v157
	v_cvt_f32_ubyte1_e32 v152, v131
	v_cvt_f32_ubyte1_e32 v153, v133
	v_cvt_f32_ubyte1_e32 v154, v135
	v_and_b32_e32 v155, 0xffff0000, v166
	v_and_b32_e32 v156, 0xffff0000, v170
	v_mul_f32_e32 v152, 0x3b808081, v152
	v_mul_f32_e32 v153, 0x3b808081, v153
	v_mul_f32_e32 v154, 0x3b808081, v154
	v_mul_f32_e32 v157, v152, v155
	v_fmac_f32_e32 v157, v153, v156
	v_fma_f32 v59, v154, v59, v157
	v_cvt_f32_ubyte2_e32 v152, v131
	v_cvt_f32_ubyte2_e32 v153, v133
	v_cvt_f32_ubyte2_e32 v154, v135
	v_lshlrev_b32_e32 v155, 16, v167
	v_lshlrev_b32_e32 v156, 16, v171
	v_mul_f32_e32 v152, 0x3b808081, v152
	v_mul_f32_e32 v153, 0x3b808081, v153
	v_mul_f32_e32 v154, 0x3b808081, v154
	v_mul_f32_e32 v157, v152, v155
	v_fmac_f32_e32 v157, v153, v156
	v_fma_f32 v60, v154, v60, v157
	v_cvt_f32_ubyte3_e32 v152, v131
	v_cvt_f32_ubyte3_e32 v153, v133
	v_cvt_f32_ubyte3_e32 v154, v135
	v_and_b32_e32 v155, 0xffff0000, v167
	v_and_b32_e32 v156, 0xffff0000, v171
	v_mul_f32_e32 v152, 0x3b808081, v152
	v_mul_f32_e32 v153, 0x3b808081, v153
	v_mul_f32_e32 v154, 0x3b808081, v154
	v_mul_f32_e32 v157, v152, v155
	v_fmac_f32_e32 v157, v153, v156
	v_fma_f32 v61, v154, v61, v157
	v_cvt_pk_bf16_f32 v62, v62, v63
	v_cvt_pk_bf16_f32 v63, v64, v65
	v_cvt_pk_bf16_f32 v64, v58, v59
	v_cvt_pk_bf16_f32 v65, v60, v61
	s_waitcnt lgkmcnt(0)
; __device__ __forceinline__ void unpack8(const u32x4 w, float* f) { f[0] = bflo(w.x); f[1] = bfhi(w.x); f[2] = bflo(w.y); f[3] = bfhi(w.y); f[4] = bflo(w.z); f[5] = bfhi(w.z); f[6] = bflo(w.w); f[7] = bfhi(w.w); }
; __device__ __forceinline__ u32x4 pack8(const float* f) { u32x4 w; w.x = cvt_pk(f[0], f[1]); w.y = cvt_pk(f[2], f[3]); w.z = cvt_pk(f[4], f[5]); w.w = cvt_pk(f[6], f[7]); return w; }
;     __device__ __forceinline__ void operator()(const f32x4 (&acc)[2][2][4][2], const UnitD& u, int wr, int wc, int fr, int fq) const {
;     ...
;                     for (int bj = 0; bj < 2; ++bj) { g0[bj] = *(const u32x2*)(gp + bj * HALF); g1[bj] = *(const u32x2*)(gp + 2048 + bj * HALF); g2[bj] = *(const u32x2*)(gp + 4096 + bj * HALF);
;                         a[bj] = *(const u32x4*)(PA + po + bj * HALF); b[bj] = *(const u32x4*)(PB + po + bj * HALF); }
; #pragma unroll
;                     for (int bj = 0; bj < 2; ++bj) { float f0[8], f1[8], f2[8], fa[8], fb[8], o[8];
;                         unpack_u8(g0[bj], f0); unpack_u8(g1[bj], f1); unpack_u8(g2[bj], f2); unpack8(a[bj], fa); unpack8(b[bj], fb);
;                         const f32x4 v0 = acc[ai][bj][m][0], v1 = acc[ai][bj][m][1];
; #pragma unroll
;                         for (int j = 0; j < 4; ++j) { o[j] = f0[j] * fa[j] + f1[j] * fb[j] + f2[j] * v0[j]; o[4 + j] = f0[4 + j] * fa[4 + j] + f1[4 + j] * fb[4 + j] + f2[4 + j] * v1[j]; }
;                         *(u32x4*)(H + po + bj * HALF) = pack8(o); } }
	v_cvt_f32_ubyte0_e32 v152, v136
	v_cvt_f32_ubyte0_e32 v153, v160
	v_cvt_f32_ubyte0_e32 v154, v162
	v_lshlrev_b32_e32 v155, 16, v172
	v_lshlrev_b32_e32 v156, 16, v176
	v_mul_f32_e32 v152, 0x3b808081, v152
	v_mul_f32_e32 v153, 0x3b808081, v153
	v_mul_f32_e32 v154, 0x3b808081, v154
	v_mul_f32_e32 v157, v152, v155
	v_fmac_f32_e32 v157, v153, v156
	v_fma_f32 v46, v154, v46, v157
	v_cvt_f32_ubyte1_e32 v152, v136
	v_cvt_f32_ubyte1_e32 v153, v160
	v_cvt_f32_ubyte1_e32 v154, v162
	v_and_b32_e32 v155, 0xffff0000, v172
	v_and_b32_e32 v156, 0xffff0000, v176
	v_mul_f32_e32 v152, 0x3b808081, v152
	v_mul_f32_e32 v153, 0x3b808081, v153
	v_mul_f32_e32 v154, 0x3b808081, v154
	v_mul_f32_e32 v157, v152, v155
	v_fmac_f32_e32 v157, v153, v156
	v_fma_f32 v47, v154, v47, v157
	v_cvt_f32_ubyte2_e32 v152, v136
	v_cvt_f32_ubyte2_e32 v153, v160
	v_cvt_f32_ubyte2_e32 v154, v162
	v_lshlrev_b32_e32 v155, 16, v173
	v_lshlrev_b32_e32 v156, 16, v177
	v_mul_f32_e32 v152, 0x3b808081, v152
	v_mul_f32_e32 v153, 0x3b808081, v153
	v_mul_f32_e32 v154, 0x3b808081, v154
	v_mul_f32_e32 v157, v152, v155
	v_fmac_f32_e32 v157, v153, v156
	v_fma_f32 v48, v154, v48, v157
	v_cvt_f32_ubyte3_e32 v152, v136
	v_cvt_f32_ubyte3_e32 v153, v160
	v_cvt_f32_ubyte3_e32 v154, v162
	v_and_b32_e32 v155, 0xffff0000, v173
	v_and_b32_e32 v156, 0xffff0000, v177
	v_mul_f32_e32 v152, 0x3b808081, v152
	v_mul_f32_e32 v153, 0x3b808081, v153
	v_mul_f32_e32 v154, 0x3b808081, v154
	v_mul_f32_e32 v157, v152, v155
	v_fmac_f32_e32 v157, v153, v156
	v_fma_f32 v49, v154, v49, v157
	v_cvt_f32_ubyte0_e32 v152, v137
	v_cvt_f32_ubyte0_e32 v153, v161
	v_cvt_f32_ubyte0_e32 v154, v163
	v_lshlrev_b32_e32 v155, 16, v174
	v_lshlrev_b32_e32 v156, 16, v178
	v_mul_f32_e32 v152, 0x3b808081, v152
	v_mul_f32_e32 v153, 0x3b808081, v153
	v_mul_f32_e32 v154, 0x3b808081, v154
	v_mul_f32_e32 v157, v152, v155
	v_fmac_f32_e32 v157, v153, v156
	v_fma_f32 v42, v154, v42, v157
	v_cvt_f32_ubyte1_e32 v152, v137
	v_cvt_f32_ubyte1_e32 v153, v161
	v_cvt_f32_ubyte1_e32 v154, v163
	v_and_b32_e32 v155, 0xffff0000, v174
	v_and_b32_e32 v156, 0xffff0000, v178
	v_mul_f32_e32 v152, 0x3b808081, v152
	v_mul_f32_e32 v153, 0x3b808081, v153
	v_mul_f32_e32 v154, 0x3b808081, v154
	v_mul_f32_e32 v157, v152, v155
	v_fmac_f32_e32 v157, v153, v156
	v_fma_f32 v43, v154, v43, v157
	v_cvt_f32_ubyte2_e32 v152, v137
	v_cvt_f32_ubyte2_e32 v153, v161
	v_cvt_f32_ubyte2_e32 v154, v163
	v_lshlrev_b32_e32 v155, 16, v175
	v_lshlrev_b32_e32 v156, 16, v179
	v_mul_f32_e32 v152, 0x3b808081, v152
	v_mul_f32_e32 v153, 0x3b808081, v153
	v_mul_f32_e32 v154, 0x3b808081, v154
	v_mul_f32_e32 v157, v152, v155
	v_fmac_f32_e32 v157, v153, v156
	v_fma_f32 v44, v154, v44, v157
	v_cvt_f32_ubyte3_e32 v152, v137
	v_cvt_f32_ubyte3_e32 v153, v161
	v_cvt_f32_ubyte3_e32 v154, v163
	v_and_b32_e32 v155, 0xffff0000, v175
	v_and_b32_e32 v156, 0xffff0000, v179
	v_mul_f32_e32 v152, 0x3b808081, v152
	v_mul_f32_e32 v153, 0x3b808081, v153
	v_mul_f32_e32 v154, 0x3b808081, v154
	v_mul_f32_e32 v157, v152, v155
	v_fmac_f32_e32 v157, v153, v156
	v_fma_f32 v45, v154, v45, v157
	v_cvt_pk_bf16_f32 v46, v46, v47
	v_cvt_pk_bf16_f32 v47, v48, v49
	v_cvt_pk_bf16_f32 v48, v42, v43
	v_cvt_pk_bf16_f32 v49, v44, v45
	v_add_u32_e32 v147, 0x14000, v145
	v_add_u32_e32 v148, 0x514000, v146
	global_load_dwordx2 v[130:131], v148, s[20:21] offset:-2048
	global_load_dwordx2 v[132:133], v148, s[20:21]
	global_load_dwordx2 v[134:135], v148, s[20:21] offset:2048
	global_load_dwordx2 v[136:137], v148, s[20:21] offset:-1920
	global_load_dwordx2 v[160:161], v148, s[20:21] offset:128
	global_load_dwordx2 v[162:163], v148, s[20:21] offset:2176
	global_load_dwordx4 v[164:167], v147, s[58:59]
	global_load_dwordx4 v[168:171], v147, s[60:61]
	global_load_dwordx4 v[172:175], v147, s[58:59] offset:256
	global_load_dwordx4 v[176:179], v147, s[60:61] offset:256
	ds_write_b128 v251, v[54:57]
	ds_read_b128 v[54:57], v252
	ds_write_b128 v251, v[50:53]
	ds_read_b128 v[50:53], v252
	ds_write_b128 v251, v[30:33]
	ds_read_b128 v[30:33], v252
	ds_write_b128 v251, v[26:29]
	ds_read_b128 v[26:29], v252
	v_add_u32_e32 v149, 0x90000, v151
	s_waitcnt vmcnt(10)
	s_waitcnt lgkmcnt(4)
	v_cvt_f32_ubyte0_e32 v152, v198
	v_cvt_f32_ubyte0_e32 v153, v200
	v_cvt_f32_ubyte0_e32 v154, v202
	v_lshlrev_b32_e32 v155, 16, v210
	v_lshlrev_b32_e32 v156, 16, v214
	v_mul_f32_e32 v152, 0x3b808081, v152
	v_mul_f32_e32 v153, 0x3b808081, v153
	v_mul_f32_e32 v154, 0x3b808081, v154
	v_mul_f32_e32 v157, v152, v155
	v_fmac_f32_e32 v157, v153, v156
	v_fma_f32 v54, v154, v54, v157
	v_cvt_f32_ubyte1_e32 v152, v198
	v_cvt_f32_ubyte1_e32 v153, v200
	v_cvt_f32_ubyte1_e32 v154, v202
	v_and_b32_e32 v155, 0xffff0000, v210
	v_and_b32_e32 v156, 0xffff0000, v214
	v_mul_f32_e32 v152, 0x3b808081, v152
	v_mul_f32_e32 v153, 0x3b808081, v153
	v_mul_f32_e32 v154, 0x3b808081, v154
	v_mul_f32_e32 v157, v152, v155
	v_fmac_f32_e32 v157, v153, v156
	v_fma_f32 v55, v154, v55, v157
	v_cvt_f32_ubyte2_e32 v152, v198
	v_cvt_f32_ubyte2_e32 v153, v200
	v_cvt_f32_ubyte2_e32 v154, v202
	v_lshlrev_b32_e32 v155, 16, v211
	v_lshlrev_b32_e32 v156, 16, v215
	v_mul_f32_e32 v152, 0x3b808081, v152
	v_mul_f32_e32 v153, 0x3b808081, v153
	v_mul_f32_e32 v154, 0x3b808081, v154
	v_mul_f32_e32 v157, v152, v155
	v_fmac_f32_e32 v157, v153, v156
	v_fma_f32 v56, v154, v56, v157
	v_cvt_f32_ubyte3_e32 v152, v198
	v_cvt_f32_ubyte3_e32 v153, v200
	v_cvt_f32_ubyte3_e32 v154, v202
	v_and_b32_e32 v155, 0xffff0000, v211
	v_and_b32_e32 v156, 0xffff0000, v215
	v_mul_f32_e32 v152, 0x3b808081, v152
	v_mul_f32_e32 v153, 0x3b808081, v153
	v_mul_f32_e32 v154, 0x3b808081, v154
	v_mul_f32_e32 v157, v152, v155
	v_fmac_f32_e32 v157, v153, v156
; __device__ __forceinline__ void unpack8(const u32x4 w, float* f) { f[0] = bflo(w.x); f[1] = bfhi(w.x); f[2] = bflo(w.y); f[3] = bfhi(w.y); f[4] = bflo(w.z); f[5] = bfhi(w.z); f[6] = bflo(w.w); f[7] = bfhi(w.w); }
; __device__ __forceinline__ u32x4 pack8(const float* f) { u32x4 w; w.x = cvt_pk(f[0], f[1]); w.y = cvt_pk(f[2], f[3]); w.z = cvt_pk(f[4], f[5]); w.w = cvt_pk(f[6], f[7]); return w; }
;     __device__ __forceinline__ void operator()(const f32x4 (&acc)[2][2][4][2], const UnitD& u, int wr, int wc, int fr, int fq) const {
;     ...
;                 for (int m = 0; m < 4; ++m) { const int row = row0 + ai * HALF + m * 16;
;                     const unsigned char* gp = (const unsigned char*)(proj + (size_t)row * NP + C_G) + col0; const size_t po = (size_t)row * 2048 + col0;
;                     u32x2 g0[2], g1[2], g2[2]; u32x4 a[2], b[2];
; #pragma unroll
;                     for (int bj = 0; bj < 2; ++bj) { g0[bj] = *(const u32x2*)(gp + bj * HALF); g1[bj] = *(const u32x2*)(gp + 2048 + bj * HALF); g2[bj] = *(const u32x2*)(gp + 4096 + bj * HALF);
;                         a[bj] = *(const u32x4*)(PA + po + bj * HALF); b[bj] = *(const u32x4*)(PB + po + bj * HALF); }
; #pragma unroll
;                     for (int bj = 0; bj < 2; ++bj) { float f0[8], f1[8], f2[8], fa[8], fb[8], o[8];
;                         unpack_u8(g0[bj], f0); unpack_u8(g1[bj], f1); unpack_u8(g2[bj], f2); unpack8(a[bj], fa); unpack8(b[bj], fb);
;                         const f32x4 v0 = acc[ai][bj][m][0], v1 = acc[ai][bj][m][1];
; #pragma unroll
;                         for (int j = 0; j < 4; ++j) { o[j] = f0[j] * fa[j] + f1[j] * fb[j] + f2[j] * v0[j]; o[4 + j] = f0[4 + j] * fa[4 + j] + f1[4 + j] * fb[4 + j] + f2[4 + j] * v1[j]; }
;                         *(u32x4*)(H + po + bj * HALF) = pack8(o); } }
	v_fma_f32 v57, v154, v57, v157
	v_cvt_f32_ubyte0_e32 v152, v199
	v_cvt_f32_ubyte0_e32 v153, v201
	v_cvt_f32_ubyte0_e32 v154, v203
	v_lshlrev_b32_e32 v155, 16, v212
	v_lshlrev_b32_e32 v156, 16, v216
	v_mul_f32_e32 v152, 0x3b808081, v152
	v_mul_f32_e32 v153, 0x3b808081, v153
	v_mul_f32_e32 v154, 0x3b808081, v154
	v_mul_f32_e32 v157, v152, v155
	v_fmac_f32_e32 v157, v153, v156
	v_fma_f32 v50, v154, v50, v157
	v_cvt_f32_ubyte1_e32 v152, v199
	v_cvt_f32_ubyte1_e32 v153, v201
	v_cvt_f32_ubyte1_e32 v154, v203
	v_and_b32_e32 v155, 0xffff0000, v212
	v_and_b32_e32 v156, 0xffff0000, v216
	v_mul_f32_e32 v152, 0x3b808081, v152
	v_mul_f32_e32 v153, 0x3b808081, v153
	v_mul_f32_e32 v154, 0x3b808081, v154
	v_mul_f32_e32 v157, v152, v155
	v_fmac_f32_e32 v157, v153, v156
	v_fma_f32 v51, v154, v51, v157
	v_cvt_f32_ubyte2_e32 v152, v199
	v_cvt_f32_ubyte2_e32 v153, v201
	v_cvt_f32_ubyte2_e32 v154, v203
	v_lshlrev_b32_e32 v155, 16, v213
	v_lshlrev_b32_e32 v156, 16, v217
	v_mul_f32_e32 v152, 0x3b808081, v152
	v_mul_f32_e32 v153, 0x3b808081, v153
	v_mul_f32_e32 v154, 0x3b808081, v154
	v_mul_f32_e32 v157, v152, v155
	v_fmac_f32_e32 v157, v153, v156
	v_fma_f32 v52, v154, v52, v157
	v_cvt_f32_ubyte3_e32 v152, v199
	v_cvt_f32_ubyte3_e32 v153, v201
	v_cvt_f32_ubyte3_e32 v154, v203
	v_and_b32_e32 v155, 0xffff0000, v213
	v_and_b32_e32 v156, 0xffff0000, v217
	v_mul_f32_e32 v152, 0x3b808081, v152
	v_mul_f32_e32 v153, 0x3b808081, v153
	v_mul_f32_e32 v154, 0x3b808081, v154
	v_mul_f32_e32 v157, v152, v155
	v_fmac_f32_e32 v157, v153, v156
	v_fma_f32 v53, v154, v53, v157
	v_cvt_pk_bf16_f32 v54, v54, v55
	v_cvt_pk_bf16_f32 v55, v56, v57
	v_cvt_pk_bf16_f32 v56, v50, v51
	v_cvt_pk_bf16_f32 v57, v52, v53
	s_waitcnt lgkmcnt(0)
	v_cvt_f32_ubyte0_e32 v152, v204
	v_cvt_f32_ubyte0_e32 v153, v206
	v_cvt_f32_ubyte0_e32 v154, v208
	v_lshlrev_b32_e32 v155, 16, v218
	v_lshlrev_b32_e32 v156, 16, v222
	v_mul_f32_e32 v152, 0x3b808081, v152
	v_mul_f32_e32 v153, 0x3b808081, v153
	v_mul_f32_e32 v154, 0x3b808081, v154
	v_mul_f32_e32 v157, v152, v155
	v_fmac_f32_e32 v157, v153, v156
	v_fma_f32 v30, v154, v30, v157
	v_cvt_f32_ubyte1_e32 v152, v204
	v_cvt_f32_ubyte1_e32 v153, v206
	v_cvt_f32_ubyte1_e32 v154, v208
	v_and_b32_e32 v155, 0xffff0000, v218
	v_and_b32_e32 v156, 0xffff0000, v222
	v_mul_f32_e32 v152, 0x3b808081, v152
	v_mul_f32_e32 v153, 0x3b808081, v153
	v_mul_f32_e32 v154, 0x3b808081, v154
	v_mul_f32_e32 v157, v152, v155
	v_fmac_f32_e32 v157, v153, v156
	v_fma_f32 v31, v154, v31, v157
	v_cvt_f32_ubyte2_e32 v152, v204
	v_cvt_f32_ubyte2_e32 v153, v206
	v_cvt_f32_ubyte2_e32 v154, v208
	v_lshlrev_b32_e32 v155, 16, v219
	v_lshlrev_b32_e32 v156, 16, v223
	v_mul_f32_e32 v152, 0x3b808081, v152
	v_mul_f32_e32 v153, 0x3b808081, v153
	v_mul_f32_e32 v154, 0x3b808081, v154
	v_mul_f32_e32 v157, v152, v155
	v_fmac_f32_e32 v157, v153, v156
	v_fma_f32 v32, v154, v32, v157
	v_cvt_f32_ubyte3_e32 v152, v204
	v_cvt_f32_ubyte3_e32 v153, v206
	v_cvt_f32_ubyte3_e32 v154, v208
	v_and_b32_e32 v155, 0xffff0000, v219
	v_and_b32_e32 v156, 0xffff0000, v223
	v_mul_f32_e32 v152, 0x3b808081, v152
	v_mul_f32_e32 v153, 0x3b808081, v153
	v_mul_f32_e32 v154, 0x3b808081, v154
	v_mul_f32_e32 v157, v152, v155
	v_fmac_f32_e32 v157, v153, v156
	v_fma_f32 v33, v154, v33, v157
	v_cvt_f32_ubyte0_e32 v152, v205
	v_cvt_f32_ubyte0_e32 v153, v207
	v_cvt_f32_ubyte0_e32 v154, v209
	v_lshlrev_b32_e32 v155, 16, v220
	v_lshlrev_b32_e32 v156, 16, v224
	v_mul_f32_e32 v152, 0x3b808081, v152
	v_mul_f32_e32 v153, 0x3b808081, v153
	v_mul_f32_e32 v154, 0x3b808081, v154
	v_mul_f32_e32 v157, v152, v155
	v_fmac_f32_e32 v157, v153, v156
	v_fma_f32 v26, v154, v26, v157
	v_cvt_f32_ubyte1_e32 v152, v205
	v_cvt_f32_ubyte1_e32 v153, v207
	v_cvt_f32_ubyte1_e32 v154, v209
	v_and_b32_e32 v155, 0xffff0000, v220
	v_and_b32_e32 v156, 0xffff0000, v224
	v_mul_f32_e32 v152, 0x3b808081, v152
	v_mul_f32_e32 v153, 0x3b808081, v153
	v_mul_f32_e32 v154, 0x3b808081, v154
	v_mul_f32_e32 v157, v152, v155
	v_fmac_f32_e32 v157, v153, v156
	v_fma_f32 v27, v154, v27, v157
	v_cvt_f32_ubyte2_e32 v152, v205
	v_cvt_f32_ubyte2_e32 v153, v207
	v_cvt_f32_ubyte2_e32 v154, v209
	v_lshlrev_b32_e32 v155, 16, v221
	v_lshlrev_b32_e32 v156, 16, v225
	v_mul_f32_e32 v152, 0x3b808081, v152
	v_mul_f32_e32 v153, 0x3b808081, v153
	v_mul_f32_e32 v154, 0x3b808081, v154
	v_mul_f32_e32 v157, v152, v155
	v_fmac_f32_e32 v157, v153, v156
	v_fma_f32 v28, v154, v28, v157
	v_cvt_f32_ubyte3_e32 v152, v205
	v_cvt_f32_ubyte3_e32 v153, v207
	v_cvt_f32_ubyte3_e32 v154, v209
	v_and_b32_e32 v155, 0xffff0000, v221
	v_and_b32_e32 v156, 0xffff0000, v225
	v_mul_f32_e32 v152, 0x3b808081, v152
	v_mul_f32_e32 v153, 0x3b808081, v153
	v_mul_f32_e32 v154, 0x3b808081, v154
	v_mul_f32_e32 v157, v152, v155
	v_fmac_f32_e32 v157, v153, v156
	v_fma_f32 v29, v154, v29, v157
	v_cvt_pk_bf16_f32 v30, v30, v31
	v_cvt_pk_bf16_f32 v31, v32, v33
	v_cvt_pk_bf16_f32 v32, v26, v27
	v_cvt_pk_bf16_f32 v33, v28, v29
	v_add_u32_e32 v147, 0x16000, v145
	v_add_u32_e32 v148, 0x596000, v146
	global_load_dwordx2 v[198:199], v148, s[20:21] offset:-2048
	global_load_dwordx2 v[200:201], v148, s[20:21]
	global_load_dwordx2 v[202:203], v148, s[20:21] offset:2048
	global_load_dwordx2 v[204:205], v148, s[20:21] offset:-1920
	global_load_dwordx2 v[206:207], v148, s[20:21] offset:128
	global_load_dwordx2 v[208:209], v148, s[20:21] offset:2176
	global_load_dwordx4 v[210:213], v147, s[58:59]
	global_load_dwordx4 v[214:217], v147, s[60:61]
	global_load_dwordx4 v[218:221], v147, s[58:59] offset:256
	global_load_dwordx4 v[222:225], v147, s[60:61] offset:256
	ds_write_b128 v251, v[38:41]
	ds_read_b128 v[38:41], v252
	ds_write_b128 v251, v[34:37]
	ds_read_b128 v[34:37], v252
	ds_write_b128 v251, v[14:17]
	ds_read_b128 v[14:17], v252
	ds_write_b128 v251, v[10:13]
	ds_read_b128 v[10:13], v252
	v_add_u32_e32 v149, 0xa0000, v151
	s_waitcnt vmcnt(10)
; __device__ __forceinline__ void unpack8(const u32x4 w, float* f) { f[0] = bflo(w.x); f[1] = bfhi(w.x); f[2] = bflo(w.y); f[3] = bfhi(w.y); f[4] = bflo(w.z); f[5] = bfhi(w.z); f[6] = bflo(w.w); f[7] = bfhi(w.w); }
; __device__ __forceinline__ u32x4 pack8(const float* f) { u32x4 w; w.x = cvt_pk(f[0], f[1]); w.y = cvt_pk(f[2], f[3]); w.z = cvt_pk(f[4], f[5]); w.w = cvt_pk(f[6], f[7]); return w; }
;     __device__ __forceinline__ void operator()(const f32x4 (&acc)[2][2][4][2], const UnitD& u, int wr, int wc, int fr, int fq) const {
;     ...
;                 for (int m = 0; m < 4; ++m) { const int row = row0 + ai * HALF + m * 16;
;                     const unsigned char* gp = (const unsigned char*)(proj + (size_t)row * NP + C_G) + col0; const size_t po = (size_t)row * 2048 + col0;
;                     u32x2 g0[2], g1[2], g2[2]; u32x4 a[2], b[2];
; #pragma unroll
;                     for (int bj = 0; bj < 2; ++bj) { g0[bj] = *(const u32x2*)(gp + bj * HALF); g1[bj] = *(const u32x2*)(gp + 2048 + bj * HALF); g2[bj] = *(const u32x2*)(gp + 4096 + bj * HALF);
;                         a[bj] = *(const u32x4*)(PA + po + bj * HALF); b[bj] = *(const u32x4*)(PB + po + bj * HALF); }
; #pragma unroll
;                     for (int bj = 0; bj < 2; ++bj) { float f0[8], f1[8], f2[8], fa[8], fb[8], o[8];
;                         unpack_u8(g0[bj], f0); unpack_u8(g1[bj], f1); unpack_u8(g2[bj], f2); unpack8(a[bj], fa); unpack8(b[bj], fb);
;                         const f32x4 v0 = acc[ai][bj][m][0], v1 = acc[ai][bj][m][1];
; #pragma unroll
;                         for (int j = 0; j < 4; ++j) { o[j] = f0[j] * fa[j] + f1[j] * fb[j] + f2[j] * v0[j]; o[4 + j] = f0[4 + j] * fa[4 + j] + f1[4 + j] * fb[4 + j] + f2[4 + j] * v1[j]; }
;                         *(u32x4*)(H + po + bj * HALF) = pack8(o); } }
	s_waitcnt lgkmcnt(4)
	v_cvt_f32_ubyte0_e32 v152, v130
	v_cvt_f32_ubyte0_e32 v153, v132
	v_cvt_f32_ubyte0_e32 v154, v134
	v_lshlrev_b32_e32 v155, 16, v164
	v_lshlrev_b32_e32 v156, 16, v168
	v_mul_f32_e32 v152, 0x3b808081, v152
	v_mul_f32_e32 v153, 0x3b808081, v153
	v_mul_f32_e32 v154, 0x3b808081, v154
	v_mul_f32_e32 v157, v152, v155
	v_fmac_f32_e32 v157, v153, v156
	v_fma_f32 v38, v154, v38, v157
	v_cvt_f32_ubyte1_e32 v152, v130
	v_cvt_f32_ubyte1_e32 v153, v132
	v_cvt_f32_ubyte1_e32 v154, v134
	v_and_b32_e32 v155, 0xffff0000, v164
	v_and_b32_e32 v156, 0xffff0000, v168
	v_mul_f32_e32 v152, 0x3b808081, v152
	v_mul_f32_e32 v153, 0x3b808081, v153
	v_mul_f32_e32 v154, 0x3b808081, v154
	v_mul_f32_e32 v157, v152, v155
	v_fmac_f32_e32 v157, v153, v156
	v_fma_f32 v39, v154, v39, v157
	v_cvt_f32_ubyte2_e32 v152, v130
	v_cvt_f32_ubyte2_e32 v153, v132
	v_cvt_f32_ubyte2_e32 v154, v134
	v_lshlrev_b32_e32 v155, 16, v165
	v_lshlrev_b32_e32 v156, 16, v169
	v_mul_f32_e32 v152, 0x3b808081, v152
	v_mul_f32_e32 v153, 0x3b808081, v153
	v_mul_f32_e32 v154, 0x3b808081, v154
	v_mul_f32_e32 v157, v152, v155
	v_fmac_f32_e32 v157, v153, v156
	v_fma_f32 v40, v154, v40, v157
	v_cvt_f32_ubyte3_e32 v152, v130
	v_cvt_f32_ubyte3_e32 v153, v132
	v_cvt_f32_ubyte3_e32 v154, v134
	v_and_b32_e32 v155, 0xffff0000, v165
	v_and_b32_e32 v156, 0xffff0000, v169
	v_mul_f32_e32 v152, 0x3b808081, v152
	v_mul_f32_e32 v153, 0x3b808081, v153
	v_mul_f32_e32 v154, 0x3b808081, v154
	v_mul_f32_e32 v157, v152, v155
	v_fmac_f32_e32 v157, v153, v156
	v_fma_f32 v41, v154, v41, v157
	v_cvt_f32_ubyte0_e32 v152, v131
	v_cvt_f32_ubyte0_e32 v153, v133
	v_cvt_f32_ubyte0_e32 v154, v135
	v_lshlrev_b32_e32 v155, 16, v166
	v_lshlrev_b32_e32 v156, 16, v170
	v_mul_f32_e32 v152, 0x3b808081, v152
	v_mul_f32_e32 v153, 0x3b808081, v153
	v_mul_f32_e32 v154, 0x3b808081, v154
	v_mul_f32_e32 v157, v152, v155
	v_fmac_f32_e32 v157, v153, v156
	v_fma_f32 v34, v154, v34, v157
	v_cvt_f32_ubyte1_e32 v152, v131
	v_cvt_f32_ubyte1_e32 v153, v133
	v_cvt_f32_ubyte1_e32 v154, v135
	v_and_b32_e32 v155, 0xffff0000, v166
	v_and_b32_e32 v156, 0xffff0000, v170
	v_mul_f32_e32 v152, 0x3b808081, v152
	v_mul_f32_e32 v153, 0x3b808081, v153
	v_mul_f32_e32 v154, 0x3b808081, v154
	v_mul_f32_e32 v157, v152, v155
	v_fmac_f32_e32 v157, v153, v156
	v_fma_f32 v35, v154, v35, v157
	v_cvt_f32_ubyte2_e32 v152, v131
	v_cvt_f32_ubyte2_e32 v153, v133
	v_cvt_f32_ubyte2_e32 v154, v135
	v_lshlrev_b32_e32 v155, 16, v167
	v_lshlrev_b32_e32 v156, 16, v171
	v_mul_f32_e32 v152, 0x3b808081, v152
	v_mul_f32_e32 v153, 0x3b808081, v153
	v_mul_f32_e32 v154, 0x3b808081, v154
	v_mul_f32_e32 v157, v152, v155
	v_fmac_f32_e32 v157, v153, v156
	v_fma_f32 v36, v154, v36, v157
	v_cvt_f32_ubyte3_e32 v152, v131
	v_cvt_f32_ubyte3_e32 v153, v133
	v_cvt_f32_ubyte3_e32 v154, v135
	v_and_b32_e32 v155, 0xffff0000, v167
	v_and_b32_e32 v156, 0xffff0000, v171
	v_mul_f32_e32 v152, 0x3b808081, v152
	v_mul_f32_e32 v153, 0x3b808081, v153
	v_mul_f32_e32 v154, 0x3b808081, v154
	v_mul_f32_e32 v157, v152, v155
	v_fmac_f32_e32 v157, v153, v156
	v_fma_f32 v37, v154, v37, v157
	v_cvt_pk_bf16_f32 v38, v38, v39
	v_cvt_pk_bf16_f32 v39, v40, v41
	v_cvt_pk_bf16_f32 v40, v34, v35
	v_cvt_pk_bf16_f32 v41, v36, v37
	s_waitcnt lgkmcnt(0)
	v_cvt_f32_ubyte0_e32 v152, v136
	v_cvt_f32_ubyte0_e32 v153, v160
	v_cvt_f32_ubyte0_e32 v154, v162
	v_lshlrev_b32_e32 v155, 16, v172
	v_lshlrev_b32_e32 v156, 16, v176
	v_mul_f32_e32 v152, 0x3b808081, v152
	v_mul_f32_e32 v153, 0x3b808081, v153
	v_mul_f32_e32 v154, 0x3b808081, v154
	v_mul_f32_e32 v157, v152, v155
	v_fmac_f32_e32 v157, v153, v156
	v_fma_f32 v14, v154, v14, v157
	v_cvt_f32_ubyte1_e32 v152, v136
	v_cvt_f32_ubyte1_e32 v153, v160
	v_cvt_f32_ubyte1_e32 v154, v162
	v_and_b32_e32 v155, 0xffff0000, v172
	v_and_b32_e32 v156, 0xffff0000, v176
	v_mul_f32_e32 v152, 0x3b808081, v152
	v_mul_f32_e32 v153, 0x3b808081, v153
	v_mul_f32_e32 v154, 0x3b808081, v154
	v_mul_f32_e32 v157, v152, v155
	v_fmac_f32_e32 v157, v153, v156
	v_fma_f32 v15, v154, v15, v157
	v_cvt_f32_ubyte2_e32 v152, v136
	v_cvt_f32_ubyte2_e32 v153, v160
	v_cvt_f32_ubyte2_e32 v154, v162
	v_lshlrev_b32_e32 v155, 16, v173
	v_lshlrev_b32_e32 v156, 16, v177
	v_mul_f32_e32 v152, 0x3b808081, v152
	v_mul_f32_e32 v153, 0x3b808081, v153
	v_mul_f32_e32 v154, 0x3b808081, v154
	v_mul_f32_e32 v157, v152, v155
	v_fmac_f32_e32 v157, v153, v156
	v_fma_f32 v16, v154, v16, v157
	v_cvt_f32_ubyte3_e32 v152, v136
	v_cvt_f32_ubyte3_e32 v153, v160
	v_cvt_f32_ubyte3_e32 v154, v162
	v_and_b32_e32 v155, 0xffff0000, v173
	v_and_b32_e32 v156, 0xffff0000, v177
	v_mul_f32_e32 v152, 0x3b808081, v152
	v_mul_f32_e32 v153, 0x3b808081, v153
	v_mul_f32_e32 v154, 0x3b808081, v154
	v_mul_f32_e32 v157, v152, v155
	v_fmac_f32_e32 v157, v153, v156
	v_fma_f32 v17, v154, v17, v157
	v_cvt_f32_ubyte0_e32 v152, v137
	v_cvt_f32_ubyte0_e32 v153, v161
	v_cvt_f32_ubyte0_e32 v154, v163
	v_lshlrev_b32_e32 v155, 16, v174
	v_lshlrev_b32_e32 v156, 16, v178
	v_mul_f32_e32 v152, 0x3b808081, v152
	v_mul_f32_e32 v153, 0x3b808081, v153
	v_mul_f32_e32 v154, 0x3b808081, v154
	v_mul_f32_e32 v157, v152, v155
	v_fmac_f32_e32 v157, v153, v156
	v_fma_f32 v10, v154, v10, v157
	v_cvt_f32_ubyte1_e32 v152, v137
	v_cvt_f32_ubyte1_e32 v153, v161
	v_cvt_f32_ubyte1_e32 v154, v163
	v_and_b32_e32 v155, 0xffff0000, v174
	v_and_b32_e32 v156, 0xffff0000, v178
	v_mul_f32_e32 v152, 0x3b808081, v152
	v_mul_f32_e32 v153, 0x3b808081, v153
	v_mul_f32_e32 v154, 0x3b808081, v154
	v_mul_f32_e32 v157, v152, v155
	v_fmac_f32_e32 v157, v153, v156
	v_fma_f32 v11, v154, v11, v157
	v_cvt_f32_ubyte2_e32 v152, v137
	v_cvt_f32_ubyte2_e32 v153, v161
	v_cvt_f32_ubyte2_e32 v154, v163
	v_lshlrev_b32_e32 v155, 16, v175
	v_lshlrev_b32_e32 v156, 16, v179
	v_mul_f32_e32 v152, 0x3b808081, v152
	v_mul_f32_e32 v153, 0x3b808081, v153
	v_mul_f32_e32 v154, 0x3b808081, v154
	v_mul_f32_e32 v157, v152, v155
	v_fmac_f32_e32 v157, v153, v156
	v_fma_f32 v12, v154, v12, v157
	v_cvt_f32_ubyte3_e32 v152, v137
	v_cvt_f32_ubyte3_e32 v153, v161
	v_cvt_f32_ubyte3_e32 v154, v163
	v_and_b32_e32 v155, 0xffff0000, v175
	v_and_b32_e32 v156, 0xffff0000, v179
	v_mul_f32_e32 v152, 0x3b808081, v152
	v_mul_f32_e32 v153, 0x3b808081, v153
	v_mul_f32_e32 v154, 0x3b808081, v154
	v_mul_f32_e32 v157, v152, v155
	v_fmac_f32_e32 v157, v153, v156
	v_fma_f32 v13, v154, v13, v157
	v_cvt_pk_bf16_f32 v14, v14, v15
	v_cvt_pk_bf16_f32 v15, v16, v17
	v_cvt_pk_bf16_f32 v16, v10, v11
	v_cvt_pk_bf16_f32 v17, v12, v13
	ds_write_b128 v251, v[22:25]
	ds_read_b128 v[22:25], v252
	ds_write_b128 v251, v[18:21]
	ds_read_b128 v[18:21], v252
	ds_write_b128 v251, v[6:9]
	ds_read_b128 v[6:9], v252
	ds_write_b128 v251, v[2:5]
	ds_read_b128 v[2:5], v252
	v_add_u32_e32 v149, 0xb0000, v151
	s_waitcnt vmcnt(0)
; __device__ __forceinline__ void unpack8(const u32x4 w, float* f) { f[0] = bflo(w.x); f[1] = bfhi(w.x); f[2] = bflo(w.y); f[3] = bfhi(w.y); f[4] = bflo(w.z); f[5] = bfhi(w.z); f[6] = bflo(w.w); f[7] = bfhi(w.w); }
; __device__ __forceinline__ u32x4 pack8(const float* f) { u32x4 w; w.x = cvt_pk(f[0], f[1]); w.y = cvt_pk(f[2], f[3]); w.z = cvt_pk(f[4], f[5]); w.w = cvt_pk(f[6], f[7]); return w; }
;     __device__ __forceinline__ void operator()(const f32x4 (&acc)[2][2][4][2], const UnitD& u, int wr, int wc, int fr, int fq) const {
;     ...
;                     for (int bj = 0; bj < 2; ++bj) { float f0[8], f1[8], f2[8], fa[8], fb[8], o[8];
;                         unpack_u8(g0[bj], f0); unpack_u8(g1[bj], f1); unpack_u8(g2[bj], f2); unpack8(a[bj], fa); unpack8(b[bj], fb);
;                         const f32x4 v0 = acc[ai][bj][m][0], v1 = acc[ai][bj][m][1];
; #pragma unroll
;                         for (int j = 0; j < 4; ++j) { o[j] = f0[j] * fa[j] + f1[j] * fb[j] + f2[j] * v0[j]; o[4 + j] = f0[4 + j] * fa[4 + j] + f1[4 + j] * fb[4 + j] + f2[4 + j] * v1[j]; }
;                         *(u32x4*)(H + po + bj * HALF) = pack8(o); } }
	s_waitcnt lgkmcnt(4)
	v_cvt_f32_ubyte0_e32 v152, v198
	v_cvt_f32_ubyte0_e32 v153, v200
	v_cvt_f32_ubyte0_e32 v154, v202
	v_lshlrev_b32_e32 v155, 16, v210
	v_lshlrev_b32_e32 v156, 16, v214
	v_mul_f32_e32 v152, 0x3b808081, v152
	v_mul_f32_e32 v153, 0x3b808081, v153
	v_mul_f32_e32 v154, 0x3b808081, v154
	v_mul_f32_e32 v157, v152, v155
	v_fmac_f32_e32 v157, v153, v156
	v_fma_f32 v22, v154, v22, v157
	v_cvt_f32_ubyte1_e32 v152, v198
	v_cvt_f32_ubyte1_e32 v153, v200
	v_cvt_f32_ubyte1_e32 v154, v202
	v_and_b32_e32 v155, 0xffff0000, v210
	v_and_b32_e32 v156, 0xffff0000, v214
	v_mul_f32_e32 v152, 0x3b808081, v152
	v_mul_f32_e32 v153, 0x3b808081, v153
	v_mul_f32_e32 v154, 0x3b808081, v154
	v_mul_f32_e32 v157, v152, v155
	v_fmac_f32_e32 v157, v153, v156
	v_fma_f32 v23, v154, v23, v157
	v_cvt_f32_ubyte2_e32 v152, v198
	v_cvt_f32_ubyte2_e32 v153, v200
	v_cvt_f32_ubyte2_e32 v154, v202
	v_lshlrev_b32_e32 v155, 16, v211
	v_lshlrev_b32_e32 v156, 16, v215
	v_mul_f32_e32 v152, 0x3b808081, v152
	v_mul_f32_e32 v153, 0x3b808081, v153
	v_mul_f32_e32 v154, 0x3b808081, v154
	v_mul_f32_e32 v157, v152, v155
	v_fmac_f32_e32 v157, v153, v156
	v_fma_f32 v24, v154, v24, v157
	v_cvt_f32_ubyte3_e32 v152, v198
	v_cvt_f32_ubyte3_e32 v153, v200
	v_cvt_f32_ubyte3_e32 v154, v202
	v_and_b32_e32 v155, 0xffff0000, v211
	v_and_b32_e32 v156, 0xffff0000, v215
	v_mul_f32_e32 v152, 0x3b808081, v152
	v_mul_f32_e32 v153, 0x3b808081, v153
	v_mul_f32_e32 v154, 0x3b808081, v154
	v_mul_f32_e32 v157, v152, v155
	v_fmac_f32_e32 v157, v153, v156
	v_fma_f32 v25, v154, v25, v157
	v_cvt_f32_ubyte0_e32 v152, v199
	v_cvt_f32_ubyte0_e32 v153, v201
	v_cvt_f32_ubyte0_e32 v154, v203
	v_lshlrev_b32_e32 v155, 16, v212
	v_lshlrev_b32_e32 v156, 16, v216
	v_mul_f32_e32 v152, 0x3b808081, v152
	v_mul_f32_e32 v153, 0x3b808081, v153
	v_mul_f32_e32 v154, 0x3b808081, v154
	v_mul_f32_e32 v157, v152, v155
	v_fmac_f32_e32 v157, v153, v156
	v_fma_f32 v18, v154, v18, v157
	v_cvt_f32_ubyte1_e32 v152, v199
	v_cvt_f32_ubyte1_e32 v153, v201
	v_cvt_f32_ubyte1_e32 v154, v203
	v_and_b32_e32 v155, 0xffff0000, v212
	v_and_b32_e32 v156, 0xffff0000, v216
	v_mul_f32_e32 v152, 0x3b808081, v152
	v_mul_f32_e32 v153, 0x3b808081, v153
	v_mul_f32_e32 v154, 0x3b808081, v154
	v_mul_f32_e32 v157, v152, v155
	v_fmac_f32_e32 v157, v153, v156
	v_fma_f32 v19, v154, v19, v157
	v_cvt_f32_ubyte2_e32 v152, v199
	v_cvt_f32_ubyte2_e32 v153, v201
	v_cvt_f32_ubyte2_e32 v154, v203
	v_lshlrev_b32_e32 v155, 16, v213
	v_lshlrev_b32_e32 v156, 16, v217
	v_mul_f32_e32 v152, 0x3b808081, v152
	v_mul_f32_e32 v153, 0x3b808081, v153
	v_mul_f32_e32 v154, 0x3b808081, v154
	v_mul_f32_e32 v157, v152, v155
	v_fmac_f32_e32 v157, v153, v156
	v_fma_f32 v20, v154, v20, v157
	v_cvt_f32_ubyte3_e32 v152, v199
	v_cvt_f32_ubyte3_e32 v153, v201
	v_cvt_f32_ubyte3_e32 v154, v203
	v_and_b32_e32 v155, 0xffff0000, v213
	v_and_b32_e32 v156, 0xffff0000, v217
	v_mul_f32_e32 v152, 0x3b808081, v152
	v_mul_f32_e32 v153, 0x3b808081, v153
	v_mul_f32_e32 v154, 0x3b808081, v154
	v_mul_f32_e32 v157, v152, v155
	v_fmac_f32_e32 v157, v153, v156
	v_fma_f32 v21, v154, v21, v157
	v_cvt_pk_bf16_f32 v22, v22, v23
	v_cvt_pk_bf16_f32 v23, v24, v25
	v_cvt_pk_bf16_f32 v24, v18, v19
	v_cvt_pk_bf16_f32 v25, v20, v21
	s_waitcnt lgkmcnt(0)
; __device__ __forceinline__ void unpack8(const u32x4 w, float* f) { f[0] = bflo(w.x); f[1] = bfhi(w.x); f[2] = bflo(w.y); f[3] = bfhi(w.y); f[4] = bflo(w.z); f[5] = bfhi(w.z); f[6] = bflo(w.w); f[7] = bfhi(w.w); }
; __device__ __forceinline__ u32x4 pack8(const float* f) { u32x4 w; w.x = cvt_pk(f[0], f[1]); w.y = cvt_pk(f[2], f[3]); w.z = cvt_pk(f[4], f[5]); w.w = cvt_pk(f[6], f[7]); return w; }
;     __device__ __forceinline__ void operator()(const f32x4 (&acc)[2][2][4][2], const UnitD& u, int wr, int wc, int fr, int fq) const {
;     ...
;                     for (int bj = 0; bj < 2; ++bj) { float f0[8], f1[8], f2[8], fa[8], fb[8], o[8];
;                         unpack_u8(g0[bj], f0); unpack_u8(g1[bj], f1); unpack_u8(g2[bj], f2); unpack8(a[bj], fa); unpack8(b[bj], fb);
;                         const f32x4 v0 = acc[ai][bj][m][0], v1 = acc[ai][bj][m][1];
; #pragma unroll
;                         for (int j = 0; j < 4; ++j) { o[j] = f0[j] * fa[j] + f1[j] * fb[j] + f2[j] * v0[j]; o[4 + j] = f0[4 + j] * fa[4 + j] + f1[4 + j] * fb[4 + j] + f2[4 + j] * v1[j]; }
;                         *(u32x4*)(H + po + bj * HALF) = pack8(o); } }
	v_cvt_f32_ubyte0_e32 v152, v204
	v_cvt_f32_ubyte0_e32 v153, v206
	v_cvt_f32_ubyte0_e32 v154, v208
	v_lshlrev_b32_e32 v155, 16, v218
	v_lshlrev_b32_e32 v156, 16, v222
	v_mul_f32_e32 v152, 0x3b808081, v152
	v_mul_f32_e32 v153, 0x3b808081, v153
	v_mul_f32_e32 v154, 0x3b808081, v154
	v_mul_f32_e32 v157, v152, v155
	v_fmac_f32_e32 v157, v153, v156
	v_fma_f32 v6, v154, v6, v157
	v_cvt_f32_ubyte1_e32 v152, v204
	v_cvt_f32_ubyte1_e32 v153, v206
	v_cvt_f32_ubyte1_e32 v154, v208
	v_and_b32_e32 v155, 0xffff0000, v218
	v_and_b32_e32 v156, 0xffff0000, v222
	v_mul_f32_e32 v152, 0x3b808081, v152
	v_mul_f32_e32 v153, 0x3b808081, v153
	v_mul_f32_e32 v154, 0x3b808081, v154
	v_mul_f32_e32 v157, v152, v155
	v_fmac_f32_e32 v157, v153, v156
	v_fma_f32 v7, v154, v7, v157
	v_cvt_f32_ubyte2_e32 v152, v204
	v_cvt_f32_ubyte2_e32 v153, v206
	v_cvt_f32_ubyte2_e32 v154, v208
	v_lshlrev_b32_e32 v155, 16, v219
	v_lshlrev_b32_e32 v156, 16, v223
	v_mul_f32_e32 v152, 0x3b808081, v152
	v_mul_f32_e32 v153, 0x3b808081, v153
	v_mul_f32_e32 v154, 0x3b808081, v154
	v_mul_f32_e32 v157, v152, v155
	v_fmac_f32_e32 v157, v153, v156
	v_fma_f32 v8, v154, v8, v157
	v_cvt_f32_ubyte3_e32 v152, v204
	v_cvt_f32_ubyte3_e32 v153, v206
	v_cvt_f32_ubyte3_e32 v154, v208
	v_and_b32_e32 v155, 0xffff0000, v219
	v_and_b32_e32 v156, 0xffff0000, v223
	v_mul_f32_e32 v152, 0x3b808081, v152
	v_mul_f32_e32 v153, 0x3b808081, v153
	v_mul_f32_e32 v154, 0x3b808081, v154
	v_mul_f32_e32 v157, v152, v155
	v_fmac_f32_e32 v157, v153, v156
	v_fma_f32 v9, v154, v9, v157
	v_cvt_f32_ubyte0_e32 v152, v205
	v_cvt_f32_ubyte0_e32 v153, v207
	v_cvt_f32_ubyte0_e32 v154, v209
	v_lshlrev_b32_e32 v155, 16, v220
	v_lshlrev_b32_e32 v156, 16, v224
	v_mul_f32_e32 v152, 0x3b808081, v152
	v_mul_f32_e32 v153, 0x3b808081, v153
	v_mul_f32_e32 v154, 0x3b808081, v154
	v_mul_f32_e32 v157, v152, v155
	v_fmac_f32_e32 v157, v153, v156
	v_fma_f32 v2, v154, v2, v157
	v_cvt_f32_ubyte1_e32 v152, v205
	v_cvt_f32_ubyte1_e32 v153, v207
	v_cvt_f32_ubyte1_e32 v154, v209
	v_and_b32_e32 v155, 0xffff0000, v220
	v_and_b32_e32 v156, 0xffff0000, v224
	v_mul_f32_e32 v152, 0x3b808081, v152
	v_mul_f32_e32 v153, 0x3b808081, v153
	v_mul_f32_e32 v154, 0x3b808081, v154
	v_mul_f32_e32 v157, v152, v155
	v_fmac_f32_e32 v157, v153, v156
	v_fma_f32 v3, v154, v3, v157
	v_cvt_f32_ubyte2_e32 v152, v205
	v_cvt_f32_ubyte2_e32 v153, v207
	v_cvt_f32_ubyte2_e32 v154, v209
	v_lshlrev_b32_e32 v155, 16, v221
	v_lshlrev_b32_e32 v156, 16, v225
	v_mul_f32_e32 v152, 0x3b808081, v152
	v_mul_f32_e32 v153, 0x3b808081, v153
	v_mul_f32_e32 v154, 0x3b808081, v154
	v_mul_f32_e32 v157, v152, v155
	v_fmac_f32_e32 v157, v153, v156
	v_fma_f32 v4, v154, v4, v157
	v_cvt_f32_ubyte3_e32 v152, v205
	v_cvt_f32_ubyte3_e32 v153, v207
	v_cvt_f32_ubyte3_e32 v154, v209
	v_and_b32_e32 v155, 0xffff0000, v221
	v_and_b32_e32 v156, 0xffff0000, v225
	v_mul_f32_e32 v152, 0x3b808081, v152
	v_mul_f32_e32 v153, 0x3b808081, v153
	v_mul_f32_e32 v154, 0x3b808081, v154
	v_mul_f32_e32 v157, v152, v155
	v_fmac_f32_e32 v157, v153, v156
	v_fma_f32 v5, v154, v5, v157
	v_cvt_pk_bf16_f32 v6, v6, v7
	v_cvt_pk_bf16_f32 v7, v8, v9
	v_cvt_pk_bf16_f32 v8, v2, v3
	v_cvt_pk_bf16_f32 v9, v4, v5
	v_mov_b32_e32 v149, v151
	global_store_dwordx4 v149, v[126:129], s[62:63]
	global_store_dwordx4 v149, v[110:113], s[62:63] offset:256
	v_add_u32_e32 v149, 0x10000, v151
	global_store_dwordx4 v149, v[118:121], s[62:63]
	global_store_dwordx4 v149, v[94:97], s[62:63] offset:256
	v_add_u32_e32 v149, 0x20000, v151
	global_store_dwordx4 v149, v[102:105], s[62:63]
	global_store_dwordx4 v149, v[78:81], s[62:63] offset:256
	v_add_u32_e32 v149, 0x30000, v151
	global_store_dwordx4 v149, v[86:89], s[62:63]
	global_store_dwordx4 v149, v[70:73], s[62:63] offset:256
	v_add_u32_e32 v149, 0x80000, v151
	global_store_dwordx4 v149, v[62:65], s[62:63]
	global_store_dwordx4 v149, v[46:49], s[62:63] offset:256
	v_add_u32_e32 v149, 0x90000, v151
	global_store_dwordx4 v149, v[54:57], s[62:63]
	global_store_dwordx4 v149, v[30:33], s[62:63] offset:256
	v_add_u32_e32 v149, 0xa0000, v151
	global_store_dwordx4 v149, v[38:41], s[62:63]
	global_store_dwordx4 v149, v[14:17], s[62:63] offset:256
	v_add_u32_e32 v149, 0xb0000, v151
	global_store_dwordx4 v149, v[22:25], s[62:63]
	global_store_dwordx4 v149, v[6:9], s[62:63] offset:256
	s_branch .Lg3_done

; #define G_STA(bufoff, gbase, ld) G_STAGE(bufoff, gbase, RA0, RA1, ld)
; #define G_STB(bufoff, gbase, ld) G_STAGE(bufoff, gbase, RB0, RB1, ld)
; #define G_LDA(dst, b, h) do { _Pragma("unroll") for (int m = 0; m < 4; ++m) _Pragma("unroll") for (int k = 0; k < 2; ++k) dst[m][k] = *(const LAS bf16x8*)(lds + G_SA(b, h) + aoff + m * 2048 + k * 1024); } while (0)
; #define G_LDB(dst, b, h) do { _Pragma("unroll") for (int n = 0; n < 2; ++n) _Pragma("unroll") for (int k = 0; k < 2; ++k) dst[n][k] = *(const LAS bf16x8*)(lds + G_SB(b, h) + boff + n * 2048 + k * 1024); } while (0)
; #define G_MMA(ai, bj, At, Bt) do { __builtin_amdgcn_s_setprio(1); _Pragma("unroll") for (int m = 0; m < 4; ++m) _Pragma("unroll") for (int n = 0; n < 2; ++n) _Pragma("unroll") for (int k = 0; k < 2; ++k) \
;         acc[ai][bj][m][n] = __builtin_amdgcn_mfma_f32_16x16x32_bf16(Bt[n][k], At[m][k], acc[ai][bj][m][n], 0, 0, 0); __builtin_amdgcn_s_setprio(0); } while (0)
; #define G_WAIT_V(n) asm volatile("s_waitcnt vmcnt(" #n ")" ::: "memory")
; #define G_WAIT_L(n) asm volatile("s_waitcnt lgkmcnt(" #n ")" ::: "memory")
; #define G_BAR __builtin_amdgcn_s_barrier()
; #define G_SCHED __builtin_amdgcn_sched_barrier(0)
; template <bool PERM, class SchedT, class Epi>
; __device__ __forceinline__ void gemm_phase(LAS unsigned char* lds, const SchedT& S, const Epi& E) {
;     ...
;             G_LDB(B0, 0, 0); G_SCHED; G_LDA(At, 0, 0); G_STA(G_SA(1, 1), a1 + HSTEP(lda), lda);
;             G_WAIT_L(8); G_BAR; G_WAIT_L(0); G_MMA(0, 0, At, B0); G_BAR; G_SCHED;
;             G_LDB(B1, 0, 1); G_STB(G_SB(0, 0), b2, wK);
;             G_BAR; G_WAIT_L(0); G_MMA(0, 1, At, B1); G_BAR;
;             G_LDA(At, 0, 1); G_STA(G_SA(0, 0), a2, wlda);
;             G_BAR; G_WAIT_L(0); G_MMA(1, 0, At, B0); G_BAR; G_SCHED;
;             G_STB(G_SB(0, 1), b2 + HSTEP(wK), wK);
;             G_WAIT_V(6); G_BAR; G_MMA(1, 1, At, B1); G_BAR;
.LBB0_366:
	s_add_u32 s26, s24, 0xfff80080
	s_addc_u32 s27, s25, -1
	s_add_i32 s42, 0, 0x10000
	v_add_u32_e32 v148, s42, v155
	ds_read_b128 v[136:139], v148
	ds_read_b128 v[140:143], v148 offset:1024
	ds_read_b128 v[144:147], v148 offset:2048
	ds_read_b128 v[148:151], v148 offset:3072
	s_cmp_eq_u32 s41, 28
	s_cselect_b32 s29, s21, s27
	s_cselect_b32 s28, s20, s26
	s_cselect_b32 s27, s23, s19
	s_cselect_b32 s26, s22, s17
	v_lshl_add_u64 v[152:153], s[24:25], 0, v[132:133]
	s_add_i32 m0, s30, 0xc000
	ds_read_b128 v[160:163], v157
	ds_read_b128 v[164:167], v157 offset:1024
	ds_read_b128 v[168:171], v157 offset:2048
	ds_read_b128 v[172:175], v157 offset:3072
	ds_read_b128 v[176:179], v157 offset:4096
	ds_read_b128 v[192:195], v157 offset:5120
	ds_read_b128 v[196:199], v157 offset:6144
	ds_read_b128 v[200:203], v157 offset:7168
	global_load_lds_dwordx4 v[152:153], off
	v_lshl_add_u64 v[152:153], s[24:25], 0, v[134:135]
	s_add_i32 m0, s30, 0xe000
	s_nop 0
	global_load_lds_dwordx4 v[152:153], off
	s_waitcnt lgkmcnt(8)
	s_barrier
	s_waitcnt lgkmcnt(0)
	s_setprio 1
	s_waitcnt lgkmcnt(0)
	v_mfma_f32_16x16x32_bf16 v[66:69], v[136:139], v[160:163], v[66:69]
	v_mfma_f32_16x16x32_bf16 v[70:73], v[144:147], v[160:163], v[70:73]
	v_mfma_f32_16x16x32_bf16 v[82:85], v[136:139], v[168:171], v[82:85]
	v_mfma_f32_16x16x32_bf16 v[110:113], v[144:147], v[168:171], v[110:113]
	v_mfma_f32_16x16x32_bf16 v[126:129], v[136:139], v[176:179], v[126:129]
	v_mfma_f32_16x16x32_bf16 v[118:121], v[144:147], v[176:179], v[118:121]
	v_mfma_f32_16x16x32_bf16 v[122:125], v[136:139], v[196:199], v[122:125]
	v_mfma_f32_16x16x32_bf16 v[114:117], v[144:147], v[196:199], v[114:117]
	v_mfma_f32_16x16x32_bf16 v[66:69], v[140:143], v[164:167], v[66:69]
	v_mfma_f32_16x16x32_bf16 v[70:73], v[148:151], v[164:167], v[70:73]
	v_mfma_f32_16x16x32_bf16 v[82:85], v[140:143], v[172:175], v[82:85]
	v_mfma_f32_16x16x32_bf16 v[110:113], v[148:151], v[172:175], v[110:113]
	v_mfma_f32_16x16x32_bf16 v[126:129], v[140:143], v[192:195], v[126:129]
	v_mfma_f32_16x16x32_bf16 v[118:121], v[148:151], v[192:195], v[118:121]
	v_mfma_f32_16x16x32_bf16 v[122:125], v[140:143], v[200:203], v[122:125]
	v_mfma_f32_16x16x32_bf16 v[114:117], v[148:151], v[200:203], v[114:117]
	s_setprio 0
	s_barrier
	s_add_i32 s44, 0, 0x14000
	v_add_u32_e32 v152, s44, v155
	s_add_i32 s42, s42, s5
	ds_read_b128 v[204:207], v152
	ds_read_b128 v[208:211], v152 offset:1024
	ds_read_b128 v[212:215], v152 offset:2048
	ds_read_b128 v[216:219], v152 offset:3072
	v_lshl_add_u64 v[152:153], s[26:27], 0, v[0:1]
	s_mov_b32 m0, s42
	v_lshl_add_u64 v[220:221], s[26:27], 0, v[130:131]
	global_load_lds_dwordx4 v[152:153], off
	s_add_i32 m0, s42, 0x2000
	s_nop 0
	global_load_lds_dwordx4 v[220:221], off
	s_barrier
	s_waitcnt lgkmcnt(0)
	s_setprio 1
	s_waitcnt lgkmcnt(0)
	v_mfma_f32_16x16x32_bf16 v[74:77], v[204:207], v[160:163], v[74:77]
	v_mfma_f32_16x16x32_bf16 v[78:81], v[212:215], v[160:163], v[78:81]
	v_mfma_f32_16x16x32_bf16 v[98:101], v[204:207], v[168:171], v[98:101]
	v_mfma_f32_16x16x32_bf16 v[86:89], v[212:215], v[168:171], v[86:89]
	v_mfma_f32_16x16x32_bf16 v[106:109], v[204:207], v[176:179], v[106:109]
	v_mfma_f32_16x16x32_bf16 v[94:97], v[212:215], v[176:179], v[94:97]
	v_mfma_f32_16x16x32_bf16 v[102:105], v[204:207], v[196:199], v[102:105]
	v_mfma_f32_16x16x32_bf16 v[90:93], v[212:215], v[196:199], v[90:93]
	v_mfma_f32_16x16x32_bf16 v[74:77], v[208:211], v[164:167], v[74:77]
	v_mfma_f32_16x16x32_bf16 v[78:81], v[216:219], v[164:167], v[78:81]
	v_mfma_f32_16x16x32_bf16 v[98:101], v[208:211], v[172:175], v[98:101]
	v_mfma_f32_16x16x32_bf16 v[86:89], v[216:219], v[172:175], v[86:89]
	v_mfma_f32_16x16x32_bf16 v[106:109], v[208:211], v[192:195], v[106:109]
	v_mfma_f32_16x16x32_bf16 v[94:97], v[216:219], v[192:195], v[94:97]
	v_mfma_f32_16x16x32_bf16 v[102:105], v[208:211], v[200:203], v[102:105]
	v_mfma_f32_16x16x32_bf16 v[90:93], v[216:219], v[200:203], v[90:93]
	s_setprio 0
	s_mov_b32 m0, s30
	v_lshl_add_u64 v[222:223], s[28:29], 0, v[0:1]
	s_barrier
	ds_read_b128 v[160:163], v157 offset:16384
	ds_read_b128 v[164:167], v157 offset:17408
	ds_read_b128 v[168:171], v157 offset:18432
	ds_read_b128 v[172:175], v157 offset:19456
	ds_read_b128 v[176:179], v157 offset:20480
	ds_read_b128 v[192:195], v157 offset:21504
	ds_read_b128 v[196:199], v157 offset:22528
	ds_read_b128 v[200:203], v157 offset:23552
	global_load_lds_dwordx4 v[222:223], off
	v_lshl_add_u64 v[224:225], s[28:29], 0, v[130:131]
	s_mov_b32 m0, s31
	s_nop 0
	global_load_lds_dwordx4 v[224:225], off
	s_barrier
	s_waitcnt lgkmcnt(0)
	s_setprio 1
	s_waitcnt lgkmcnt(0)
	v_mfma_f32_16x16x32_bf16 v[62:65], v[136:139], v[160:163], v[62:65]
	v_mfma_f32_16x16x32_bf16 v[58:61], v[144:147], v[160:163], v[58:61]
	v_mfma_f32_16x16x32_bf16 v[46:49], v[136:139], v[168:171], v[46:49]
	v_mfma_f32_16x16x32_bf16 v[42:45], v[144:147], v[168:171], v[42:45]
	v_mfma_f32_16x16x32_bf16 v[30:33], v[136:139], v[176:179], v[30:33]
	v_mfma_f32_16x16x32_bf16 v[26:29], v[144:147], v[176:179], v[26:29]
	v_mfma_f32_16x16x32_bf16 v[14:17], v[136:139], v[196:199], v[14:17]
	v_mfma_f32_16x16x32_bf16 v[10:13], v[144:147], v[196:199], v[10:13]
	v_mfma_f32_16x16x32_bf16 v[62:65], v[140:143], v[164:167], v[62:65]
	v_mfma_f32_16x16x32_bf16 v[58:61], v[148:151], v[164:167], v[58:61]
	v_mfma_f32_16x16x32_bf16 v[46:49], v[140:143], v[172:175], v[46:49]
	v_mfma_f32_16x16x32_bf16 v[42:45], v[148:151], v[172:175], v[42:45]
	v_mfma_f32_16x16x32_bf16 v[30:33], v[140:143], v[192:195], v[30:33]
	v_mfma_f32_16x16x32_bf16 v[26:29], v[148:151], v[192:195], v[26:29]
	v_mfma_f32_16x16x32_bf16 v[14:17], v[140:143], v[200:203], v[14:17]
	v_mfma_f32_16x16x32_bf16 v[10:13], v[148:151], v[200:203], v[10:13]
	s_setprio 0
	s_barrier
; #define G_STA(bufoff, gbase, ld) G_STAGE(bufoff, gbase, RA0, RA1, ld)
; #define G_STB(bufoff, gbase, ld) G_STAGE(bufoff, gbase, RB0, RB1, ld)
; #define G_LDA(dst, b, h) do { _Pragma("unroll") for (int m = 0; m < 4; ++m) _Pragma("unroll") for (int k = 0; k < 2; ++k) dst[m][k] = *(const LAS bf16x8*)(lds + G_SA(b, h) + aoff + m * 2048 + k * 1024); } while (0)
; #define G_LDB(dst, b, h) do { _Pragma("unroll") for (int n = 0; n < 2; ++n) _Pragma("unroll") for (int k = 0; k < 2; ++k) dst[n][k] = *(const LAS bf16x8*)(lds + G_SB(b, h) + boff + n * 2048 + k * 1024); } while (0)
; #define G_MMA(ai, bj, At, Bt) do { __builtin_amdgcn_s_setprio(1); _Pragma("unroll") for (int m = 0; m < 4; ++m) _Pragma("unroll") for (int n = 0; n < 2; ++n) _Pragma("unroll") for (int k = 0; k < 2; ++k) \
;         acc[ai][bj][m][n] = __builtin_amdgcn_mfma_f32_16x16x32_bf16(Bt[n][k], At[m][k], acc[ai][bj][m][n], 0, 0, 0); __builtin_amdgcn_s_setprio(0); } while (0)
; #define G_WAIT_V(n) asm volatile("s_waitcnt vmcnt(" #n ")" ::: "memory")
; #define G_WAIT_L(n) asm volatile("s_waitcnt lgkmcnt(" #n ")" ::: "memory")
; #define G_BAR __builtin_amdgcn_s_barrier()
; #define G_SCHED __builtin_amdgcn_sched_barrier(0)
; template <bool PERM, class SchedT, class Epi>
; __device__ __forceinline__ void gemm_phase(LAS unsigned char* lds, const SchedT& S, const Epi& E) {
;     ...
;             G_STB(G_SB(0, 1), b2 + HSTEP(wK), wK);
;             G_WAIT_V(6); G_BAR; G_MMA(1, 1, At, B1); G_BAR;
;             G_LDB(B0, 1, 0); G_SCHED; G_LDA(At, 1, 0); G_STA(G_SA(0, 1), a2 + HSTEP(wlda), wlda);
;             G_WAIT_L(8); G_BAR; G_WAIT_L(0); G_MMA(0, 0, At, B0); G_BAR; G_SCHED;
;             G_LDB(B1, 1, 1); G_STB(G_SB(1, 0), b3, wK);
;             G_BAR; G_WAIT_L(0); G_MMA(0, 1, At, B1); G_BAR;
;             G_LDA(At, 1, 1); G_STA(G_SA(1, 0), a3, wlda);
;             G_BAR; G_WAIT_L(0); G_MMA(1, 0, At, B0); G_BAR; G_SCHED;
	s_add_u32 s42, s26, 0x80000
	s_addc_u32 s43, s27, 0
	s_add_i32 s44, s44, s5
	v_lshl_add_u64 v[136:137], s[42:43], 0, v[0:1]
	s_mov_b32 m0, s44
	s_nop 0
	global_load_lds_dwordx4 v[136:137], off
	v_lshl_add_u64 v[136:137], s[42:43], 0, v[130:131]
	s_add_i32 m0, s44, 0x2000
	s_nop 0
	global_load_lds_dwordx4 v[136:137], off
	s_waitcnt vmcnt(6)
	s_barrier
	s_setprio 1
	v_mfma_f32_16x16x32_bf16 v[54:57], v[204:207], v[160:163], v[54:57]
	v_mfma_f32_16x16x32_bf16 v[50:53], v[212:215], v[160:163], v[50:53]
	v_mfma_f32_16x16x32_bf16 v[38:41], v[204:207], v[168:171], v[38:41]
	v_mfma_f32_16x16x32_bf16 v[34:37], v[212:215], v[168:171], v[34:37]
	v_mfma_f32_16x16x32_bf16 v[22:25], v[204:207], v[176:179], v[22:25]
	v_mfma_f32_16x16x32_bf16 v[18:21], v[212:215], v[176:179], v[18:21]
	v_mfma_f32_16x16x32_bf16 v[6:9], v[204:207], v[196:199], v[6:9]
	v_mfma_f32_16x16x32_bf16 v[2:5], v[212:215], v[196:199], v[2:5]
	v_mfma_f32_16x16x32_bf16 v[54:57], v[208:211], v[164:167], v[54:57]
	v_mfma_f32_16x16x32_bf16 v[50:53], v[216:219], v[164:167], v[50:53]
	v_mfma_f32_16x16x32_bf16 v[38:41], v[208:211], v[172:175], v[38:41]
	v_mfma_f32_16x16x32_bf16 v[34:37], v[216:219], v[172:175], v[34:37]
	v_mfma_f32_16x16x32_bf16 v[22:25], v[208:211], v[192:195], v[22:25]
	v_mfma_f32_16x16x32_bf16 v[18:21], v[216:219], v[192:195], v[18:21]
	v_mfma_f32_16x16x32_bf16 v[6:9], v[208:211], v[200:203], v[6:9]
	v_mfma_f32_16x16x32_bf16 v[2:5], v[216:219], v[200:203], v[2:5]
	s_setprio 0
	s_add_i32 s42, 0, 0x18000
	v_add_u32_e32 v148, s42, v155
	s_barrier
	ds_read_b128 v[136:139], v148
	ds_read_b128 v[140:143], v148 offset:1024
	ds_read_b128 v[144:147], v148 offset:2048
	ds_read_b128 v[148:151], v148 offset:3072
	s_add_u32 s28, s28, 0x80000
	s_addc_u32 s29, s29, 0
	s_mov_b32 m0, s34
	v_lshl_add_u64 v[204:205], s[28:29], 0, v[0:1]
	ds_read_b128 v[160:163], v157 offset:32768
	ds_read_b128 v[164:167], v157 offset:33792
	ds_read_b128 v[168:171], v157 offset:34816
	ds_read_b128 v[172:175], v157 offset:35840
	ds_read_b128 v[176:179], v157 offset:36864
	ds_read_b128 v[192:195], v157 offset:37888
	ds_read_b128 v[196:199], v157 offset:38912
	ds_read_b128 v[200:203], v157 offset:39936
	global_load_lds_dwordx4 v[204:205], off
	v_lshl_add_u64 v[204:205], s[28:29], 0, v[130:131]
	s_mov_b32 m0, s35
	s_nop 0
	global_load_lds_dwordx4 v[204:205], off
	s_waitcnt lgkmcnt(8)
	s_barrier
	s_waitcnt lgkmcnt(0)
	s_setprio 1
	s_waitcnt lgkmcnt(0)
	v_mfma_f32_16x16x32_bf16 v[66:69], v[136:139], v[160:163], v[66:69]
	v_mfma_f32_16x16x32_bf16 v[70:73], v[144:147], v[160:163], v[70:73]
	v_mfma_f32_16x16x32_bf16 v[82:85], v[136:139], v[168:171], v[82:85]
	v_mfma_f32_16x16x32_bf16 v[110:113], v[144:147], v[168:171], v[110:113]
	v_mfma_f32_16x16x32_bf16 v[126:129], v[136:139], v[176:179], v[126:129]
	v_mfma_f32_16x16x32_bf16 v[118:121], v[144:147], v[176:179], v[118:121]
	v_mfma_f32_16x16x32_bf16 v[122:125], v[136:139], v[196:199], v[122:125]
	v_mfma_f32_16x16x32_bf16 v[114:117], v[144:147], v[196:199], v[114:117]
	v_mfma_f32_16x16x32_bf16 v[66:69], v[140:143], v[164:167], v[66:69]
	v_mfma_f32_16x16x32_bf16 v[70:73], v[148:151], v[164:167], v[70:73]
	v_mfma_f32_16x16x32_bf16 v[82:85], v[140:143], v[172:175], v[82:85]
	v_mfma_f32_16x16x32_bf16 v[110:113], v[148:151], v[172:175], v[110:113]
	v_mfma_f32_16x16x32_bf16 v[126:129], v[140:143], v[192:195], v[126:129]
	v_mfma_f32_16x16x32_bf16 v[118:121], v[148:151], v[192:195], v[118:121]
	v_mfma_f32_16x16x32_bf16 v[122:125], v[140:143], v[200:203], v[122:125]
	v_mfma_f32_16x16x32_bf16 v[114:117], v[148:151], v[200:203], v[114:117]
	s_setprio 0
	s_barrier
	s_add_i32 s28, 0, 0x1c000
	s_add_i32 s29, s42, s5
	v_add_u32_e32 v216, s28, v155
	v_lshl_add_u64 v[152:153], v[152:153], 0, s[78:79]
	s_mov_b32 m0, s29
	ds_read_b128 v[204:207], v216
	ds_read_b128 v[208:211], v216 offset:1024
	ds_read_b128 v[212:215], v216 offset:2048
	ds_read_b128 v[216:219], v216 offset:3072
	global_load_lds_dwordx4 v[152:153], off
	v_lshl_add_u64 v[152:153], v[220:221], 0, s[78:79]
	s_add_i32 m0, s29, 0x2000
	s_nop 0
	global_load_lds_dwordx4 v[152:153], off
	s_barrier
	s_waitcnt lgkmcnt(0)
	s_setprio 1
	s_waitcnt lgkmcnt(0)
	v_mfma_f32_16x16x32_bf16 v[74:77], v[204:207], v[160:163], v[74:77]
	v_mfma_f32_16x16x32_bf16 v[78:81], v[212:215], v[160:163], v[78:81]
	v_mfma_f32_16x16x32_bf16 v[98:101], v[204:207], v[168:171], v[98:101]
	v_mfma_f32_16x16x32_bf16 v[86:89], v[212:215], v[168:171], v[86:89]
	v_mfma_f32_16x16x32_bf16 v[106:109], v[204:207], v[176:179], v[106:109]
	v_mfma_f32_16x16x32_bf16 v[94:97], v[212:215], v[176:179], v[94:97]
	v_mfma_f32_16x16x32_bf16 v[102:105], v[204:207], v[196:199], v[102:105]
	v_mfma_f32_16x16x32_bf16 v[90:93], v[212:215], v[196:199], v[90:93]
	v_mfma_f32_16x16x32_bf16 v[74:77], v[208:211], v[164:167], v[74:77]
	v_mfma_f32_16x16x32_bf16 v[78:81], v[216:219], v[164:167], v[78:81]
	v_mfma_f32_16x16x32_bf16 v[98:101], v[208:211], v[172:175], v[98:101]
	v_mfma_f32_16x16x32_bf16 v[86:89], v[216:219], v[172:175], v[86:89]
	v_mfma_f32_16x16x32_bf16 v[106:109], v[208:211], v[192:195], v[106:109]
	v_mfma_f32_16x16x32_bf16 v[94:97], v[216:219], v[192:195], v[94:97]
	v_mfma_f32_16x16x32_bf16 v[102:105], v[208:211], v[200:203], v[102:105]
	v_mfma_f32_16x16x32_bf16 v[90:93], v[216:219], v[200:203], v[90:93]
	s_setprio 0
	s_mov_b32 m0, s36
	v_lshl_add_u64 v[152:153], v[222:223], 0, s[78:79]
	s_barrier
	ds_read_b128 v[160:163], v157 offset:49152
	ds_read_b128 v[164:167], v157 offset:50176
	ds_read_b128 v[168:171], v157 offset:51200
	ds_read_b128 v[172:175], v157 offset:52224
	ds_read_b128 v[176:179], v157 offset:53248
	ds_read_b128 v[192:195], v157 offset:54272
	ds_read_b128 v[196:199], v157 offset:55296
	ds_read_b128 v[200:203], v157 offset:56320
	global_load_lds_dwordx4 v[152:153], off
	v_lshl_add_u64 v[152:153], v[224:225], 0, s[78:79]
	s_mov_b32 m0, s37
	s_nop 0
	global_load_lds_dwordx4 v[152:153], off
	s_barrier
; #define G_STA(bufoff, gbase, ld) G_STAGE(bufoff, gbase, RA0, RA1, ld)
; #define G_STB(bufoff, gbase, ld) G_STAGE(bufoff, gbase, RB0, RB1, ld)
; #define G_LDA(dst, b, h) do { _Pragma("unroll") for (int m = 0; m < 4; ++m) _Pragma("unroll") for (int k = 0; k < 2; ++k) dst[m][k] = *(const LAS bf16x8*)(lds + G_SA(b, h) + aoff + m * 2048 + k * 1024); } while (0)
; #define G_MMA(ai, bj, At, Bt) do { __builtin_amdgcn_s_setprio(1); _Pragma("unroll") for (int m = 0; m < 4; ++m) _Pragma("unroll") for (int n = 0; n < 2; ++n) _Pragma("unroll") for (int k = 0; k < 2; ++k) \
;         acc[ai][bj][m][n] = __builtin_amdgcn_mfma_f32_16x16x32_bf16(Bt[n][k], At[m][k], acc[ai][bj][m][n], 0, 0, 0); __builtin_amdgcn_s_setprio(0); } while (0)
; #define G_WAIT_V(n) asm volatile("s_waitcnt vmcnt(" #n ")" ::: "memory")
; #define G_WAIT_L(n) asm volatile("s_waitcnt lgkmcnt(" #n ")" ::: "memory")
; #define G_BAR __builtin_amdgcn_s_barrier()
; #define G_SCHED __builtin_amdgcn_sched_barrier(0)
; template <bool PERM, class SchedT, class Epi>
; __device__ __forceinline__ void gemm_phase(LAS unsigned char* lds, const SchedT& S, const Epi& E) {
;     ...
;             G_BAR; G_WAIT_L(0); G_MMA(0, 1, At, B1); G_BAR;
;             G_LDA(At, 1, 1); G_STA(G_SA(1, 0), a3, wlda);
;             G_BAR; G_WAIT_L(0); G_MMA(1, 0, At, B0); G_BAR; G_SCHED;
;             G_STB(G_SB(1, 1), b3 + HSTEP(wK), wK);
;             G_WAIT_V(6); G_BAR; G_MMA(1, 1, At, B1); G_BAR;
;     __device__ __forceinline__ void operator()(f32x4 (&acc)[2][2][4][2], const UnitD& u, int wr, int wc, int fr, int fq) const {
;         const int row0 = u.pm * BM + wr * 64 + fr, col0 = u.pn * BM + wc * 32 + 4 * fq;
; #pragma unroll
;         for (int ai = 0; ai < 2; ++ai)
; #pragma unroll
;             for (int m = 0; m < 4; ++m) { const int row = row0 + ai * HALF + m * 16;
;                 const float* xr = (row < TP ? xp + (size_t)row * 2048 : xs + (size_t)(row - TP) * 2048) + col0;
; #pragma unroll
;                 for (int bj = 0; bj < 2; ++bj)
; #pragma unroll
;                     for (int n = 0; n < 2; ++n) acc[ai][bj][m][n] += *(const f32x4*)(xr + bj * HALF + n * 16);
;                 if (m & 1) asm volatile("" ::: "memory"); }
	s_waitcnt lgkmcnt(0)
	s_setprio 1
	s_waitcnt lgkmcnt(0)
	v_mfma_f32_16x16x32_bf16 v[62:65], v[136:139], v[160:163], v[62:65]
	v_mfma_f32_16x16x32_bf16 v[58:61], v[144:147], v[160:163], v[58:61]
	v_mfma_f32_16x16x32_bf16 v[46:49], v[136:139], v[168:171], v[46:49]
	v_mfma_f32_16x16x32_bf16 v[42:45], v[144:147], v[168:171], v[42:45]
	v_mfma_f32_16x16x32_bf16 v[30:33], v[136:139], v[176:179], v[30:33]
	v_mfma_f32_16x16x32_bf16 v[26:29], v[144:147], v[176:179], v[26:29]
	v_mfma_f32_16x16x32_bf16 v[14:17], v[136:139], v[196:199], v[14:17]
	v_mfma_f32_16x16x32_bf16 v[10:13], v[144:147], v[196:199], v[10:13]
	v_mfma_f32_16x16x32_bf16 v[62:65], v[140:143], v[164:167], v[62:65]
	v_mfma_f32_16x16x32_bf16 v[58:61], v[148:151], v[164:167], v[58:61]
	v_mfma_f32_16x16x32_bf16 v[46:49], v[140:143], v[172:175], v[46:49]
	v_mfma_f32_16x16x32_bf16 v[42:45], v[148:151], v[172:175], v[42:45]
	v_mfma_f32_16x16x32_bf16 v[30:33], v[140:143], v[192:195], v[30:33]
	v_mfma_f32_16x16x32_bf16 v[26:29], v[148:151], v[192:195], v[26:29]
	v_mfma_f32_16x16x32_bf16 v[14:17], v[140:143], v[200:203], v[14:17]
	v_mfma_f32_16x16x32_bf16 v[10:13], v[148:151], v[200:203], v[10:13]
	s_setprio 0
	s_barrier
	s_add_u32 s26, s26, 0x80080
	s_addc_u32 s27, s27, 0
	s_add_i32 s28, s28, s5
	v_lshl_add_u64 v[136:137], s[26:27], 0, v[0:1]
	s_mov_b32 m0, s28
	s_nop 0
	global_load_lds_dwordx4 v[136:137], off
	v_lshl_add_u64 v[136:137], s[26:27], 0, v[130:131]
	s_add_i32 m0, s28, 0x2000
	s_nop 0
	global_load_lds_dwordx4 v[136:137], off
	s_waitcnt vmcnt(6)
	s_barrier
	s_setprio 1
	v_mfma_f32_16x16x32_bf16 v[54:57], v[204:207], v[160:163], v[54:57]
	v_mfma_f32_16x16x32_bf16 v[50:53], v[212:215], v[160:163], v[50:53]
	v_mfma_f32_16x16x32_bf16 v[38:41], v[204:207], v[168:171], v[38:41]
	v_mfma_f32_16x16x32_bf16 v[34:37], v[212:215], v[168:171], v[34:37]
	v_mfma_f32_16x16x32_bf16 v[22:25], v[204:207], v[176:179], v[22:25]
	v_mfma_f32_16x16x32_bf16 v[18:21], v[212:215], v[176:179], v[18:21]
	v_mfma_f32_16x16x32_bf16 v[6:9], v[204:207], v[196:199], v[6:9]
	v_mfma_f32_16x16x32_bf16 v[2:5], v[212:215], v[196:199], v[2:5]
	v_mfma_f32_16x16x32_bf16 v[54:57], v[208:211], v[164:167], v[54:57]
	v_mfma_f32_16x16x32_bf16 v[50:53], v[216:219], v[164:167], v[50:53]
	v_mfma_f32_16x16x32_bf16 v[38:41], v[208:211], v[172:175], v[38:41]
	v_mfma_f32_16x16x32_bf16 v[34:37], v[216:219], v[172:175], v[34:37]
	v_mfma_f32_16x16x32_bf16 v[22:25], v[208:211], v[192:195], v[22:25]
	v_mfma_f32_16x16x32_bf16 v[18:21], v[216:219], v[192:195], v[18:21]
	v_mfma_f32_16x16x32_bf16 v[6:9], v[208:211], v[200:203], v[6:9]
	v_mfma_f32_16x16x32_bf16 v[2:5], v[216:219], v[200:203], v[2:5]
	s_setprio 0
	s_add_i32 s41, s41, 2
	s_add_u32 s24, s24, 0x100
	s_addc_u32 s25, s25, 0
	s_add_u32 s17, s17, 0x100
	s_addc_u32 s19, s19, 0
	s_cmp_gt_u32 s41, 29
	s_barrier
	s_cbranch_scc0 .LBB0_366
	v_lshl_add_u32 v208, s39, 8, v154
	v_lshl_or_b32 v209, s40, 8, v156
	v_lshlrev_b32_e32 v209, 2, v209
	v_lshl_add_u32 v208, v208, 13, v209
	v_mov_b32_e32 v209, 0
	v_lshl_add_u64 v[210:211], s[8:9], 0, v[208:209]
	v_lshl_add_u64 v[212:213], s[12:13], 0, v[208:209]
	v_mov_b32_e32 v214, v210
	v_mov_b32_e32 v215, v211
	global_load_dwordx4 v[136:139], v[214:215], off
	global_load_dwordx4 v[140:143], v[214:215], off offset:64
	global_load_dwordx4 v[144:147], v[214:215], off offset:512
	global_load_dwordx4 v[148:151], v[214:215], off offset:576
	v_add_co_u32_e32 v214, vcc, 0x20000, v210
	s_nop 1
	v_addc_co_u32_e32 v215, vcc, 0, v211, vcc
	global_load_dwordx4 v[160:163], v[214:215], off
	global_load_dwordx4 v[164:167], v[214:215], off offset:64
	global_load_dwordx4 v[168:171], v[214:215], off offset:512
	global_load_dwordx4 v[172:175], v[214:215], off offset:576
	v_add_co_u32_e32 v214, vcc, 0x40000, v210
	s_nop 1
	v_addc_co_u32_e32 v215, vcc, 0, v211, vcc
	global_load_dwordx4 v[192:195], v[214:215], off
	global_load_dwordx4 v[196:199], v[214:215], off offset:64
	global_load_dwordx4 v[200:203], v[214:215], off offset:512
	global_load_dwordx4 v[204:207], v[214:215], off offset:576
	ds_write_b128 v251, v[66:69]
	ds_read_b128 v[66:69], v252
	ds_write_b128 v251, v[70:73]
	ds_read_b128 v[70:73], v252
	ds_write_b128 v251, v[74:77]
	ds_read_b128 v[74:77], v252
	ds_write_b128 v251, v[78:81]
	ds_read_b128 v[78:81], v252
	v_mov_b32_e32 v216, v212
	v_mov_b32_e32 v217, v213
	s_waitcnt vmcnt(8)
	s_waitcnt lgkmcnt(6)
	v_pk_add_f32 v[66:67], v[66:67], v[136:137]
	v_pk_add_f32 v[68:69], v[68:69], v[138:139]
	s_waitcnt lgkmcnt(4)
	v_pk_add_f32 v[70:71], v[70:71], v[140:141]
	v_pk_add_f32 v[72:73], v[72:73], v[142:143]
	s_waitcnt lgkmcnt(2)
	v_pk_add_f32 v[74:75], v[74:75], v[144:145]
	v_pk_add_f32 v[76:77], v[76:77], v[146:147]
	s_waitcnt lgkmcnt(0)
	v_pk_add_f32 v[78:79], v[78:79], v[148:149]
	v_pk_add_f32 v[80:81], v[80:81], v[150:151]
	v_add_co_u32_e32 v214, vcc, 0x60000, v210
	s_nop 1
	v_addc_co_u32_e32 v215, vcc, 0, v211, vcc
	global_load_dwordx4 v[136:139], v[214:215], off
	global_load_dwordx4 v[140:143], v[214:215], off offset:64
	global_load_dwordx4 v[144:147], v[214:215], off offset:512
	global_load_dwordx4 v[148:151], v[214:215], off offset:576
	ds_write_b128 v251, v[82:85]
	ds_read_b128 v[82:85], v252
	ds_write_b128 v251, v[110:113]
	ds_read_b128 v[110:113], v252
	ds_write_b128 v251, v[98:101]
	ds_read_b128 v[98:101], v252
	ds_write_b128 v251, v[86:89]
	ds_read_b128 v[86:89], v252
	v_add_co_u32_e32 v216, vcc, 0x20000, v212
	s_nop 1
	v_addc_co_u32_e32 v217, vcc, 0, v213, vcc
	s_waitcnt vmcnt(8)
	s_waitcnt lgkmcnt(6)
	v_pk_add_f32 v[82:83], v[82:83], v[160:161]
	v_pk_add_f32 v[84:85], v[84:85], v[162:163]
	s_waitcnt lgkmcnt(4)
;     __device__ __forceinline__ void operator()(f32x4 (&acc)[2][2][4][2], const UnitD& u, int wr, int wc, int fr, int fq) const {
;     ...
;         for (int ai = 0; ai < 2; ++ai)
; #pragma unroll
;             for (int m = 0; m < 4; ++m) { const int row = row0 + ai * HALF + m * 16;
;                 const float* xr = (row < TP ? xp + (size_t)row * 2048 : xs + (size_t)(row - TP) * 2048) + col0;
; #pragma unroll
;                 for (int bj = 0; bj < 2; ++bj)
; #pragma unroll
;                     for (int n = 0; n < 2; ++n) acc[ai][bj][m][n] += *(const f32x4*)(xr + bj * HALF + n * 16);
;                 if (m & 1) asm volatile("" ::: "memory"); }
	v_pk_add_f32 v[110:111], v[110:111], v[164:165]
	v_pk_add_f32 v[112:113], v[112:113], v[166:167]
	s_waitcnt lgkmcnt(2)
	v_pk_add_f32 v[98:99], v[98:99], v[168:169]
	v_pk_add_f32 v[100:101], v[100:101], v[170:171]
	s_waitcnt lgkmcnt(0)
	v_pk_add_f32 v[86:87], v[86:87], v[172:173]
	v_pk_add_f32 v[88:89], v[88:89], v[174:175]
	v_add_co_u32_e32 v214, vcc, 0x100000, v210
	s_nop 1
	v_addc_co_u32_e32 v215, vcc, 0, v211, vcc
	global_load_dwordx4 v[160:163], v[214:215], off
	global_load_dwordx4 v[164:167], v[214:215], off offset:64
	global_load_dwordx4 v[168:171], v[214:215], off offset:512
	global_load_dwordx4 v[172:175], v[214:215], off offset:576
	ds_write_b128 v251, v[126:129]
	ds_read_b128 v[126:129], v252
	ds_write_b128 v251, v[118:121]
	ds_read_b128 v[118:121], v252
	ds_write_b128 v251, v[106:109]
	ds_read_b128 v[106:109], v252
	ds_write_b128 v251, v[94:97]
	ds_read_b128 v[94:97], v252
	v_add_co_u32_e32 v216, vcc, 0x40000, v212
	s_nop 1
	v_addc_co_u32_e32 v217, vcc, 0, v213, vcc
	s_waitcnt vmcnt(8)
	s_waitcnt lgkmcnt(6)
	v_pk_add_f32 v[126:127], v[126:127], v[192:193]
	v_pk_add_f32 v[128:129], v[128:129], v[194:195]
	s_waitcnt lgkmcnt(4)
	v_pk_add_f32 v[118:119], v[118:119], v[196:197]
	v_pk_add_f32 v[120:121], v[120:121], v[198:199]
	s_waitcnt lgkmcnt(2)
	v_pk_add_f32 v[106:107], v[106:107], v[200:201]
	v_pk_add_f32 v[108:109], v[108:109], v[202:203]
	s_waitcnt lgkmcnt(0)
	v_pk_add_f32 v[94:95], v[94:95], v[204:205]
	v_pk_add_f32 v[96:97], v[96:97], v[206:207]
	v_add_co_u32_e32 v214, vcc, 0x120000, v210
	s_nop 1
	v_addc_co_u32_e32 v215, vcc, 0, v211, vcc
	global_load_dwordx4 v[192:195], v[214:215], off
	global_load_dwordx4 v[196:199], v[214:215], off offset:64
	global_load_dwordx4 v[200:203], v[214:215], off offset:512
	global_load_dwordx4 v[204:207], v[214:215], off offset:576
	ds_write_b128 v251, v[122:125]
	ds_read_b128 v[122:125], v252
	ds_write_b128 v251, v[114:117]
	ds_read_b128 v[114:117], v252
	ds_write_b128 v251, v[102:105]
	ds_read_b128 v[102:105], v252
	ds_write_b128 v251, v[90:93]
	ds_read_b128 v[90:93], v252
	v_add_co_u32_e32 v216, vcc, 0x60000, v212
	s_nop 1
	v_addc_co_u32_e32 v217, vcc, 0, v213, vcc
	s_waitcnt vmcnt(8)
	s_waitcnt lgkmcnt(6)
	v_pk_add_f32 v[122:123], v[122:123], v[136:137]
	v_pk_add_f32 v[124:125], v[124:125], v[138:139]
	s_waitcnt lgkmcnt(4)
	v_pk_add_f32 v[114:115], v[114:115], v[140:141]
	v_pk_add_f32 v[116:117], v[116:117], v[142:143]
	s_waitcnt lgkmcnt(2)
	v_pk_add_f32 v[102:103], v[102:103], v[144:145]
	v_pk_add_f32 v[104:105], v[104:105], v[146:147]
	s_waitcnt lgkmcnt(0)
	v_pk_add_f32 v[90:91], v[90:91], v[148:149]
	v_pk_add_f32 v[92:93], v[92:93], v[150:151]
	v_add_co_u32_e32 v214, vcc, 0x140000, v210
	s_nop 1
	v_addc_co_u32_e32 v215, vcc, 0, v211, vcc
	global_load_dwordx4 v[136:139], v[214:215], off
	global_load_dwordx4 v[140:143], v[214:215], off offset:64
	global_load_dwordx4 v[144:147], v[214:215], off offset:512
	global_load_dwordx4 v[148:151], v[214:215], off offset:576
	ds_write_b128 v251, v[62:65]
	ds_read_b128 v[62:65], v252
	ds_write_b128 v251, v[58:61]
	ds_read_b128 v[58:61], v252
	ds_write_b128 v251, v[54:57]
	ds_read_b128 v[54:57], v252
	ds_write_b128 v251, v[50:53]
	ds_read_b128 v[50:53], v252
	v_add_co_u32_e32 v216, vcc, 0x100000, v212
	s_nop 1
	v_addc_co_u32_e32 v217, vcc, 0, v213, vcc
	s_waitcnt vmcnt(8)
	s_waitcnt lgkmcnt(6)
	v_pk_add_f32 v[62:63], v[62:63], v[160:161]
	v_pk_add_f32 v[64:65], v[64:65], v[162:163]
	s_waitcnt lgkmcnt(4)
	v_pk_add_f32 v[58:59], v[58:59], v[164:165]
	v_pk_add_f32 v[60:61], v[60:61], v[166:167]
	s_waitcnt lgkmcnt(2)
	v_pk_add_f32 v[54:55], v[54:55], v[168:169]
	v_pk_add_f32 v[56:57], v[56:57], v[170:171]
	s_waitcnt lgkmcnt(0)
	v_pk_add_f32 v[50:51], v[50:51], v[172:173]
	v_pk_add_f32 v[52:53], v[52:53], v[174:175]
	v_add_co_u32_e32 v214, vcc, 0x160000, v210
	s_nop 1
	v_addc_co_u32_e32 v215, vcc, 0, v211, vcc
	global_load_dwordx4 v[160:163], v[214:215], off
	global_load_dwordx4 v[164:167], v[214:215], off offset:64
	global_load_dwordx4 v[168:171], v[214:215], off offset:512
	global_load_dwordx4 v[172:175], v[214:215], off offset:576
	ds_write_b128 v251, v[46:49]
	ds_read_b128 v[46:49], v252
	ds_write_b128 v251, v[42:45]
	ds_read_b128 v[42:45], v252
	ds_write_b128 v251, v[38:41]
	ds_read_b128 v[38:41], v252
	ds_write_b128 v251, v[34:37]
	ds_read_b128 v[34:37], v252
	v_add_co_u32_e32 v216, vcc, 0x120000, v212
	s_nop 1
	v_addc_co_u32_e32 v217, vcc, 0, v213, vcc
	s_waitcnt vmcnt(8)
	s_waitcnt lgkmcnt(6)
	v_pk_add_f32 v[46:47], v[46:47], v[192:193]
	v_pk_add_f32 v[48:49], v[48:49], v[194:195]
	s_waitcnt lgkmcnt(4)
;     __device__ __forceinline__ void operator()(f32x4 (&acc)[2][2][4][2], const UnitD& u, int wr, int wc, int fr, int fq) const {
;     ...
; #pragma unroll
;                     for (int n = 0; n < 2; ++n) acc[ai][bj][m][n] += *(const f32x4*)(xr + bj * HALF + n * 16);
;                 if (m & 1) asm volatile("" ::: "memory"); }
; #pragma unroll
;         for (int ai = 0; ai < 2; ++ai)
; #pragma unroll
;             for (int m = 0; m < 4; ++m) { const int row = row0 + ai * HALF + m * 16; float* orow = out + (size_t)row * 2048 + col0;
; #pragma unroll
;                 for (int bj = 0; bj < 2; ++bj)
; #pragma unroll
;                     for (int n = 0; n < 2; ++n) *(f32x4*)(orow + bj * HALF + n * 16) = acc[ai][bj][m][n]; }
	v_pk_add_f32 v[42:43], v[42:43], v[196:197]
	v_pk_add_f32 v[44:45], v[44:45], v[198:199]
	s_waitcnt lgkmcnt(2)
	v_pk_add_f32 v[38:39], v[38:39], v[200:201]
	v_pk_add_f32 v[40:41], v[40:41], v[202:203]
	s_waitcnt lgkmcnt(0)
	v_pk_add_f32 v[34:35], v[34:35], v[204:205]
	v_pk_add_f32 v[36:37], v[36:37], v[206:207]
	ds_write_b128 v251, v[30:33]
	ds_read_b128 v[30:33], v252
	ds_write_b128 v251, v[26:29]
	ds_read_b128 v[26:29], v252
	ds_write_b128 v251, v[22:25]
	ds_read_b128 v[22:25], v252
	ds_write_b128 v251, v[18:21]
	ds_read_b128 v[18:21], v252
	v_add_co_u32_e32 v216, vcc, 0x140000, v212
	s_nop 1
	v_addc_co_u32_e32 v217, vcc, 0, v213, vcc
	s_waitcnt vmcnt(4)
	s_waitcnt lgkmcnt(6)
	v_pk_add_f32 v[30:31], v[30:31], v[136:137]
	v_pk_add_f32 v[32:33], v[32:33], v[138:139]
	s_waitcnt lgkmcnt(4)
	v_pk_add_f32 v[26:27], v[26:27], v[140:141]
	v_pk_add_f32 v[28:29], v[28:29], v[142:143]
	s_waitcnt lgkmcnt(2)
	v_pk_add_f32 v[22:23], v[22:23], v[144:145]
	v_pk_add_f32 v[24:25], v[24:25], v[146:147]
	s_waitcnt lgkmcnt(0)
	v_pk_add_f32 v[18:19], v[18:19], v[148:149]
	v_pk_add_f32 v[20:21], v[20:21], v[150:151]
	ds_write_b128 v251, v[14:17]
	ds_read_b128 v[14:17], v252
	ds_write_b128 v251, v[10:13]
	ds_read_b128 v[10:13], v252
	ds_write_b128 v251, v[6:9]
	ds_read_b128 v[6:9], v252
	ds_write_b128 v251, v[2:5]
	ds_read_b128 v[2:5], v252
	v_add_co_u32_e32 v216, vcc, 0x160000, v212
	s_nop 1
	v_addc_co_u32_e32 v217, vcc, 0, v213, vcc
	s_waitcnt vmcnt(0)
	s_waitcnt lgkmcnt(6)
	v_pk_add_f32 v[14:15], v[14:15], v[160:161]
	v_pk_add_f32 v[16:17], v[16:17], v[162:163]
	s_waitcnt lgkmcnt(4)
	v_pk_add_f32 v[10:11], v[10:11], v[164:165]
	v_pk_add_f32 v[12:13], v[12:13], v[166:167]
	s_waitcnt lgkmcnt(2)
	v_pk_add_f32 v[6:7], v[6:7], v[168:169]
	v_pk_add_f32 v[8:9], v[8:9], v[170:171]
	s_waitcnt lgkmcnt(0)
	v_pk_add_f32 v[2:3], v[2:3], v[172:173]
	v_pk_add_f32 v[4:5], v[4:5], v[174:175]
	v_mov_b32_e32 v216, v212
	v_mov_b32_e32 v217, v213
	global_store_dwordx4 v[216:217], v[66:69], off
	global_store_dwordx4 v[216:217], v[70:73], off offset:64
	global_store_dwordx4 v[216:217], v[74:77], off offset:512
	global_store_dwordx4 v[216:217], v[78:81], off offset:576
	v_add_co_u32_e32 v216, vcc, 0x20000, v212
	s_nop 1
	v_addc_co_u32_e32 v217, vcc, 0, v213, vcc
	global_store_dwordx4 v[216:217], v[82:85], off
	global_store_dwordx4 v[216:217], v[110:113], off offset:64
	global_store_dwordx4 v[216:217], v[98:101], off offset:512
	global_store_dwordx4 v[216:217], v[86:89], off offset:576
	v_add_co_u32_e32 v216, vcc, 0x40000, v212
	s_nop 1
	v_addc_co_u32_e32 v217, vcc, 0, v213, vcc
	global_store_dwordx4 v[216:217], v[126:129], off
	global_store_dwordx4 v[216:217], v[118:121], off offset:64
	global_store_dwordx4 v[216:217], v[106:109], off offset:512
	global_store_dwordx4 v[216:217], v[94:97], off offset:576
	v_add_co_u32_e32 v216, vcc, 0x60000, v212
	s_nop 1
	v_addc_co_u32_e32 v217, vcc, 0, v213, vcc
	global_store_dwordx4 v[216:217], v[122:125], off
	global_store_dwordx4 v[216:217], v[114:117], off offset:64
	global_store_dwordx4 v[216:217], v[102:105], off offset:512
	global_store_dwordx4 v[216:217], v[90:93], off offset:576
	v_add_co_u32_e32 v216, vcc, 0x100000, v212
	s_nop 1
	v_addc_co_u32_e32 v217, vcc, 0, v213, vcc
	global_store_dwordx4 v[216:217], v[62:65], off
	global_store_dwordx4 v[216:217], v[58:61], off offset:64
	global_store_dwordx4 v[216:217], v[54:57], off offset:512
	global_store_dwordx4 v[216:217], v[50:53], off offset:576
	v_add_co_u32_e32 v216, vcc, 0x120000, v212
	s_nop 1
	v_addc_co_u32_e32 v217, vcc, 0, v213, vcc
	global_store_dwordx4 v[216:217], v[46:49], off
	global_store_dwordx4 v[216:217], v[42:45], off offset:64
	global_store_dwordx4 v[216:217], v[38:41], off offset:512
	global_store_dwordx4 v[216:217], v[34:37], off offset:576
	v_add_co_u32_e32 v216, vcc, 0x140000, v212
	s_nop 1
	v_addc_co_u32_e32 v217, vcc, 0, v213, vcc
	global_store_dwordx4 v[216:217], v[30:33], off
	global_store_dwordx4 v[216:217], v[26:29], off offset:64
	global_store_dwordx4 v[216:217], v[22:25], off offset:512
	global_store_dwordx4 v[216:217], v[18:21], off offset:576
	v_add_co_u32_e32 v216, vcc, 0x160000, v212
	s_nop 1
	v_addc_co_u32_e32 v217, vcc, 0, v213, vcc
	global_store_dwordx4 v[216:217], v[14:17], off
	global_store_dwordx4 v[216:217], v[10:13], off offset:64
	global_store_dwordx4 v[216:217], v[6:9], off offset:512
	global_store_dwordx4 v[216:217], v[2:5], off offset:576
	s_movk_i32 s17, 0x3f50
	s_mov_b32 s39, s18
	s_mov_b32 s40, s16
	s_mov_b64 s[26:27], s[22:23]
	s_mov_b64 s[24:25], s[20:21]
	s_and_b64 vcc, exec, s[14:15]
	s_cbranch_vccz .LBB0_359
	s_waitcnt vmcnt(0)
	s_cmpk_gt_u32 s4, 0xff
	s_cbranch_scc1 .LBB0_370
	s_barrier
